# every 32-MFMA block of the GEMM K-loops starts on a 64-byte instruction-cache line (s_nop padding in the load segment in front of it): a block spans exactly four lines
# baseline (speedup 1.0000x reference)
; #define PG8_STAGEA(bufoff, gbase, voff) PG8_STAGE_X(bufoff, gbase, voff, AUXA)
; #define PG8_STR(x) PG8_STR2(x)
;     ...
;         const bool has_next = S.next(ui + 1, nxt);
;         const char* nA = has_next ? (const char*)g.A + (size_t)nxt.pm * tstepA : cA; const char* nB = has_next ? (const char*)g.Bt + (size_t)nxt.pn * tstepB : cB;
;         int t0 = 0;
;         if constexpr (SP2 && GEMM_RELAX == 1) { if (ui > 0) {
;             const char* a1 = cA + kstepA; const char* a2 = cA + 2 * kstepA; const char* b2 = cB + 2 * kstepB; const char* a3 = a2 + kstepA; const char* b3 = b2 + kstepB;
;             PG8_LDB(B0, 0, 0); PG8_LDB(B1, 0, 1); PG8_SCHED; PG8_LDA(At, 0, 0); PG8_STAGEA(PG8_SA(1, 1), a1 + hstepA, voffA);
;             PG8_WAIT_V(24); PG8_WAIT_L(0); PG8_BAR; PG8_MMA(0, 0, At, B0); PG8_MMA(0, 1, At, B1); PG8_BAR; PG8_SCHED;
;             PG8_LDA(At, 0, 1); PG8_STAGEB(PG8_SB(0, 0), b2, voffB); PG8_STAGEB(PG8_SB(0, 1), b2 + hstepB, voffB); PG8_STAGEA(PG8_SA(0, 0), a2, voffA);
;             PG8_WAIT_V(24); PG8_WAIT_L(0); PG8_BAR; PG8_MMA(1, 0, At, B0); PG8_MMA(1, 1, At, B1); PG8_BAR; PG8_SCHED;
;             PG8_LDB(B0, 1, 0); PG8_LDB(B1, 1, 1); PG8_SCHED; PG8_LDA(At, 1, 0); PG8_STAGEA(PG8_SA(0, 1), a2 + hstepA, voffA);
;             PG8_WAIT_V(8); PG8_WAIT_L(0); PG8_BAR; PG8_MMA(0, 0, At, B0); PG8_MMA(0, 1, At, B1); PG8_BAR; PG8_SCHED;
;             PG8_LDA(At, 1, 1); PG8_STAGEB(PG8_SB(1, 0), b3, voffB); PG8_STAGEB(PG8_SB(1, 1), b3 + hstepB, voffB); PG8_STAGEA(PG8_SA(1, 0), a3, voffA);
;             PG8_WAIT_V(8); PG8_WAIT_L(0); PG8_BAR; PG8_MMA(1, 0, At, B0); PG8_MMA(1, 1, At, B1); PG8_BAR; PG8_SCHED;
;             t0 = 2; } }
;     ...
;         asm volatile(".p2align " PG8_STR(GEMM_LOOP_ALIGN) ::: "memory");
;     ...
;         for (int t = t0; t < nt; t += 2) {
;             const bool last = (t == nt - 2);
;             const char* a1 = cA + (size_t)(t + 1) * kstepA;
;             const char* a2 = last ? nA : cA + (size_t)(t + 2) * kstepA; const char* b2 = last ? nB : cB + (size_t)(t + 2) * kstepB;
;             const char* a3 = a2 + kstepA; const char* b3 = b2 + kstepB;
;             if (last && has_next) S.a_ready(nxt);
;             if constexpr (SP2) {
;             PG8_LDB(B0, 0, 0); PG8_LDB(B1, 0, 1); PG8_SCHED; PG8_LDA(At, 0, 0); PG8_STAGEA(PG8_SA(1, 1), a1 + hstepA, voffA);
;     ...
;             const int relax = __builtin_amdgcn_readfirstlane((t == 0 && ui > 0) ? 1 : 0);
.LBB0_128:
	s_ashr_i32 s37, s36, 31
	s_lshl_b64 s[4:5], s[36:37], 21
	s_add_u32 s38, s56, s4
	s_addc_u32 s39, s57, s5
	s_and_b64 s[4:5], s[6:7], exec
	s_cselect_b32 s4, s39, s1
	s_cselect_b32 s5, s38, s0
	s_ashr_i32 s27, s26, 31
	s_lshl_b64 s[8:9], s[26:27], 21
	s_add_u32 s40, s43, s8
	s_addc_u32 s41, s50, s9
	s_and_b64 s[8:9], s[6:7], exec
	s_cselect_b32 s16, s41, s11
	s_cselect_b32 s17, s40, s10
	s_add_u32 s8, s0, 0x100080
	s_addc_u32 s9, s1, 0
	s_add_u32 s0, s10, 0x100
	s_addc_u32 s1, s11, 0
	s_mov_b32 s27, -2
	s_add_u32 s10, s8, 0xfff00080
	s_addc_u32 s11, s9, -1
	s_add_i32 s18, 0, 0x10000
	s_cmp_eq_u32 s27, 60
	s_cselect_b32 s15, s4, s11
	s_cselect_b32 s14, s5, s10
	v_add_u32_e32 v16, s18, v167
	s_cselect_b32 s11, s16, s1
	s_cselect_b32 s10, s17, s0
	s_add_i32 s20, 0, 0x14000
	s_waitcnt lgkmcnt(0)
	ds_read_b128 v[130:133], v16
	ds_read_b128 v[134:137], v16 offset:1024
	ds_read_b128 v[152:155], v16 offset:2048
	ds_read_b128 v[156:159], v16 offset:3072
	v_add_u32_e32 v16, s20, v167
	ds_read_b128 v[160:163], v16
	ds_read_b128 v[174:177], v16 offset:1024
	ds_read_b128 v[178:181], v16 offset:2048
	ds_read_b128 v[182:185], v16 offset:3072
	v_lshl_add_u64 v[164:165], s[8:9], 0, v[148:149]
	s_add_i32 m0, s51, 0xc000
	ds_read_b128 v[186:189], v172
	ds_read_b128 v[190:193], v172 offset:1024
	ds_read_b128 v[194:197], v172 offset:2048
	ds_read_b128 v[198:201], v172 offset:3072
	ds_read_b128 v[202:205], v172 offset:4096
	ds_read_b128 v[206:209], v172 offset:5120
	ds_read_b128 v[210:213], v172 offset:6144
	ds_read_b128 v[214:217], v172 offset:7168
	global_load_lds_dwordx4 v[164:165], off
	v_lshl_add_u64 v[164:165], s[8:9], 0, v[150:151]
	s_add_i32 m0, s51, 0xe000
	s_nop 0
	global_load_lds_dwordx4 v[164:165], off
	s_waitcnt vmcnt(8)
	s_waitcnt lgkmcnt(0)
	s_nop 0
	s_nop 0
	s_nop 0
	s_nop 0
	s_nop 0
	s_nop 0
	s_nop 0
	s_nop 0
	s_nop 0
	s_nop 0
	s_nop 0
	s_nop 0
	s_nop 0
	s_nop 0
	s_setprio 1
	s_barrier
	v_mfma_f32_16x16x32_bf16 v[126:129], v[130:133], v[186:189], 0
	v_mfma_f32_16x16x32_bf16 v[122:125], v[152:155], v[186:189], 0
	v_mfma_f32_16x16x32_bf16 v[110:113], v[130:133], v[194:197], 0
	v_mfma_f32_16x16x32_bf16 v[106:109], v[152:155], v[194:197], 0
	v_mfma_f32_16x16x32_bf16 v[94:97], v[130:133], v[202:205], 0
	v_mfma_f32_16x16x32_bf16 v[90:93], v[152:155], v[202:205], 0
	v_mfma_f32_16x16x32_bf16 v[78:81], v[130:133], v[210:213], 0
	v_mfma_f32_16x16x32_bf16 v[74:77], v[152:155], v[210:213], 0
	v_mfma_f32_16x16x32_bf16 v[126:129], v[134:137], v[190:193], v[126:129]
	v_mfma_f32_16x16x32_bf16 v[122:125], v[156:159], v[190:193], v[122:125]
	v_mfma_f32_16x16x32_bf16 v[110:113], v[134:137], v[198:201], v[110:113]
	v_mfma_f32_16x16x32_bf16 v[106:109], v[156:159], v[198:201], v[106:109]
	v_mfma_f32_16x16x32_bf16 v[94:97], v[134:137], v[206:209], v[94:97]
	v_mfma_f32_16x16x32_bf16 v[90:93], v[156:159], v[206:209], v[90:93]
	v_mfma_f32_16x16x32_bf16 v[78:81], v[134:137], v[214:217], v[78:81]
	v_mfma_f32_16x16x32_bf16 v[74:77], v[156:159], v[214:217], v[74:77]
	v_mfma_f32_16x16x32_bf16 v[118:121], v[160:163], v[186:189], 0
	v_mfma_f32_16x16x32_bf16 v[114:117], v[178:181], v[186:189], 0
	v_mfma_f32_16x16x32_bf16 v[102:105], v[160:163], v[194:197], 0
	v_mfma_f32_16x16x32_bf16 v[98:101], v[178:181], v[194:197], 0
	v_mfma_f32_16x16x32_bf16 v[86:89], v[160:163], v[202:205], 0
	v_mfma_f32_16x16x32_bf16 v[82:85], v[178:181], v[202:205], 0
	v_mfma_f32_16x16x32_bf16 v[70:73], v[160:163], v[210:213], 0
	v_mfma_f32_16x16x32_bf16 v[66:69], v[178:181], v[210:213], 0
	v_mfma_f32_16x16x32_bf16 v[118:121], v[174:177], v[190:193], v[118:121]
	v_mfma_f32_16x16x32_bf16 v[114:117], v[182:185], v[190:193], v[114:117]
	v_mfma_f32_16x16x32_bf16 v[102:105], v[174:177], v[198:201], v[102:105]
	v_mfma_f32_16x16x32_bf16 v[98:101], v[182:185], v[198:201], v[98:101]
	v_mfma_f32_16x16x32_bf16 v[86:89], v[174:177], v[206:209], v[86:89]
	v_mfma_f32_16x16x32_bf16 v[82:85], v[182:185], v[206:209], v[82:85]
	v_mfma_f32_16x16x32_bf16 v[70:73], v[174:177], v[214:217], v[70:73]
	v_mfma_f32_16x16x32_bf16 v[66:69], v[182:185], v[214:217], v[66:69]
	s_barrier
	s_setprio 0
	s_add_i32 s18, s18, s42
	v_lshl_add_u64 v[164:165], s[10:11], 0, v[142:143]
	s_mov_b32 m0, s18
	ds_read_b128 v[186:189], v172 offset:16384
	ds_read_b128 v[190:193], v172 offset:17408
	ds_read_b128 v[194:197], v172 offset:18432
	ds_read_b128 v[198:201], v172 offset:19456
	ds_read_b128 v[202:205], v172 offset:20480
	ds_read_b128 v[206:209], v172 offset:21504
	ds_read_b128 v[210:213], v172 offset:22528
	ds_read_b128 v[214:217], v172 offset:23552
	global_load_lds_dwordx4 v[164:165], off
	s_add_i32 m0, s18, 0x2000
	s_add_u32 s18, s10, 0x100000
	v_lshl_add_u64 v[218:219], s[10:11], 0, v[138:139]
	s_addc_u32 s19, s11, 0
	s_add_i32 s20, s20, s42
	global_load_lds_dwordx4 v[218:219], off
	v_lshl_add_u64 v[220:221], s[18:19], 0, v[142:143]
	s_mov_b32 m0, s20
	v_lshl_add_u64 v[222:223], s[14:15], 0, v[140:141]
	global_load_lds_dwordx4 v[220:221], off
	v_lshl_add_u64 v[220:221], s[18:19], 0, v[138:139]
	s_add_i32 m0, s20, 0x2000
	s_nop 0
	global_load_lds_dwordx4 v[220:221], off
	v_lshl_add_u64 v[220:221], s[14:15], 0, v[144:145]
	s_mov_b32 m0, s51
	s_nop 0
	global_load_lds_dwordx4 v[220:221], off
	s_mov_b32 m0, s68
	s_nop 0
	global_load_lds_dwordx4 v[222:223], off
	s_waitcnt vmcnt(8)
	s_waitcnt lgkmcnt(0)
	s_nop 0
	s_nop 0
	s_setprio 1
	s_barrier
; #define PG8_STAGEA(bufoff, gbase, voff) PG8_STAGE_X(bufoff, gbase, voff, AUXA)
; #define PG8_STAGEB(bufoff, gbase, voff) PG8_STAGE_X(bufoff, gbase, voff, AUXB)
; #define PG8_LDA(dst, b, h) do { _Pragma("unroll") for (int m = 0; m < 4; ++m) _Pragma("unroll") for (int k = 0; k < 2; ++k) dst[m][k] = *(const PG8_LAS bf16x8*)(lds + PG8_SA(b, h) + aoff + m * 2048 + k * 1024); } while (0)
; #define PG8_LDB(dst, b, h) do { _Pragma("unroll") for (int n = 0; n < 2; ++n) _Pragma("unroll") for (int k = 0; k < 2; ++k) dst[n][k] = *(const PG8_LAS bf16x8*)(lds + PG8_SB(b, h) + boff + n * 2048 + k * 1024); } while (0)
; #define PG8_MMA(ai, bj, At, Bt) do { if (GEMM_PRIO_MODE == 0) __builtin_amdgcn_s_setprio(1); PG8_MMA_LOOPS \
;         acc[ai][bj][m][n] = __builtin_amdgcn_mfma_f32_16x16x32_bf16(Bt[n][k], At[m][k], acc[ai][bj][m][n], 0, 0, 0); if (GEMM_PRIO_MODE == 0) __builtin_amdgcn_s_setprio(0); } while (0)
; #define PG8_WAIT_V(n) asm volatile("s_waitcnt vmcnt(" #n ")" ::: "memory")
; #define PG8_WAIT_VR(n, nr, flag) asm volatile("s_cmp_eq_u32 %0, 0\n\ts_cbranch_scc1 .Lpg8s%=\n\ts_waitcnt vmcnt(" #nr ")\n\ts_branch .Lpg8d%=\n.Lpg8s%=:\n\ts_waitcnt vmcnt(" #n ")\n.Lpg8d%=:" :: "s"(flag) : "memory", "scc")
; #define PG8_WAIT_L(n) asm volatile("s_waitcnt lgkmcnt(" #n ")" ::: "memory")
; #define PG8_BAR __builtin_amdgcn_s_barrier()
; #define PG8_SCHED __builtin_amdgcn_sched_barrier(0)
;     ...
;             PG8_LDA(At, 0, 1); PG8_STAGEB(PG8_SB(0, 0), b2, voffB); PG8_STAGEB(PG8_SB(0, 1), b2 + hstepB, voffB); PG8_STAGEA(PG8_SA(0, 0), a2, voffA);
;     ...
;             PG8_WAIT_VR(8, 24, relax); PG8_WAIT_L(0); PG8_BAR; PG8_MMA(1, 0, At, B0); PG8_MMA(1, 1, At, B1); PG8_BAR; PG8_SCHED;
;     ...
;             PG8_WAIT_V(8); PG8_WAIT_L(0); PG8_BAR; PG8_MMA(1, 0, At, B0); PG8_MMA(1, 1, At, B1); PG8_BAR; PG8_SCHED;
;     ...
;             PG8_LDB(B0, 1, 0); PG8_LDB(B1, 1, 1); PG8_SCHED; PG8_LDA(At, 1, 0); PG8_STAGEA(PG8_SA(0, 1), a2 + hstepA, voffA);
;             PG8_WAIT_V(8); PG8_WAIT_L(0); PG8_BAR; PG8_MMA(0, 0, At, B0); PG8_MMA(0, 1, At, B1); PG8_BAR; PG8_SCHED;
	v_mfma_f32_16x16x32_bf16 v[62:65], v[130:133], v[186:189], 0
	v_mfma_f32_16x16x32_bf16 v[58:61], v[152:155], v[186:189], 0
	v_mfma_f32_16x16x32_bf16 v[46:49], v[130:133], v[194:197], 0
	v_mfma_f32_16x16x32_bf16 v[42:45], v[152:155], v[194:197], 0
	v_mfma_f32_16x16x32_bf16 v[30:33], v[130:133], v[202:205], 0
	v_mfma_f32_16x16x32_bf16 v[26:29], v[152:155], v[202:205], 0
	v_mfma_f32_16x16x32_bf16 v[12:15], v[130:133], v[210:213], 0
	v_mfma_f32_16x16x32_bf16 v[8:11], v[152:155], v[210:213], 0
	v_mfma_f32_16x16x32_bf16 v[62:65], v[134:137], v[190:193], v[62:65]
	v_mfma_f32_16x16x32_bf16 v[58:61], v[156:159], v[190:193], v[58:61]
	v_mfma_f32_16x16x32_bf16 v[46:49], v[134:137], v[198:201], v[46:49]
	v_mfma_f32_16x16x32_bf16 v[42:45], v[156:159], v[198:201], v[42:45]
	v_mfma_f32_16x16x32_bf16 v[30:33], v[134:137], v[206:209], v[30:33]
	v_mfma_f32_16x16x32_bf16 v[26:29], v[156:159], v[206:209], v[26:29]
	v_mfma_f32_16x16x32_bf16 v[12:15], v[134:137], v[214:217], v[12:15]
	v_mfma_f32_16x16x32_bf16 v[8:11], v[156:159], v[214:217], v[8:11]
	v_mfma_f32_16x16x32_bf16 v[54:57], v[160:163], v[186:189], 0
	v_mfma_f32_16x16x32_bf16 v[50:53], v[178:181], v[186:189], 0
	v_mfma_f32_16x16x32_bf16 v[38:41], v[160:163], v[194:197], 0
	v_mfma_f32_16x16x32_bf16 v[34:37], v[178:181], v[194:197], 0
	v_mfma_f32_16x16x32_bf16 v[22:25], v[160:163], v[202:205], 0
	v_mfma_f32_16x16x32_bf16 v[18:21], v[178:181], v[202:205], 0
	v_mfma_f32_16x16x32_bf16 v[4:7], v[160:163], v[210:213], 0
	v_mfma_f32_16x16x32_bf16 v[0:3], v[178:181], v[210:213], 0
	v_mfma_f32_16x16x32_bf16 v[54:57], v[174:177], v[190:193], v[54:57]
	v_mfma_f32_16x16x32_bf16 v[50:53], v[182:185], v[190:193], v[50:53]
	v_mfma_f32_16x16x32_bf16 v[38:41], v[174:177], v[198:201], v[38:41]
	v_mfma_f32_16x16x32_bf16 v[34:37], v[182:185], v[198:201], v[34:37]
	v_mfma_f32_16x16x32_bf16 v[22:25], v[174:177], v[206:209], v[22:25]
	v_mfma_f32_16x16x32_bf16 v[18:21], v[182:185], v[206:209], v[18:21]
	v_mfma_f32_16x16x32_bf16 v[4:7], v[174:177], v[214:217], v[4:7]
	v_mfma_f32_16x16x32_bf16 v[0:3], v[182:185], v[214:217], v[0:3]
	s_barrier
	s_setprio 0
	s_add_i32 s18, 0, 0x18000
	v_add_u32_e32 v16, s18, v167
	s_add_i32 s19, 0, 0x1c000
	ds_read_b128 v[130:133], v16
	ds_read_b128 v[134:137], v16 offset:1024
	ds_read_b128 v[152:155], v16 offset:2048
	ds_read_b128 v[156:159], v16 offset:3072
	v_add_u32_e32 v16, s19, v167
	ds_read_b128 v[160:163], v16
	ds_read_b128 v[174:177], v16 offset:1024
	ds_read_b128 v[178:181], v16 offset:2048
	ds_read_b128 v[182:185], v16 offset:3072
	s_add_u32 s14, s14, 0x100000
	s_addc_u32 s15, s15, 0
	s_mov_b32 m0, s69
	v_lshl_add_u64 v[224:225], s[14:15], 0, v[144:145]
	ds_read_b128 v[186:189], v172 offset:32768
	ds_read_b128 v[190:193], v172 offset:33792
	ds_read_b128 v[194:197], v172 offset:34816
	ds_read_b128 v[198:201], v172 offset:35840
	ds_read_b128 v[202:205], v172 offset:36864
	ds_read_b128 v[206:209], v172 offset:37888
	ds_read_b128 v[210:213], v172 offset:38912
	ds_read_b128 v[214:217], v172 offset:39936
	global_load_lds_dwordx4 v[224:225], off
	v_lshl_add_u64 v[224:225], s[14:15], 0, v[140:141]
	s_mov_b32 m0, s72
	s_nop 0
	global_load_lds_dwordx4 v[224:225], off
	s_waitcnt vmcnt(8)
	s_waitcnt lgkmcnt(0)
	s_nop 0
	s_nop 0
	s_nop 0
	s_nop 0
	s_nop 0
	s_nop 0
	s_setprio 1
	s_barrier
	v_mfma_f32_16x16x32_bf16 v[126:129], v[130:133], v[186:189], v[126:129]
	v_mfma_f32_16x16x32_bf16 v[122:125], v[152:155], v[186:189], v[122:125]
	v_mfma_f32_16x16x32_bf16 v[110:113], v[130:133], v[194:197], v[110:113]
	v_mfma_f32_16x16x32_bf16 v[106:109], v[152:155], v[194:197], v[106:109]
	v_mfma_f32_16x16x32_bf16 v[94:97], v[130:133], v[202:205], v[94:97]
	v_mfma_f32_16x16x32_bf16 v[90:93], v[152:155], v[202:205], v[90:93]
	v_mfma_f32_16x16x32_bf16 v[78:81], v[130:133], v[210:213], v[78:81]
	v_mfma_f32_16x16x32_bf16 v[74:77], v[152:155], v[210:213], v[74:77]
	v_mfma_f32_16x16x32_bf16 v[126:129], v[134:137], v[190:193], v[126:129]
	v_mfma_f32_16x16x32_bf16 v[122:125], v[156:159], v[190:193], v[122:125]
	v_mfma_f32_16x16x32_bf16 v[110:113], v[134:137], v[198:201], v[110:113]
	v_mfma_f32_16x16x32_bf16 v[106:109], v[156:159], v[198:201], v[106:109]
	v_mfma_f32_16x16x32_bf16 v[94:97], v[134:137], v[206:209], v[94:97]
	v_mfma_f32_16x16x32_bf16 v[90:93], v[156:159], v[206:209], v[90:93]
	v_mfma_f32_16x16x32_bf16 v[78:81], v[134:137], v[214:217], v[78:81]
	v_mfma_f32_16x16x32_bf16 v[74:77], v[156:159], v[214:217], v[74:77]
	v_mfma_f32_16x16x32_bf16 v[118:121], v[160:163], v[186:189], v[118:121]
	v_mfma_f32_16x16x32_bf16 v[114:117], v[178:181], v[186:189], v[114:117]
	v_mfma_f32_16x16x32_bf16 v[102:105], v[160:163], v[194:197], v[102:105]
	v_mfma_f32_16x16x32_bf16 v[98:101], v[178:181], v[194:197], v[98:101]
	v_mfma_f32_16x16x32_bf16 v[86:89], v[160:163], v[202:205], v[86:89]
	v_mfma_f32_16x16x32_bf16 v[82:85], v[178:181], v[202:205], v[82:85]
	v_mfma_f32_16x16x32_bf16 v[70:73], v[160:163], v[210:213], v[70:73]
	v_mfma_f32_16x16x32_bf16 v[66:69], v[178:181], v[210:213], v[66:69]
	v_mfma_f32_16x16x32_bf16 v[118:121], v[174:177], v[190:193], v[118:121]
	v_mfma_f32_16x16x32_bf16 v[114:117], v[182:185], v[190:193], v[114:117]
	v_mfma_f32_16x16x32_bf16 v[102:105], v[174:177], v[198:201], v[102:105]
	v_mfma_f32_16x16x32_bf16 v[98:101], v[182:185], v[198:201], v[98:101]
	v_mfma_f32_16x16x32_bf16 v[86:89], v[174:177], v[206:209], v[86:89]
	v_mfma_f32_16x16x32_bf16 v[82:85], v[182:185], v[206:209], v[82:85]
	v_mfma_f32_16x16x32_bf16 v[70:73], v[174:177], v[214:217], v[70:73]
	v_mfma_f32_16x16x32_bf16 v[66:69], v[182:185], v[214:217], v[66:69]
	s_barrier
; #define PG8_STAGEA(bufoff, gbase, voff) PG8_STAGE_X(bufoff, gbase, voff, AUXA)
; #define PG8_STAGEB(bufoff, gbase, voff) PG8_STAGE_X(bufoff, gbase, voff, AUXB)
; #define PG8_LDA(dst, b, h) do { _Pragma("unroll") for (int m = 0; m < 4; ++m) _Pragma("unroll") for (int k = 0; k < 2; ++k) dst[m][k] = *(const PG8_LAS bf16x8*)(lds + PG8_SA(b, h) + aoff + m * 2048 + k * 1024); } while (0)
; #define PG8_WAIT_V(n) asm volatile("s_waitcnt vmcnt(" #n ")" ::: "memory")
; #define PG8_WAIT_L(n) asm volatile("s_waitcnt lgkmcnt(" #n ")" ::: "memory")
;     ...
;         for (int t = t0; t < nt; t += 2) {
;             const bool last = (t == nt - 2);
;             const char* a1 = cA + (size_t)(t + 1) * kstepA;
;             const char* a2 = last ? nA : cA + (size_t)(t + 2) * kstepA; const char* b2 = last ? nB : cB + (size_t)(t + 2) * kstepB;
;             const char* a3 = a2 + kstepA; const char* b3 = b2 + kstepB;
;             if (last && has_next) S.a_ready(nxt);
;             if constexpr (SP2) {
;             PG8_LDB(B0, 0, 0); PG8_LDB(B1, 0, 1); PG8_SCHED; PG8_LDA(At, 0, 0); PG8_STAGEA(PG8_SA(1, 1), a1 + hstepA, voffA);
;     ...
;             const int relax = __builtin_amdgcn_readfirstlane((t == 0 && ui > 0) ? 1 : 0);
;             PG8_WAIT_VR(8, 24, relax); PG8_WAIT_L(0); PG8_BAR; PG8_MMA(0, 0, At, B0); PG8_MMA(0, 1, At, B1); PG8_BAR; PG8_SCHED;
;     ...
;             PG8_WAIT_V(8); PG8_WAIT_L(0); PG8_BAR; PG8_MMA(0, 0, At, B0); PG8_MMA(0, 1, At, B1); PG8_BAR; PG8_SCHED;
;     ...
;             PG8_LDA(At, 0, 1); PG8_STAGEB(PG8_SB(0, 0), b2, voffB); PG8_STAGEB(PG8_SB(0, 1), b2 + hstepB, voffB); PG8_STAGEA(PG8_SA(0, 0), a2, voffA);
;     ...
;             PG8_WAIT_VR(8, 24, relax); PG8_WAIT_L(0); PG8_BAR; PG8_MMA(1, 0, At, B0); PG8_MMA(1, 1, At, B1); PG8_BAR; PG8_SCHED;
;     ...
;             PG8_WAIT_V(8); PG8_WAIT_L(0); PG8_BAR; PG8_MMA(1, 0, At, B0); PG8_MMA(1, 1, At, B1); PG8_BAR; PG8_SCHED;
;     ...
;             PG8_LDB(B0, 1, 0); PG8_LDB(B1, 1, 1); PG8_SCHED; PG8_LDA(At, 1, 0); PG8_STAGEA(PG8_SA(0, 1), a2 + hstepA, voffA);
;             PG8_WAIT_V(8); PG8_WAIT_L(0); PG8_BAR; PG8_MMA(0, 0, At, B0); PG8_MMA(0, 1, At, B1); PG8_BAR; PG8_SCHED;
;             PG8_LDA(At, 1, 1); PG8_STAGEB(PG8_SB(1, 0), b3, voffB); PG8_STAGEB(PG8_SB(1, 1), b3 + hstepB, voffB); PG8_STAGEA(PG8_SA(1, 0), a3, voffA);
;             PG8_WAIT_V(8); PG8_WAIT_L(0); PG8_BAR; PG8_MMA(1, 0, At, B0); PG8_MMA(1, 1, At, B1); PG8_BAR; PG8_SCHED;
	s_setprio 0
	s_add_i32 s14, s18, s42
	v_lshl_add_u64 v[164:165], v[164:165], 0, s[86:87]
	s_mov_b32 m0, s14
	ds_read_b128 v[186:189], v172 offset:49152
	ds_read_b128 v[190:193], v172 offset:50176
	ds_read_b128 v[194:197], v172 offset:51200
	ds_read_b128 v[198:201], v172 offset:52224
	ds_read_b128 v[202:205], v172 offset:53248
	ds_read_b128 v[206:209], v172 offset:54272
	ds_read_b128 v[210:213], v172 offset:55296
	ds_read_b128 v[214:217], v172 offset:56320
	global_load_lds_dwordx4 v[164:165], off
	s_add_i32 m0, s14, 0x2000
	s_add_u32 s10, s10, 0x100080
	v_lshl_add_u64 v[164:165], v[218:219], 0, s[86:87]
	s_addc_u32 s11, s11, 0
	s_add_i32 s14, s19, s42
	global_load_lds_dwordx4 v[164:165], off
	v_lshl_add_u64 v[164:165], s[10:11], 0, v[142:143]
	s_mov_b32 m0, s14
	s_nop 0
	global_load_lds_dwordx4 v[164:165], off
	v_lshl_add_u64 v[164:165], s[10:11], 0, v[138:139]
	s_add_i32 m0, s14, 0x2000
	s_nop 0
	global_load_lds_dwordx4 v[164:165], off
	v_lshl_add_u64 v[164:165], v[220:221], 0, s[86:87]
	s_mov_b32 m0, s73
	s_nop 0
	global_load_lds_dwordx4 v[164:165], off
	v_lshl_add_u64 v[164:165], v[222:223], 0, s[86:87]
	s_mov_b32 m0, s82
	s_nop 0
	global_load_lds_dwordx4 v[164:165], off
	s_waitcnt vmcnt(8)
	s_waitcnt lgkmcnt(0)
	s_nop 0
	s_setprio 1
	s_barrier
	v_mfma_f32_16x16x32_bf16 v[62:65], v[130:133], v[186:189], v[62:65]
	v_mfma_f32_16x16x32_bf16 v[58:61], v[152:155], v[186:189], v[58:61]
	v_mfma_f32_16x16x32_bf16 v[46:49], v[130:133], v[194:197], v[46:49]
	v_mfma_f32_16x16x32_bf16 v[42:45], v[152:155], v[194:197], v[42:45]
	v_mfma_f32_16x16x32_bf16 v[30:33], v[130:133], v[202:205], v[30:33]
	v_mfma_f32_16x16x32_bf16 v[26:29], v[152:155], v[202:205], v[26:29]
	v_mfma_f32_16x16x32_bf16 v[12:15], v[130:133], v[210:213], v[12:15]
	v_mfma_f32_16x16x32_bf16 v[8:11], v[152:155], v[210:213], v[8:11]
	v_mfma_f32_16x16x32_bf16 v[62:65], v[134:137], v[190:193], v[62:65]
	v_mfma_f32_16x16x32_bf16 v[58:61], v[156:159], v[190:193], v[58:61]
	v_mfma_f32_16x16x32_bf16 v[46:49], v[134:137], v[198:201], v[46:49]
	v_mfma_f32_16x16x32_bf16 v[42:45], v[156:159], v[198:201], v[42:45]
	v_mfma_f32_16x16x32_bf16 v[30:33], v[134:137], v[206:209], v[30:33]
	v_mfma_f32_16x16x32_bf16 v[26:29], v[156:159], v[206:209], v[26:29]
	v_mfma_f32_16x16x32_bf16 v[12:15], v[134:137], v[214:217], v[12:15]
	v_mfma_f32_16x16x32_bf16 v[8:11], v[156:159], v[214:217], v[8:11]
	v_mfma_f32_16x16x32_bf16 v[54:57], v[160:163], v[186:189], v[54:57]
	v_mfma_f32_16x16x32_bf16 v[50:53], v[178:181], v[186:189], v[50:53]
	v_mfma_f32_16x16x32_bf16 v[38:41], v[160:163], v[194:197], v[38:41]
	v_mfma_f32_16x16x32_bf16 v[34:37], v[178:181], v[194:197], v[34:37]
	v_mfma_f32_16x16x32_bf16 v[22:25], v[160:163], v[202:205], v[22:25]
	v_mfma_f32_16x16x32_bf16 v[18:21], v[178:181], v[202:205], v[18:21]
	v_mfma_f32_16x16x32_bf16 v[4:7], v[160:163], v[210:213], v[4:7]
	v_mfma_f32_16x16x32_bf16 v[0:3], v[178:181], v[210:213], v[0:3]
	v_mfma_f32_16x16x32_bf16 v[54:57], v[174:177], v[190:193], v[54:57]
	v_mfma_f32_16x16x32_bf16 v[50:53], v[182:185], v[190:193], v[50:53]
	v_mfma_f32_16x16x32_bf16 v[38:41], v[174:177], v[198:201], v[38:41]
	v_mfma_f32_16x16x32_bf16 v[34:37], v[182:185], v[198:201], v[34:37]
	v_mfma_f32_16x16x32_bf16 v[22:25], v[174:177], v[206:209], v[22:25]
	v_mfma_f32_16x16x32_bf16 v[18:21], v[182:185], v[206:209], v[18:21]
	v_mfma_f32_16x16x32_bf16 v[4:7], v[174:177], v[214:217], v[4:7]
	v_mfma_f32_16x16x32_bf16 v[0:3], v[182:185], v[214:217], v[0:3]
	s_barrier
	s_setprio 0
	s_add_i32 s27, s27, 2
	s_add_u32 s8, s8, 0x100
	s_addc_u32 s9, s9, 0
	s_add_u32 s0, s0, 0x100
	s_addc_u32 s1, s1, 0
.LBB0_129:
	s_add_u32 s10, s8, 0xfff00080
	s_addc_u32 s11, s9, -1
	s_add_i32 s18, 0, 0x10000
	s_cmp_eq_u32 s27, 60
	s_cselect_b32 s15, s4, s11
	s_cselect_b32 s14, s5, s10
	v_add_u32_e32 v16, s18, v167
	s_cselect_b32 s11, s16, s1
	s_cselect_b32 s10, s17, s0
	s_add_i32 s20, 0, 0x14000
	s_waitcnt lgkmcnt(0)
	ds_read_b128 v[130:133], v16
	ds_read_b128 v[134:137], v16 offset:1024
	ds_read_b128 v[152:155], v16 offset:2048
	ds_read_b128 v[156:159], v16 offset:3072
	v_add_u32_e32 v16, s20, v167
	ds_read_b128 v[160:163], v16
	ds_read_b128 v[174:177], v16 offset:1024
	ds_read_b128 v[178:181], v16 offset:2048
	ds_read_b128 v[182:185], v16 offset:3072
	v_lshl_add_u64 v[164:165], s[8:9], 0, v[148:149]
	s_add_i32 m0, s51, 0xc000
	ds_read_b128 v[186:189], v172
	ds_read_b128 v[190:193], v172 offset:1024
	ds_read_b128 v[194:197], v172 offset:2048
	ds_read_b128 v[198:201], v172 offset:3072
	ds_read_b128 v[202:205], v172 offset:4096
	ds_read_b128 v[206:209], v172 offset:5120
	ds_read_b128 v[210:213], v172 offset:6144
	ds_read_b128 v[214:217], v172 offset:7168
	global_load_lds_dwordx4 v[164:165], off
	v_lshl_add_u64 v[164:165], s[8:9], 0, v[150:151]
	s_add_i32 m0, s51, 0xe000
	s_nop 0
	global_load_lds_dwordx4 v[164:165], off
	s_waitcnt vmcnt(8)
	s_waitcnt lgkmcnt(0)
	s_nop 0
	s_nop 0
	s_nop 0
	s_nop 0
	s_nop 0
	s_nop 0
	s_nop 0
	s_setprio 1
	s_barrier
; #define PG8_STAGEA(bufoff, gbase, voff) PG8_STAGE_X(bufoff, gbase, voff, AUXA)
; #define PG8_STAGEB(bufoff, gbase, voff) PG8_STAGE_X(bufoff, gbase, voff, AUXB)
; #define PG8_LDA(dst, b, h) do { _Pragma("unroll") for (int m = 0; m < 4; ++m) _Pragma("unroll") for (int k = 0; k < 2; ++k) dst[m][k] = *(const PG8_LAS bf16x8*)(lds + PG8_SA(b, h) + aoff + m * 2048 + k * 1024); } while (0)
; #define PG8_LDB(dst, b, h) do { _Pragma("unroll") for (int n = 0; n < 2; ++n) _Pragma("unroll") for (int k = 0; k < 2; ++k) dst[n][k] = *(const PG8_LAS bf16x8*)(lds + PG8_SB(b, h) + boff + n * 2048 + k * 1024); } while (0)
; #define PG8_MMA(ai, bj, At, Bt) do { if (GEMM_PRIO_MODE == 0) __builtin_amdgcn_s_setprio(1); PG8_MMA_LOOPS \
;         acc[ai][bj][m][n] = __builtin_amdgcn_mfma_f32_16x16x32_bf16(Bt[n][k], At[m][k], acc[ai][bj][m][n], 0, 0, 0); if (GEMM_PRIO_MODE == 0) __builtin_amdgcn_s_setprio(0); } while (0)
; #define PG8_WAIT_V(n) asm volatile("s_waitcnt vmcnt(" #n ")" ::: "memory")
; #define PG8_WAIT_VR(n, nr, flag) asm volatile("s_cmp_eq_u32 %0, 0\n\ts_cbranch_scc1 .Lpg8s%=\n\ts_waitcnt vmcnt(" #nr ")\n\ts_branch .Lpg8d%=\n.Lpg8s%=:\n\ts_waitcnt vmcnt(" #n ")\n.Lpg8d%=:" :: "s"(flag) : "memory", "scc")
; #define PG8_WAIT_L(n) asm volatile("s_waitcnt lgkmcnt(" #n ")" ::: "memory")
; #define PG8_BAR __builtin_amdgcn_s_barrier()
; #define PG8_SCHED __builtin_amdgcn_sched_barrier(0)
;     ...
;             PG8_LDB(B0, 0, 0); PG8_LDB(B1, 0, 1); PG8_SCHED; PG8_LDA(At, 0, 0); PG8_STAGEA(PG8_SA(1, 1), a1 + hstepA, voffA);
;     ...
;             const int relax = __builtin_amdgcn_readfirstlane((t == 0 && ui > 0) ? 1 : 0);
;             PG8_WAIT_VR(8, 24, relax); PG8_WAIT_L(0); PG8_BAR; PG8_MMA(0, 0, At, B0); PG8_MMA(0, 1, At, B1); PG8_BAR; PG8_SCHED;
;     ...
;             PG8_WAIT_V(8); PG8_WAIT_L(0); PG8_BAR; PG8_MMA(0, 0, At, B0); PG8_MMA(0, 1, At, B1); PG8_BAR; PG8_SCHED;
;     ...
;             PG8_LDA(At, 0, 1); PG8_STAGEB(PG8_SB(0, 0), b2, voffB); PG8_STAGEB(PG8_SB(0, 1), b2 + hstepB, voffB); PG8_STAGEA(PG8_SA(0, 0), a2, voffA);
;     ...
;             PG8_WAIT_VR(8, 24, relax); PG8_WAIT_L(0); PG8_BAR; PG8_MMA(1, 0, At, B0); PG8_MMA(1, 1, At, B1); PG8_BAR; PG8_SCHED;
;     ...
;             PG8_WAIT_V(8); PG8_WAIT_L(0); PG8_BAR; PG8_MMA(1, 0, At, B0); PG8_MMA(1, 1, At, B1); PG8_BAR; PG8_SCHED;
	v_mfma_f32_16x16x32_bf16 v[126:129], v[130:133], v[186:189], v[126:129]
	v_mfma_f32_16x16x32_bf16 v[122:125], v[152:155], v[186:189], v[122:125]
	v_mfma_f32_16x16x32_bf16 v[110:113], v[130:133], v[194:197], v[110:113]
	v_mfma_f32_16x16x32_bf16 v[106:109], v[152:155], v[194:197], v[106:109]
	v_mfma_f32_16x16x32_bf16 v[94:97], v[130:133], v[202:205], v[94:97]
	v_mfma_f32_16x16x32_bf16 v[90:93], v[152:155], v[202:205], v[90:93]
	v_mfma_f32_16x16x32_bf16 v[78:81], v[130:133], v[210:213], v[78:81]
	v_mfma_f32_16x16x32_bf16 v[74:77], v[152:155], v[210:213], v[74:77]
	v_mfma_f32_16x16x32_bf16 v[126:129], v[134:137], v[190:193], v[126:129]
	v_mfma_f32_16x16x32_bf16 v[122:125], v[156:159], v[190:193], v[122:125]
	v_mfma_f32_16x16x32_bf16 v[110:113], v[134:137], v[198:201], v[110:113]
	v_mfma_f32_16x16x32_bf16 v[106:109], v[156:159], v[198:201], v[106:109]
	v_mfma_f32_16x16x32_bf16 v[94:97], v[134:137], v[206:209], v[94:97]
	v_mfma_f32_16x16x32_bf16 v[90:93], v[156:159], v[206:209], v[90:93]
	v_mfma_f32_16x16x32_bf16 v[78:81], v[134:137], v[214:217], v[78:81]
	v_mfma_f32_16x16x32_bf16 v[74:77], v[156:159], v[214:217], v[74:77]
	v_mfma_f32_16x16x32_bf16 v[118:121], v[160:163], v[186:189], v[118:121]
	v_mfma_f32_16x16x32_bf16 v[114:117], v[178:181], v[186:189], v[114:117]
	v_mfma_f32_16x16x32_bf16 v[102:105], v[160:163], v[194:197], v[102:105]
	v_mfma_f32_16x16x32_bf16 v[98:101], v[178:181], v[194:197], v[98:101]
	v_mfma_f32_16x16x32_bf16 v[86:89], v[160:163], v[202:205], v[86:89]
	v_mfma_f32_16x16x32_bf16 v[82:85], v[178:181], v[202:205], v[82:85]
	v_mfma_f32_16x16x32_bf16 v[70:73], v[160:163], v[210:213], v[70:73]
	v_mfma_f32_16x16x32_bf16 v[66:69], v[178:181], v[210:213], v[66:69]
	v_mfma_f32_16x16x32_bf16 v[118:121], v[174:177], v[190:193], v[118:121]
	v_mfma_f32_16x16x32_bf16 v[114:117], v[182:185], v[190:193], v[114:117]
	v_mfma_f32_16x16x32_bf16 v[102:105], v[174:177], v[198:201], v[102:105]
	v_mfma_f32_16x16x32_bf16 v[98:101], v[182:185], v[198:201], v[98:101]
	v_mfma_f32_16x16x32_bf16 v[86:89], v[174:177], v[206:209], v[86:89]
	v_mfma_f32_16x16x32_bf16 v[82:85], v[182:185], v[206:209], v[82:85]
	v_mfma_f32_16x16x32_bf16 v[70:73], v[174:177], v[214:217], v[70:73]
	v_mfma_f32_16x16x32_bf16 v[66:69], v[182:185], v[214:217], v[66:69]
	s_barrier
	s_setprio 0
	s_add_i32 s18, s18, s42
	v_lshl_add_u64 v[164:165], s[10:11], 0, v[142:143]
	s_mov_b32 m0, s18
	ds_read_b128 v[186:189], v172 offset:16384
	ds_read_b128 v[190:193], v172 offset:17408
	ds_read_b128 v[194:197], v172 offset:18432
	ds_read_b128 v[198:201], v172 offset:19456
	ds_read_b128 v[202:205], v172 offset:20480
	ds_read_b128 v[206:209], v172 offset:21504
	ds_read_b128 v[210:213], v172 offset:22528
	ds_read_b128 v[214:217], v172 offset:23552
	global_load_lds_dwordx4 v[164:165], off
	s_add_i32 m0, s18, 0x2000
	s_add_u32 s18, s10, 0x100000
	v_lshl_add_u64 v[218:219], s[10:11], 0, v[138:139]
	s_addc_u32 s19, s11, 0
	s_add_i32 s20, s20, s42
	global_load_lds_dwordx4 v[218:219], off
	v_lshl_add_u64 v[220:221], s[18:19], 0, v[142:143]
	s_mov_b32 m0, s20
	v_lshl_add_u64 v[222:223], s[14:15], 0, v[140:141]
	global_load_lds_dwordx4 v[220:221], off
	v_lshl_add_u64 v[220:221], s[18:19], 0, v[138:139]
	s_add_i32 m0, s20, 0x2000
	s_nop 0
	global_load_lds_dwordx4 v[220:221], off
	v_lshl_add_u64 v[220:221], s[14:15], 0, v[144:145]
	s_mov_b32 m0, s51
	s_nop 0
	global_load_lds_dwordx4 v[220:221], off
	s_mov_b32 m0, s68
	s_nop 0
	global_load_lds_dwordx4 v[222:223], off
	s_waitcnt vmcnt(8)
	s_waitcnt lgkmcnt(0)
	s_nop 0
	s_nop 0
	s_setprio 1
	s_barrier
	v_mfma_f32_16x16x32_bf16 v[62:65], v[130:133], v[186:189], v[62:65]
	v_mfma_f32_16x16x32_bf16 v[58:61], v[152:155], v[186:189], v[58:61]
	v_mfma_f32_16x16x32_bf16 v[46:49], v[130:133], v[194:197], v[46:49]
	v_mfma_f32_16x16x32_bf16 v[42:45], v[152:155], v[194:197], v[42:45]
	v_mfma_f32_16x16x32_bf16 v[30:33], v[130:133], v[202:205], v[30:33]
	v_mfma_f32_16x16x32_bf16 v[26:29], v[152:155], v[202:205], v[26:29]
	v_mfma_f32_16x16x32_bf16 v[12:15], v[130:133], v[210:213], v[12:15]
	v_mfma_f32_16x16x32_bf16 v[8:11], v[152:155], v[210:213], v[8:11]
	v_mfma_f32_16x16x32_bf16 v[62:65], v[134:137], v[190:193], v[62:65]
	v_mfma_f32_16x16x32_bf16 v[58:61], v[156:159], v[190:193], v[58:61]
	v_mfma_f32_16x16x32_bf16 v[46:49], v[134:137], v[198:201], v[46:49]
	v_mfma_f32_16x16x32_bf16 v[42:45], v[156:159], v[198:201], v[42:45]
	v_mfma_f32_16x16x32_bf16 v[30:33], v[134:137], v[206:209], v[30:33]
	v_mfma_f32_16x16x32_bf16 v[26:29], v[156:159], v[206:209], v[26:29]
	v_mfma_f32_16x16x32_bf16 v[12:15], v[134:137], v[214:217], v[12:15]
	v_mfma_f32_16x16x32_bf16 v[8:11], v[156:159], v[214:217], v[8:11]
	v_mfma_f32_16x16x32_bf16 v[54:57], v[160:163], v[186:189], v[54:57]
	v_mfma_f32_16x16x32_bf16 v[50:53], v[178:181], v[186:189], v[50:53]
	v_mfma_f32_16x16x32_bf16 v[38:41], v[160:163], v[194:197], v[38:41]
	v_mfma_f32_16x16x32_bf16 v[34:37], v[178:181], v[194:197], v[34:37]
	v_mfma_f32_16x16x32_bf16 v[22:25], v[160:163], v[202:205], v[22:25]
	v_mfma_f32_16x16x32_bf16 v[18:21], v[178:181], v[202:205], v[18:21]
	v_mfma_f32_16x16x32_bf16 v[4:7], v[160:163], v[210:213], v[4:7]
	v_mfma_f32_16x16x32_bf16 v[0:3], v[178:181], v[210:213], v[0:3]
	v_mfma_f32_16x16x32_bf16 v[54:57], v[174:177], v[190:193], v[54:57]
	v_mfma_f32_16x16x32_bf16 v[50:53], v[182:185], v[190:193], v[50:53]
	v_mfma_f32_16x16x32_bf16 v[38:41], v[174:177], v[198:201], v[38:41]
	v_mfma_f32_16x16x32_bf16 v[34:37], v[182:185], v[198:201], v[34:37]
	v_mfma_f32_16x16x32_bf16 v[22:25], v[174:177], v[206:209], v[22:25]
	v_mfma_f32_16x16x32_bf16 v[18:21], v[182:185], v[206:209], v[18:21]
	v_mfma_f32_16x16x32_bf16 v[4:7], v[174:177], v[214:217], v[4:7]
	v_mfma_f32_16x16x32_bf16 v[0:3], v[182:185], v[214:217], v[0:3]
	s_barrier
; #define PG8_STAGEA(bufoff, gbase, voff) PG8_STAGE_X(bufoff, gbase, voff, AUXA)
; #define PG8_LDA(dst, b, h) do { _Pragma("unroll") for (int m = 0; m < 4; ++m) _Pragma("unroll") for (int k = 0; k < 2; ++k) dst[m][k] = *(const PG8_LAS bf16x8*)(lds + PG8_SA(b, h) + aoff + m * 2048 + k * 1024); } while (0)
; #define PG8_LDB(dst, b, h) do { _Pragma("unroll") for (int n = 0; n < 2; ++n) _Pragma("unroll") for (int k = 0; k < 2; ++k) dst[n][k] = *(const PG8_LAS bf16x8*)(lds + PG8_SB(b, h) + boff + n * 2048 + k * 1024); } while (0)
; #define PG8_MMA(ai, bj, At, Bt) do { if (GEMM_PRIO_MODE == 0) __builtin_amdgcn_s_setprio(1); PG8_MMA_LOOPS \
;         acc[ai][bj][m][n] = __builtin_amdgcn_mfma_f32_16x16x32_bf16(Bt[n][k], At[m][k], acc[ai][bj][m][n], 0, 0, 0); if (GEMM_PRIO_MODE == 0) __builtin_amdgcn_s_setprio(0); } while (0)
; #define PG8_WAIT_V(n) asm volatile("s_waitcnt vmcnt(" #n ")" ::: "memory")
; #define PG8_WAIT_L(n) asm volatile("s_waitcnt lgkmcnt(" #n ")" ::: "memory")
; #define PG8_BAR __builtin_amdgcn_s_barrier()
; #define PG8_SCHED __builtin_amdgcn_sched_barrier(0)
;     ...
;             PG8_LDB(B0, 1, 0); PG8_LDB(B1, 1, 1); PG8_SCHED; PG8_LDA(At, 1, 0); PG8_STAGEA(PG8_SA(0, 1), a2 + hstepA, voffA);
;             PG8_WAIT_V(8); PG8_WAIT_L(0); PG8_BAR; PG8_MMA(0, 0, At, B0); PG8_MMA(0, 1, At, B1); PG8_BAR; PG8_SCHED;
	s_setprio 0
	s_add_i32 s18, 0, 0x18000
	v_add_u32_e32 v16, s18, v167
	s_add_i32 s19, 0, 0x1c000
	ds_read_b128 v[130:133], v16
	ds_read_b128 v[134:137], v16 offset:1024
	ds_read_b128 v[152:155], v16 offset:2048
	ds_read_b128 v[156:159], v16 offset:3072
	v_add_u32_e32 v16, s19, v167
	ds_read_b128 v[160:163], v16
	ds_read_b128 v[174:177], v16 offset:1024
	ds_read_b128 v[178:181], v16 offset:2048
	ds_read_b128 v[182:185], v16 offset:3072
	s_add_u32 s14, s14, 0x100000
	s_addc_u32 s15, s15, 0
	s_mov_b32 m0, s69
	v_lshl_add_u64 v[224:225], s[14:15], 0, v[144:145]
	ds_read_b128 v[186:189], v172 offset:32768
	ds_read_b128 v[190:193], v172 offset:33792
	ds_read_b128 v[194:197], v172 offset:34816
	ds_read_b128 v[198:201], v172 offset:35840
	ds_read_b128 v[202:205], v172 offset:36864
	ds_read_b128 v[206:209], v172 offset:37888
	ds_read_b128 v[210:213], v172 offset:38912
	ds_read_b128 v[214:217], v172 offset:39936
	global_load_lds_dwordx4 v[224:225], off
	v_lshl_add_u64 v[224:225], s[14:15], 0, v[140:141]
	s_mov_b32 m0, s72
	s_nop 0
	global_load_lds_dwordx4 v[224:225], off
	s_waitcnt vmcnt(8)
	s_waitcnt lgkmcnt(0)
	s_nop 0
	s_nop 0
	s_nop 0
	s_nop 0
	s_nop 0
	s_nop 0
	s_setprio 1
	s_barrier
	v_mfma_f32_16x16x32_bf16 v[126:129], v[130:133], v[186:189], v[126:129]
	v_mfma_f32_16x16x32_bf16 v[122:125], v[152:155], v[186:189], v[122:125]
	v_mfma_f32_16x16x32_bf16 v[110:113], v[130:133], v[194:197], v[110:113]
	v_mfma_f32_16x16x32_bf16 v[106:109], v[152:155], v[194:197], v[106:109]
	v_mfma_f32_16x16x32_bf16 v[94:97], v[130:133], v[202:205], v[94:97]
	v_mfma_f32_16x16x32_bf16 v[90:93], v[152:155], v[202:205], v[90:93]
	v_mfma_f32_16x16x32_bf16 v[78:81], v[130:133], v[210:213], v[78:81]
	v_mfma_f32_16x16x32_bf16 v[74:77], v[152:155], v[210:213], v[74:77]
	v_mfma_f32_16x16x32_bf16 v[126:129], v[134:137], v[190:193], v[126:129]
	v_mfma_f32_16x16x32_bf16 v[122:125], v[156:159], v[190:193], v[122:125]
	v_mfma_f32_16x16x32_bf16 v[110:113], v[134:137], v[198:201], v[110:113]
	v_mfma_f32_16x16x32_bf16 v[106:109], v[156:159], v[198:201], v[106:109]
	v_mfma_f32_16x16x32_bf16 v[94:97], v[134:137], v[206:209], v[94:97]
	v_mfma_f32_16x16x32_bf16 v[90:93], v[156:159], v[206:209], v[90:93]
	v_mfma_f32_16x16x32_bf16 v[78:81], v[134:137], v[214:217], v[78:81]
	v_mfma_f32_16x16x32_bf16 v[74:77], v[156:159], v[214:217], v[74:77]
	v_mfma_f32_16x16x32_bf16 v[118:121], v[160:163], v[186:189], v[118:121]
	v_mfma_f32_16x16x32_bf16 v[114:117], v[178:181], v[186:189], v[114:117]
	v_mfma_f32_16x16x32_bf16 v[102:105], v[160:163], v[194:197], v[102:105]
	v_mfma_f32_16x16x32_bf16 v[98:101], v[178:181], v[194:197], v[98:101]
	v_mfma_f32_16x16x32_bf16 v[86:89], v[160:163], v[202:205], v[86:89]
	v_mfma_f32_16x16x32_bf16 v[82:85], v[178:181], v[202:205], v[82:85]
	v_mfma_f32_16x16x32_bf16 v[70:73], v[160:163], v[210:213], v[70:73]
	v_mfma_f32_16x16x32_bf16 v[66:69], v[178:181], v[210:213], v[66:69]
	v_mfma_f32_16x16x32_bf16 v[118:121], v[174:177], v[190:193], v[118:121]
	v_mfma_f32_16x16x32_bf16 v[114:117], v[182:185], v[190:193], v[114:117]
	v_mfma_f32_16x16x32_bf16 v[102:105], v[174:177], v[198:201], v[102:105]
	v_mfma_f32_16x16x32_bf16 v[98:101], v[182:185], v[198:201], v[98:101]
	v_mfma_f32_16x16x32_bf16 v[86:89], v[174:177], v[206:209], v[86:89]
	v_mfma_f32_16x16x32_bf16 v[82:85], v[182:185], v[206:209], v[82:85]
	v_mfma_f32_16x16x32_bf16 v[70:73], v[174:177], v[214:217], v[70:73]
	v_mfma_f32_16x16x32_bf16 v[66:69], v[182:185], v[214:217], v[66:69]
	s_barrier
; #define PG8_STAGEA(bufoff, gbase, voff) PG8_STAGE_X(bufoff, gbase, voff, AUXA)
; #define PG8_STAGEB(bufoff, gbase, voff) PG8_STAGE_X(bufoff, gbase, voff, AUXB)
; #define PG8_LDA(dst, b, h) do { _Pragma("unroll") for (int m = 0; m < 4; ++m) _Pragma("unroll") for (int k = 0; k < 2; ++k) dst[m][k] = *(const PG8_LAS bf16x8*)(lds + PG8_SA(b, h) + aoff + m * 2048 + k * 1024); } while (0)
; #define PG8_MMA(ai, bj, At, Bt) do { if (GEMM_PRIO_MODE == 0) __builtin_amdgcn_s_setprio(1); PG8_MMA_LOOPS \
;         acc[ai][bj][m][n] = __builtin_amdgcn_mfma_f32_16x16x32_bf16(Bt[n][k], At[m][k], acc[ai][bj][m][n], 0, 0, 0); if (GEMM_PRIO_MODE == 0) __builtin_amdgcn_s_setprio(0); } while (0)
; #define PG8_WAIT_V(n) asm volatile("s_waitcnt vmcnt(" #n ")" ::: "memory")
; #define PG8_WAIT_L(n) asm volatile("s_waitcnt lgkmcnt(" #n ")" ::: "memory")
; #define PG8_BAR __builtin_amdgcn_s_barrier()
; #define PG8_SCHED __builtin_amdgcn_sched_barrier(0)
;     ...
;             PG8_LDA(At, 1, 1); PG8_STAGEB(PG8_SB(1, 0), b3, voffB); PG8_STAGEB(PG8_SB(1, 1), b3 + hstepB, voffB); PG8_STAGEA(PG8_SA(1, 0), a3, voffA);
;             PG8_WAIT_V(8); PG8_WAIT_L(0); PG8_BAR; PG8_MMA(1, 0, At, B0); PG8_MMA(1, 1, At, B1); PG8_BAR; PG8_SCHED;
;     ...
;         if constexpr (ALIGN_EPI) { if (wr == 0) PG8_BAR; }
	s_setprio 0
	s_add_i32 s14, s18, s42
	v_lshl_add_u64 v[164:165], v[164:165], 0, s[86:87]
	s_mov_b32 m0, s14
	ds_read_b128 v[186:189], v172 offset:49152
	ds_read_b128 v[190:193], v172 offset:50176
	ds_read_b128 v[194:197], v172 offset:51200
	ds_read_b128 v[198:201], v172 offset:52224
	ds_read_b128 v[202:205], v172 offset:53248
	ds_read_b128 v[206:209], v172 offset:54272
	ds_read_b128 v[210:213], v172 offset:55296
	ds_read_b128 v[214:217], v172 offset:56320
	global_load_lds_dwordx4 v[164:165], off
	s_add_i32 m0, s14, 0x2000
	s_add_u32 s10, s10, 0x100080
	v_lshl_add_u64 v[164:165], v[218:219], 0, s[86:87]
	s_addc_u32 s11, s11, 0
	s_add_i32 s14, s19, s42
	global_load_lds_dwordx4 v[164:165], off
	v_lshl_add_u64 v[164:165], s[10:11], 0, v[142:143]
	s_mov_b32 m0, s14
	s_nop 0
	global_load_lds_dwordx4 v[164:165], off
	v_lshl_add_u64 v[164:165], s[10:11], 0, v[138:139]
	s_add_i32 m0, s14, 0x2000
	s_nop 0
	global_load_lds_dwordx4 v[164:165], off
	v_lshl_add_u64 v[164:165], v[220:221], 0, s[86:87]
	s_mov_b32 m0, s73
	s_nop 0
	global_load_lds_dwordx4 v[164:165], off
	v_lshl_add_u64 v[164:165], v[222:223], 0, s[86:87]
	s_mov_b32 m0, s82
	s_nop 0
	global_load_lds_dwordx4 v[164:165], off
	s_waitcnt vmcnt(8)
	s_waitcnt lgkmcnt(0)
	s_nop 0
	s_setprio 1
	s_barrier
	v_mfma_f32_16x16x32_bf16 v[62:65], v[130:133], v[186:189], v[62:65]
	v_mfma_f32_16x16x32_bf16 v[58:61], v[152:155], v[186:189], v[58:61]
	v_mfma_f32_16x16x32_bf16 v[46:49], v[130:133], v[194:197], v[46:49]
	v_mfma_f32_16x16x32_bf16 v[42:45], v[152:155], v[194:197], v[42:45]
	v_mfma_f32_16x16x32_bf16 v[30:33], v[130:133], v[202:205], v[30:33]
	v_mfma_f32_16x16x32_bf16 v[26:29], v[152:155], v[202:205], v[26:29]
	v_mfma_f32_16x16x32_bf16 v[12:15], v[130:133], v[210:213], v[12:15]
	v_mfma_f32_16x16x32_bf16 v[8:11], v[152:155], v[210:213], v[8:11]
	v_mfma_f32_16x16x32_bf16 v[62:65], v[134:137], v[190:193], v[62:65]
	v_mfma_f32_16x16x32_bf16 v[58:61], v[156:159], v[190:193], v[58:61]
	v_mfma_f32_16x16x32_bf16 v[46:49], v[134:137], v[198:201], v[46:49]
	v_mfma_f32_16x16x32_bf16 v[42:45], v[156:159], v[198:201], v[42:45]
	v_mfma_f32_16x16x32_bf16 v[30:33], v[134:137], v[206:209], v[30:33]
	v_mfma_f32_16x16x32_bf16 v[26:29], v[156:159], v[206:209], v[26:29]
	v_mfma_f32_16x16x32_bf16 v[12:15], v[134:137], v[214:217], v[12:15]
	v_mfma_f32_16x16x32_bf16 v[8:11], v[156:159], v[214:217], v[8:11]
	v_mfma_f32_16x16x32_bf16 v[54:57], v[160:163], v[186:189], v[54:57]
	v_mfma_f32_16x16x32_bf16 v[50:53], v[178:181], v[186:189], v[50:53]
	v_mfma_f32_16x16x32_bf16 v[38:41], v[160:163], v[194:197], v[38:41]
	v_mfma_f32_16x16x32_bf16 v[34:37], v[178:181], v[194:197], v[34:37]
	v_mfma_f32_16x16x32_bf16 v[22:25], v[160:163], v[202:205], v[22:25]
	v_mfma_f32_16x16x32_bf16 v[18:21], v[178:181], v[202:205], v[18:21]
	v_mfma_f32_16x16x32_bf16 v[4:7], v[160:163], v[210:213], v[4:7]
	v_mfma_f32_16x16x32_bf16 v[0:3], v[178:181], v[210:213], v[0:3]
	v_mfma_f32_16x16x32_bf16 v[54:57], v[174:177], v[190:193], v[54:57]
	v_mfma_f32_16x16x32_bf16 v[50:53], v[182:185], v[190:193], v[50:53]
	v_mfma_f32_16x16x32_bf16 v[38:41], v[174:177], v[198:201], v[38:41]
	v_mfma_f32_16x16x32_bf16 v[34:37], v[182:185], v[198:201], v[34:37]
	v_mfma_f32_16x16x32_bf16 v[22:25], v[174:177], v[206:209], v[22:25]
	v_mfma_f32_16x16x32_bf16 v[18:21], v[182:185], v[206:209], v[18:21]
	v_mfma_f32_16x16x32_bf16 v[4:7], v[174:177], v[214:217], v[4:7]
	v_mfma_f32_16x16x32_bf16 v[0:3], v[182:185], v[214:217], v[0:3]
	s_barrier
	s_setprio 0
	s_add_i32 s27, s27, 2
	s_add_u32 s8, s8, 0x100
	s_addc_u32 s9, s9, 0
	s_add_u32 s0, s0, 0x100
	s_addc_u32 s1, s1, 0
	s_cmp_gt_u32 s27, 61
	s_cbranch_scc0 .LBB0_129
	s_and_b64 vcc, exec, s[24:25]
	s_cbranch_vccz .LBB0_132
	s_barrier

; #define PG8_STAGEA(bufoff, gbase, voff) PG8_STAGE_X(bufoff, gbase, voff, AUXA)
; #define PG8_STR(x) PG8_STR2(x)
;     ...
;         const bool has_next = S.next(ui + 1, nxt);
;         const char* nA = has_next ? (const char*)g.A + (size_t)nxt.pm * tstepA : cA; const char* nB = has_next ? (const char*)g.Bt + (size_t)nxt.pn * tstepB : cB;
;         int t0 = 0;
;         if constexpr (SP2 && GEMM_RELAX == 1) { if (ui > 0) {
;             const char* a1 = cA + kstepA; const char* a2 = cA + 2 * kstepA; const char* b2 = cB + 2 * kstepB; const char* a3 = a2 + kstepA; const char* b3 = b2 + kstepB;
;             PG8_LDB(B0, 0, 0); PG8_LDB(B1, 0, 1); PG8_SCHED; PG8_LDA(At, 0, 0); PG8_STAGEA(PG8_SA(1, 1), a1 + hstepA, voffA);
;             PG8_WAIT_V(24); PG8_WAIT_L(0); PG8_BAR; PG8_MMA(0, 0, At, B0); PG8_MMA(0, 1, At, B1); PG8_BAR; PG8_SCHED;
;             PG8_LDA(At, 0, 1); PG8_STAGEB(PG8_SB(0, 0), b2, voffB); PG8_STAGEB(PG8_SB(0, 1), b2 + hstepB, voffB); PG8_STAGEA(PG8_SA(0, 0), a2, voffA);
;             PG8_WAIT_V(24); PG8_WAIT_L(0); PG8_BAR; PG8_MMA(1, 0, At, B0); PG8_MMA(1, 1, At, B1); PG8_BAR; PG8_SCHED;
;             PG8_LDB(B0, 1, 0); PG8_LDB(B1, 1, 1); PG8_SCHED; PG8_LDA(At, 1, 0); PG8_STAGEA(PG8_SA(0, 1), a2 + hstepA, voffA);
;             PG8_WAIT_V(8); PG8_WAIT_L(0); PG8_BAR; PG8_MMA(0, 0, At, B0); PG8_MMA(0, 1, At, B1); PG8_BAR; PG8_SCHED;
;             PG8_LDA(At, 1, 1); PG8_STAGEB(PG8_SB(1, 0), b3, voffB); PG8_STAGEB(PG8_SB(1, 1), b3 + hstepB, voffB); PG8_STAGEA(PG8_SA(1, 0), a3, voffA);
;             PG8_WAIT_V(8); PG8_WAIT_L(0); PG8_BAR; PG8_MMA(1, 0, At, B0); PG8_MMA(1, 1, At, B1); PG8_BAR; PG8_SCHED;
;             t0 = 2; } }
;     ...
;         asm volatile(".p2align " PG8_STR(GEMM_LOOP_ALIGN) ::: "memory");
;     ...
;         for (int t = t0; t < nt; t += 2) {
;             const bool last = (t == nt - 2);
;             const char* a1 = cA + (size_t)(t + 1) * kstepA;
;             const char* a2 = last ? nA : cA + (size_t)(t + 2) * kstepA; const char* b2 = last ? nB : cB + (size_t)(t + 2) * kstepB;
;             const char* a3 = a2 + kstepA; const char* b3 = b2 + kstepB;
;             if (last && has_next) S.a_ready(nxt);
;             if constexpr (SP2) {
;             PG8_LDB(B0, 0, 0); PG8_LDB(B1, 0, 1); PG8_SCHED; PG8_LDA(At, 0, 0); PG8_STAGEA(PG8_SA(1, 1), a1 + hstepA, voffA);
;     ...
;             const int relax = __builtin_amdgcn_readfirstlane((t == 0 && ui > 0) ? 1 : 0);
.LBB0_557:
	s_ashr_i32 s21, s20, 31
	s_lshl_b64 s[6:7], s[20:21], 21
	s_add_u32 s24, s60, s6
	s_addc_u32 s25, s61, s7
	s_and_b64 s[6:7], s[26:27], exec
	s_cselect_b32 s21, s25, s1
	s_cselect_b32 s82, s24, s0
	s_ashr_i32 s23, s22, 31
	s_lshl_b64 s[6:7], s[22:23], 21
	s_add_u32 s36, s4, s6
	s_addc_u32 s37, s5, s7
	s_and_b64 s[6:7], s[26:27], exec
	s_cselect_b32 s23, s37, s41
	s_cselect_b32 s83, s36, s40
	s_add_u32 s38, s0, 0x100080
	s_addc_u32 s39, s1, 0
	s_add_u32 s0, s40, 0x100
	s_addc_u32 s1, s41, 0
	s_mov_b32 s90, -2
	s_waitcnt lgkmcnt(0)
	s_waitcnt vmcnt(0)
	s_add_u32 s6, s38, 0xfff00080
	s_addc_u32 s7, s39, -1
	s_add_i32 s91, 0, 0x10000
	s_cmp_eq_u32 s90, 60
	s_cselect_b32 s41, s21, s7
	s_cselect_b32 s40, s82, s6
	s_cselect_b32 s17, s23, s1
	s_cselect_b32 s16, s83, s0
	s_add_i32 s94, 0, 0x14000
	v_add_u32_e32 v152, s91, v157
	v_add_u32_e32 v174, s94, v157
	ds_read_b128 v[130:133], v152
	ds_read_b128 v[134:137], v152 offset:1024
	ds_read_b128 v[148:151], v152 offset:2048
	ds_read_b128 v[152:155], v152 offset:3072
	ds_read_b128 v[162:165], v174
	ds_read_b128 v[166:169], v174 offset:1024
	ds_read_b128 v[170:173], v174 offset:2048
	ds_read_b128 v[174:177], v174 offset:3072
	v_lshl_add_u64 v[210:211], s[38:39], 0, v[144:145]
	s_add_i32 m0, s13, 0xc000
	ds_read_b128 v[178:181], v161
	ds_read_b128 v[182:185], v161 offset:1024
	ds_read_b128 v[186:189], v161 offset:2048
	ds_read_b128 v[190:193], v161 offset:3072
	ds_read_b128 v[194:197], v161 offset:4096
	ds_read_b128 v[198:201], v161 offset:5120
	ds_read_b128 v[202:205], v161 offset:6144
	ds_read_b128 v[206:209], v161 offset:7168
	global_load_lds_dwordx4 v[210:211], off
	v_lshl_add_u64 v[210:211], s[38:39], 0, v[146:147]
	s_add_i32 m0, s13, 0xe000
	s_nop 0
	global_load_lds_dwordx4 v[210:211], off
	s_waitcnt vmcnt(8)
	s_waitcnt lgkmcnt(0)
	s_nop 0
	s_nop 0
	s_nop 0
	s_nop 0
	s_nop 0
	s_nop 0
	s_nop 0
	s_nop 0
	s_nop 0
	s_nop 0
	s_setprio 1
	s_barrier
	v_mfma_f32_16x16x32_bf16 v[126:129], v[130:133], v[178:181], 0
	v_mfma_f32_16x16x32_bf16 v[122:125], v[148:151], v[178:181], 0
	v_mfma_f32_16x16x32_bf16 v[110:113], v[130:133], v[186:189], 0
	v_mfma_f32_16x16x32_bf16 v[106:109], v[148:151], v[186:189], 0
	v_mfma_f32_16x16x32_bf16 v[94:97], v[130:133], v[194:197], 0
	v_mfma_f32_16x16x32_bf16 v[90:93], v[148:151], v[194:197], 0
	v_mfma_f32_16x16x32_bf16 v[78:81], v[130:133], v[202:205], 0
	v_mfma_f32_16x16x32_bf16 v[74:77], v[148:151], v[202:205], 0
	v_mfma_f32_16x16x32_bf16 v[126:129], v[134:137], v[182:185], v[126:129]
	v_mfma_f32_16x16x32_bf16 v[122:125], v[152:155], v[182:185], v[122:125]
	v_mfma_f32_16x16x32_bf16 v[110:113], v[134:137], v[190:193], v[110:113]
	v_mfma_f32_16x16x32_bf16 v[106:109], v[152:155], v[190:193], v[106:109]
	v_mfma_f32_16x16x32_bf16 v[94:97], v[134:137], v[198:201], v[94:97]
	v_mfma_f32_16x16x32_bf16 v[90:93], v[152:155], v[198:201], v[90:93]
	v_mfma_f32_16x16x32_bf16 v[78:81], v[134:137], v[206:209], v[78:81]
	v_mfma_f32_16x16x32_bf16 v[74:77], v[152:155], v[206:209], v[74:77]
	v_mfma_f32_16x16x32_bf16 v[118:121], v[162:165], v[178:181], 0
	v_mfma_f32_16x16x32_bf16 v[114:117], v[170:173], v[178:181], 0
	v_mfma_f32_16x16x32_bf16 v[102:105], v[162:165], v[186:189], 0
	v_mfma_f32_16x16x32_bf16 v[98:101], v[170:173], v[186:189], 0
	v_mfma_f32_16x16x32_bf16 v[86:89], v[162:165], v[194:197], 0
	v_mfma_f32_16x16x32_bf16 v[82:85], v[170:173], v[194:197], 0
	v_mfma_f32_16x16x32_bf16 v[70:73], v[162:165], v[202:205], 0
	v_mfma_f32_16x16x32_bf16 v[66:69], v[170:173], v[202:205], 0
	v_mfma_f32_16x16x32_bf16 v[118:121], v[166:169], v[182:185], v[118:121]
	v_mfma_f32_16x16x32_bf16 v[114:117], v[174:177], v[182:185], v[114:117]
	v_mfma_f32_16x16x32_bf16 v[102:105], v[166:169], v[190:193], v[102:105]
	v_mfma_f32_16x16x32_bf16 v[98:101], v[174:177], v[190:193], v[98:101]
	v_mfma_f32_16x16x32_bf16 v[86:89], v[166:169], v[198:201], v[86:89]
	v_mfma_f32_16x16x32_bf16 v[82:85], v[174:177], v[198:201], v[82:85]
	v_mfma_f32_16x16x32_bf16 v[70:73], v[166:169], v[206:209], v[70:73]
	v_mfma_f32_16x16x32_bf16 v[66:69], v[174:177], v[206:209], v[66:69]
	s_barrier
	s_setprio 0
	s_add_i32 s6, s91, s12
	v_lshl_add_u64 v[210:211], s[16:17], 0, v[16:17]
	s_mov_b32 m0, s6
	ds_read_b128 v[178:181], v161 offset:16384
	ds_read_b128 v[182:185], v161 offset:17408
	ds_read_b128 v[186:189], v161 offset:18432
	ds_read_b128 v[190:193], v161 offset:19456
	ds_read_b128 v[194:197], v161 offset:20480
	ds_read_b128 v[198:201], v161 offset:21504
	ds_read_b128 v[202:205], v161 offset:22528
	ds_read_b128 v[206:209], v161 offset:23552
	global_load_lds_dwordx4 v[210:211], off
	s_add_i32 m0, s6, 0x2000
	s_add_u32 s6, s16, 0x100000
	v_lshl_add_u64 v[212:213], s[16:17], 0, v[138:139]
	s_addc_u32 s7, s17, 0
	s_add_i32 s91, s94, s12
	global_load_lds_dwordx4 v[212:213], off
	v_lshl_add_u64 v[214:215], s[6:7], 0, v[16:17]
	s_mov_b32 m0, s91
	v_lshl_add_u64 v[216:217], s[40:41], 0, v[140:141]
	global_load_lds_dwordx4 v[214:215], off
	v_lshl_add_u64 v[214:215], s[6:7], 0, v[138:139]
	s_add_i32 m0, s91, 0x2000
	s_nop 0
	global_load_lds_dwordx4 v[214:215], off
	v_lshl_add_u64 v[214:215], s[40:41], 0, v[142:143]
	s_mov_b32 m0, s13
	s_nop 0
	global_load_lds_dwordx4 v[214:215], off
	s_mov_b32 m0, s42
	s_nop 0
	global_load_lds_dwordx4 v[216:217], off
	s_waitcnt vmcnt(8)
	s_waitcnt lgkmcnt(0)
	s_nop 0
	s_nop 0
	s_setprio 1
	s_barrier
; #define PG8_STAGEA(bufoff, gbase, voff) PG8_STAGE_X(bufoff, gbase, voff, AUXA)
; #define PG8_STAGEB(bufoff, gbase, voff) PG8_STAGE_X(bufoff, gbase, voff, AUXB)
; #define PG8_LDA(dst, b, h) do { _Pragma("unroll") for (int m = 0; m < 4; ++m) _Pragma("unroll") for (int k = 0; k < 2; ++k) dst[m][k] = *(const PG8_LAS bf16x8*)(lds + PG8_SA(b, h) + aoff + m * 2048 + k * 1024); } while (0)
; #define PG8_LDB(dst, b, h) do { _Pragma("unroll") for (int n = 0; n < 2; ++n) _Pragma("unroll") for (int k = 0; k < 2; ++k) dst[n][k] = *(const PG8_LAS bf16x8*)(lds + PG8_SB(b, h) + boff + n * 2048 + k * 1024); } while (0)
; #define PG8_MMA(ai, bj, At, Bt) do { if (GEMM_PRIO_MODE == 0) __builtin_amdgcn_s_setprio(1); PG8_MMA_LOOPS \
;         acc[ai][bj][m][n] = __builtin_amdgcn_mfma_f32_16x16x32_bf16(Bt[n][k], At[m][k], acc[ai][bj][m][n], 0, 0, 0); if (GEMM_PRIO_MODE == 0) __builtin_amdgcn_s_setprio(0); } while (0)
; #define PG8_WAIT_V(n) asm volatile("s_waitcnt vmcnt(" #n ")" ::: "memory")
; #define PG8_WAIT_VR(n, nr, flag) asm volatile("s_cmp_eq_u32 %0, 0\n\ts_cbranch_scc1 .Lpg8s%=\n\ts_waitcnt vmcnt(" #nr ")\n\ts_branch .Lpg8d%=\n.Lpg8s%=:\n\ts_waitcnt vmcnt(" #n ")\n.Lpg8d%=:" :: "s"(flag) : "memory", "scc")
; #define PG8_WAIT_L(n) asm volatile("s_waitcnt lgkmcnt(" #n ")" ::: "memory")
; #define PG8_BAR __builtin_amdgcn_s_barrier()
; #define PG8_SCHED __builtin_amdgcn_sched_barrier(0)
;     ...
;             PG8_LDA(At, 0, 1); PG8_STAGEB(PG8_SB(0, 0), b2, voffB); PG8_STAGEB(PG8_SB(0, 1), b2 + hstepB, voffB); PG8_STAGEA(PG8_SA(0, 0), a2, voffA);
;     ...
;             PG8_WAIT_VR(8, 24, relax); PG8_WAIT_L(0); PG8_BAR; PG8_MMA(1, 0, At, B0); PG8_MMA(1, 1, At, B1); PG8_BAR; PG8_SCHED;
;     ...
;             PG8_WAIT_V(8); PG8_WAIT_L(0); PG8_BAR; PG8_MMA(1, 0, At, B0); PG8_MMA(1, 1, At, B1); PG8_BAR; PG8_SCHED;
;     ...
;             PG8_LDB(B0, 1, 0); PG8_LDB(B1, 1, 1); PG8_SCHED; PG8_LDA(At, 1, 0); PG8_STAGEA(PG8_SA(0, 1), a2 + hstepA, voffA);
;             PG8_WAIT_V(8); PG8_WAIT_L(0); PG8_BAR; PG8_MMA(0, 0, At, B0); PG8_MMA(0, 1, At, B1); PG8_BAR; PG8_SCHED;
	v_mfma_f32_16x16x32_bf16 v[62:65], v[130:133], v[178:181], 0
	v_mfma_f32_16x16x32_bf16 v[58:61], v[148:151], v[178:181], 0
	v_mfma_f32_16x16x32_bf16 v[46:49], v[130:133], v[186:189], 0
	v_mfma_f32_16x16x32_bf16 v[42:45], v[148:151], v[186:189], 0
	v_mfma_f32_16x16x32_bf16 v[30:33], v[130:133], v[194:197], 0
	v_mfma_f32_16x16x32_bf16 v[26:29], v[148:151], v[194:197], 0
	v_mfma_f32_16x16x32_bf16 v[12:15], v[130:133], v[202:205], 0
	v_mfma_f32_16x16x32_bf16 v[8:11], v[148:151], v[202:205], 0
	v_mfma_f32_16x16x32_bf16 v[62:65], v[134:137], v[182:185], v[62:65]
	v_mfma_f32_16x16x32_bf16 v[58:61], v[152:155], v[182:185], v[58:61]
	v_mfma_f32_16x16x32_bf16 v[46:49], v[134:137], v[190:193], v[46:49]
	v_mfma_f32_16x16x32_bf16 v[42:45], v[152:155], v[190:193], v[42:45]
	v_mfma_f32_16x16x32_bf16 v[30:33], v[134:137], v[198:201], v[30:33]
	v_mfma_f32_16x16x32_bf16 v[26:29], v[152:155], v[198:201], v[26:29]
	v_mfma_f32_16x16x32_bf16 v[12:15], v[134:137], v[206:209], v[12:15]
	v_mfma_f32_16x16x32_bf16 v[8:11], v[152:155], v[206:209], v[8:11]
	v_mfma_f32_16x16x32_bf16 v[54:57], v[162:165], v[178:181], 0
	v_mfma_f32_16x16x32_bf16 v[50:53], v[170:173], v[178:181], 0
	v_mfma_f32_16x16x32_bf16 v[38:41], v[162:165], v[186:189], 0
	v_mfma_f32_16x16x32_bf16 v[34:37], v[170:173], v[186:189], 0
	v_mfma_f32_16x16x32_bf16 v[22:25], v[162:165], v[194:197], 0
	v_mfma_f32_16x16x32_bf16 v[18:21], v[170:173], v[194:197], 0
	v_mfma_f32_16x16x32_bf16 v[4:7], v[162:165], v[202:205], 0
	v_mfma_f32_16x16x32_bf16 v[0:3], v[170:173], v[202:205], 0
	v_mfma_f32_16x16x32_bf16 v[54:57], v[166:169], v[182:185], v[54:57]
	v_mfma_f32_16x16x32_bf16 v[50:53], v[174:177], v[182:185], v[50:53]
	v_mfma_f32_16x16x32_bf16 v[38:41], v[166:169], v[190:193], v[38:41]
	v_mfma_f32_16x16x32_bf16 v[34:37], v[174:177], v[190:193], v[34:37]
	v_mfma_f32_16x16x32_bf16 v[22:25], v[166:169], v[198:201], v[22:25]
	v_mfma_f32_16x16x32_bf16 v[18:21], v[174:177], v[198:201], v[18:21]
	v_mfma_f32_16x16x32_bf16 v[4:7], v[166:169], v[206:209], v[4:7]
	v_mfma_f32_16x16x32_bf16 v[0:3], v[174:177], v[206:209], v[0:3]
	s_barrier
	s_setprio 0
	s_add_i32 s91, 0, 0x18000
	s_add_i32 s94, 0, 0x1c000
	v_add_u32_e32 v152, s91, v157
	v_add_u32_e32 v174, s94, v157
	ds_read_b128 v[130:133], v152
	ds_read_b128 v[134:137], v152 offset:1024
	ds_read_b128 v[148:151], v152 offset:2048
	ds_read_b128 v[152:155], v152 offset:3072
	ds_read_b128 v[162:165], v174
	ds_read_b128 v[166:169], v174 offset:1024
	ds_read_b128 v[170:173], v174 offset:2048
	ds_read_b128 v[174:177], v174 offset:3072
	s_add_u32 s6, s40, 0x100000
	s_addc_u32 s7, s41, 0
	s_mov_b32 m0, s43
	v_lshl_add_u64 v[218:219], s[6:7], 0, v[142:143]
	ds_read_b128 v[178:181], v161 offset:32768
	ds_read_b128 v[182:185], v161 offset:33792
	ds_read_b128 v[186:189], v161 offset:34816
	ds_read_b128 v[190:193], v161 offset:35840
	ds_read_b128 v[194:197], v161 offset:36864
	ds_read_b128 v[198:201], v161 offset:37888
	ds_read_b128 v[202:205], v161 offset:38912
	ds_read_b128 v[206:209], v161 offset:39936
	global_load_lds_dwordx4 v[218:219], off
	v_lshl_add_u64 v[218:219], s[6:7], 0, v[140:141]
	s_mov_b32 m0, s50
	s_nop 0
	global_load_lds_dwordx4 v[218:219], off
	s_waitcnt vmcnt(8)
	s_waitcnt lgkmcnt(0)
	s_nop 0
	s_nop 0
	s_nop 0
	s_nop 0
	s_nop 0
	s_nop 0
	s_setprio 1
	s_barrier
	v_mfma_f32_16x16x32_bf16 v[126:129], v[130:133], v[178:181], v[126:129]
	v_mfma_f32_16x16x32_bf16 v[122:125], v[148:151], v[178:181], v[122:125]
	v_mfma_f32_16x16x32_bf16 v[110:113], v[130:133], v[186:189], v[110:113]
	v_mfma_f32_16x16x32_bf16 v[106:109], v[148:151], v[186:189], v[106:109]
	v_mfma_f32_16x16x32_bf16 v[94:97], v[130:133], v[194:197], v[94:97]
	v_mfma_f32_16x16x32_bf16 v[90:93], v[148:151], v[194:197], v[90:93]
	v_mfma_f32_16x16x32_bf16 v[78:81], v[130:133], v[202:205], v[78:81]
	v_mfma_f32_16x16x32_bf16 v[74:77], v[148:151], v[202:205], v[74:77]
	v_mfma_f32_16x16x32_bf16 v[126:129], v[134:137], v[182:185], v[126:129]
	v_mfma_f32_16x16x32_bf16 v[122:125], v[152:155], v[182:185], v[122:125]
	v_mfma_f32_16x16x32_bf16 v[110:113], v[134:137], v[190:193], v[110:113]
	v_mfma_f32_16x16x32_bf16 v[106:109], v[152:155], v[190:193], v[106:109]
	v_mfma_f32_16x16x32_bf16 v[94:97], v[134:137], v[198:201], v[94:97]
	v_mfma_f32_16x16x32_bf16 v[90:93], v[152:155], v[198:201], v[90:93]
	v_mfma_f32_16x16x32_bf16 v[78:81], v[134:137], v[206:209], v[78:81]
	v_mfma_f32_16x16x32_bf16 v[74:77], v[152:155], v[206:209], v[74:77]
	v_mfma_f32_16x16x32_bf16 v[118:121], v[162:165], v[178:181], v[118:121]
	v_mfma_f32_16x16x32_bf16 v[114:117], v[170:173], v[178:181], v[114:117]
	v_mfma_f32_16x16x32_bf16 v[102:105], v[162:165], v[186:189], v[102:105]
	v_mfma_f32_16x16x32_bf16 v[98:101], v[170:173], v[186:189], v[98:101]
	v_mfma_f32_16x16x32_bf16 v[86:89], v[162:165], v[194:197], v[86:89]
	v_mfma_f32_16x16x32_bf16 v[82:85], v[170:173], v[194:197], v[82:85]
	v_mfma_f32_16x16x32_bf16 v[70:73], v[162:165], v[202:205], v[70:73]
	v_mfma_f32_16x16x32_bf16 v[66:69], v[170:173], v[202:205], v[66:69]
	v_mfma_f32_16x16x32_bf16 v[118:121], v[166:169], v[182:185], v[118:121]
	v_mfma_f32_16x16x32_bf16 v[114:117], v[174:177], v[182:185], v[114:117]
	v_mfma_f32_16x16x32_bf16 v[102:105], v[166:169], v[190:193], v[102:105]
	v_mfma_f32_16x16x32_bf16 v[98:101], v[174:177], v[190:193], v[98:101]
	v_mfma_f32_16x16x32_bf16 v[86:89], v[166:169], v[198:201], v[86:89]
	v_mfma_f32_16x16x32_bf16 v[82:85], v[174:177], v[198:201], v[82:85]
	v_mfma_f32_16x16x32_bf16 v[70:73], v[166:169], v[206:209], v[70:73]
	v_mfma_f32_16x16x32_bf16 v[66:69], v[174:177], v[206:209], v[66:69]
	s_barrier
; #define PG8_STAGEA(bufoff, gbase, voff) PG8_STAGE_X(bufoff, gbase, voff, AUXA)
; #define PG8_STAGEB(bufoff, gbase, voff) PG8_STAGE_X(bufoff, gbase, voff, AUXB)
; #define PG8_LDA(dst, b, h) do { _Pragma("unroll") for (int m = 0; m < 4; ++m) _Pragma("unroll") for (int k = 0; k < 2; ++k) dst[m][k] = *(const PG8_LAS bf16x8*)(lds + PG8_SA(b, h) + aoff + m * 2048 + k * 1024); } while (0)
; #define PG8_WAIT_V(n) asm volatile("s_waitcnt vmcnt(" #n ")" ::: "memory")
; #define PG8_WAIT_L(n) asm volatile("s_waitcnt lgkmcnt(" #n ")" ::: "memory")
;     ...
;         for (int t = t0; t < nt; t += 2) {
;             const bool last = (t == nt - 2);
;             const char* a1 = cA + (size_t)(t + 1) * kstepA;
;             const char* a2 = last ? nA : cA + (size_t)(t + 2) * kstepA; const char* b2 = last ? nB : cB + (size_t)(t + 2) * kstepB;
;             const char* a3 = a2 + kstepA; const char* b3 = b2 + kstepB;
;             if (last && has_next) S.a_ready(nxt);
;             if constexpr (SP2) {
;             PG8_LDB(B0, 0, 0); PG8_LDB(B1, 0, 1); PG8_SCHED; PG8_LDA(At, 0, 0); PG8_STAGEA(PG8_SA(1, 1), a1 + hstepA, voffA);
;     ...
;             const int relax = __builtin_amdgcn_readfirstlane((t == 0 && ui > 0) ? 1 : 0);
;             PG8_WAIT_VR(8, 24, relax); PG8_WAIT_L(0); PG8_BAR; PG8_MMA(0, 0, At, B0); PG8_MMA(0, 1, At, B1); PG8_BAR; PG8_SCHED;
;     ...
;             PG8_WAIT_V(8); PG8_WAIT_L(0); PG8_BAR; PG8_MMA(0, 0, At, B0); PG8_MMA(0, 1, At, B1); PG8_BAR; PG8_SCHED;
;     ...
;             PG8_LDA(At, 0, 1); PG8_STAGEB(PG8_SB(0, 0), b2, voffB); PG8_STAGEB(PG8_SB(0, 1), b2 + hstepB, voffB); PG8_STAGEA(PG8_SA(0, 0), a2, voffA);
;     ...
;             PG8_WAIT_VR(8, 24, relax); PG8_WAIT_L(0); PG8_BAR; PG8_MMA(1, 0, At, B0); PG8_MMA(1, 1, At, B1); PG8_BAR; PG8_SCHED;
;     ...
;             PG8_WAIT_V(8); PG8_WAIT_L(0); PG8_BAR; PG8_MMA(1, 0, At, B0); PG8_MMA(1, 1, At, B1); PG8_BAR; PG8_SCHED;
;     ...
;             PG8_LDB(B0, 1, 0); PG8_LDB(B1, 1, 1); PG8_SCHED; PG8_LDA(At, 1, 0); PG8_STAGEA(PG8_SA(0, 1), a2 + hstepA, voffA);
;             PG8_WAIT_V(8); PG8_WAIT_L(0); PG8_BAR; PG8_MMA(0, 0, At, B0); PG8_MMA(0, 1, At, B1); PG8_BAR; PG8_SCHED;
;             PG8_LDA(At, 1, 1); PG8_STAGEB(PG8_SB(1, 0), b3, voffB); PG8_STAGEB(PG8_SB(1, 1), b3 + hstepB, voffB); PG8_STAGEA(PG8_SA(1, 0), a3, voffA);
;             PG8_WAIT_V(8); PG8_WAIT_L(0); PG8_BAR; PG8_MMA(1, 0, At, B0); PG8_MMA(1, 1, At, B1); PG8_BAR; PG8_SCHED;
	s_setprio 0
	s_add_i32 s6, s91, s12
	v_lshl_add_u64 v[210:211], v[210:211], 0, s[86:87]
	s_mov_b32 m0, s6
	ds_read_b128 v[178:181], v161 offset:49152
	ds_read_b128 v[182:185], v161 offset:50176
	ds_read_b128 v[186:189], v161 offset:51200
	ds_read_b128 v[190:193], v161 offset:52224
	ds_read_b128 v[194:197], v161 offset:53248
	ds_read_b128 v[198:201], v161 offset:54272
	ds_read_b128 v[202:205], v161 offset:55296
	ds_read_b128 v[206:209], v161 offset:56320
	global_load_lds_dwordx4 v[210:211], off
	s_add_i32 m0, s6, 0x2000
	s_add_u32 s6, s16, 0x100080
	v_lshl_add_u64 v[210:211], v[212:213], 0, s[86:87]
	s_addc_u32 s7, s17, 0
	s_add_i32 s16, s94, s12
	global_load_lds_dwordx4 v[210:211], off
	v_lshl_add_u64 v[210:211], s[6:7], 0, v[16:17]
	s_mov_b32 m0, s16
	s_nop 0
	global_load_lds_dwordx4 v[210:211], off
	v_lshl_add_u64 v[210:211], s[6:7], 0, v[138:139]
	s_add_i32 m0, s16, 0x2000
	s_nop 0
	global_load_lds_dwordx4 v[210:211], off
	v_lshl_add_u64 v[210:211], v[214:215], 0, s[86:87]
	s_mov_b32 m0, s68
	s_nop 0
	global_load_lds_dwordx4 v[210:211], off
	v_lshl_add_u64 v[210:211], v[216:217], 0, s[86:87]
	s_mov_b32 m0, s69
	s_nop 0
	global_load_lds_dwordx4 v[210:211], off
	s_waitcnt vmcnt(8)
	s_waitcnt lgkmcnt(0)
	s_nop 0
	s_setprio 1
	s_barrier
	v_mfma_f32_16x16x32_bf16 v[62:65], v[130:133], v[178:181], v[62:65]
	v_mfma_f32_16x16x32_bf16 v[58:61], v[148:151], v[178:181], v[58:61]
	v_mfma_f32_16x16x32_bf16 v[46:49], v[130:133], v[186:189], v[46:49]
	v_mfma_f32_16x16x32_bf16 v[42:45], v[148:151], v[186:189], v[42:45]
	v_mfma_f32_16x16x32_bf16 v[30:33], v[130:133], v[194:197], v[30:33]
	v_mfma_f32_16x16x32_bf16 v[26:29], v[148:151], v[194:197], v[26:29]
	v_mfma_f32_16x16x32_bf16 v[12:15], v[130:133], v[202:205], v[12:15]
	v_mfma_f32_16x16x32_bf16 v[8:11], v[148:151], v[202:205], v[8:11]
	v_mfma_f32_16x16x32_bf16 v[62:65], v[134:137], v[182:185], v[62:65]
	v_mfma_f32_16x16x32_bf16 v[58:61], v[152:155], v[182:185], v[58:61]
	v_mfma_f32_16x16x32_bf16 v[46:49], v[134:137], v[190:193], v[46:49]
	v_mfma_f32_16x16x32_bf16 v[42:45], v[152:155], v[190:193], v[42:45]
	v_mfma_f32_16x16x32_bf16 v[30:33], v[134:137], v[198:201], v[30:33]
	v_mfma_f32_16x16x32_bf16 v[26:29], v[152:155], v[198:201], v[26:29]
	v_mfma_f32_16x16x32_bf16 v[12:15], v[134:137], v[206:209], v[12:15]
	v_mfma_f32_16x16x32_bf16 v[8:11], v[152:155], v[206:209], v[8:11]
	v_mfma_f32_16x16x32_bf16 v[54:57], v[162:165], v[178:181], v[54:57]
	v_mfma_f32_16x16x32_bf16 v[50:53], v[170:173], v[178:181], v[50:53]
	v_mfma_f32_16x16x32_bf16 v[38:41], v[162:165], v[186:189], v[38:41]
	v_mfma_f32_16x16x32_bf16 v[34:37], v[170:173], v[186:189], v[34:37]
	v_mfma_f32_16x16x32_bf16 v[22:25], v[162:165], v[194:197], v[22:25]
	v_mfma_f32_16x16x32_bf16 v[18:21], v[170:173], v[194:197], v[18:21]
	v_mfma_f32_16x16x32_bf16 v[4:7], v[162:165], v[202:205], v[4:7]
	v_mfma_f32_16x16x32_bf16 v[0:3], v[170:173], v[202:205], v[0:3]
	v_mfma_f32_16x16x32_bf16 v[54:57], v[166:169], v[182:185], v[54:57]
	v_mfma_f32_16x16x32_bf16 v[50:53], v[174:177], v[182:185], v[50:53]
	v_mfma_f32_16x16x32_bf16 v[38:41], v[166:169], v[190:193], v[38:41]
	v_mfma_f32_16x16x32_bf16 v[34:37], v[174:177], v[190:193], v[34:37]
	v_mfma_f32_16x16x32_bf16 v[22:25], v[166:169], v[198:201], v[22:25]
	v_mfma_f32_16x16x32_bf16 v[18:21], v[174:177], v[198:201], v[18:21]
	v_mfma_f32_16x16x32_bf16 v[4:7], v[166:169], v[206:209], v[4:7]
	v_mfma_f32_16x16x32_bf16 v[0:3], v[174:177], v[206:209], v[0:3]
	s_barrier
	s_setprio 0
	s_add_i32 s90, s90, 2
	s_add_u32 s38, s38, 0x100
	s_addc_u32 s39, s39, 0
	s_add_u32 s0, s0, 0x100
	s_addc_u32 s1, s1, 0
.LBB0_558:
	s_add_u32 s6, s38, 0xfff00080
	s_addc_u32 s7, s39, -1
	s_add_i32 s91, 0, 0x10000
	s_cmp_eq_u32 s90, 60
	s_cselect_b32 s41, s21, s7
	s_cselect_b32 s40, s82, s6
	s_cselect_b32 s17, s23, s1
	s_cselect_b32 s16, s83, s0
	s_add_i32 s94, 0, 0x14000
	v_add_u32_e32 v152, s91, v157
	v_add_u32_e32 v174, s94, v157
	ds_read_b128 v[130:133], v152
	ds_read_b128 v[134:137], v152 offset:1024
	ds_read_b128 v[148:151], v152 offset:2048
	ds_read_b128 v[152:155], v152 offset:3072
	ds_read_b128 v[162:165], v174
	ds_read_b128 v[166:169], v174 offset:1024
	ds_read_b128 v[170:173], v174 offset:2048
	ds_read_b128 v[174:177], v174 offset:3072
	v_lshl_add_u64 v[210:211], s[38:39], 0, v[144:145]
	s_add_i32 m0, s13, 0xc000
	ds_read_b128 v[178:181], v161
	ds_read_b128 v[182:185], v161 offset:1024
	ds_read_b128 v[186:189], v161 offset:2048
	ds_read_b128 v[190:193], v161 offset:3072
	ds_read_b128 v[194:197], v161 offset:4096
	ds_read_b128 v[198:201], v161 offset:5120
	ds_read_b128 v[202:205], v161 offset:6144
	ds_read_b128 v[206:209], v161 offset:7168
	global_load_lds_dwordx4 v[210:211], off
	v_lshl_add_u64 v[210:211], s[38:39], 0, v[146:147]
	s_add_i32 m0, s13, 0xe000
	s_nop 0
	global_load_lds_dwordx4 v[210:211], off
	s_waitcnt vmcnt(8)
	s_waitcnt lgkmcnt(0)
	s_nop 0
	s_nop 0
	s_nop 0
	s_nop 0
	s_nop 0
	s_nop 0
	s_nop 0
	s_nop 0
	s_setprio 1
	s_barrier
; #define PG8_STAGEA(bufoff, gbase, voff) PG8_STAGE_X(bufoff, gbase, voff, AUXA)
; #define PG8_STAGEB(bufoff, gbase, voff) PG8_STAGE_X(bufoff, gbase, voff, AUXB)
; #define PG8_LDA(dst, b, h) do { _Pragma("unroll") for (int m = 0; m < 4; ++m) _Pragma("unroll") for (int k = 0; k < 2; ++k) dst[m][k] = *(const PG8_LAS bf16x8*)(lds + PG8_SA(b, h) + aoff + m * 2048 + k * 1024); } while (0)
; #define PG8_LDB(dst, b, h) do { _Pragma("unroll") for (int n = 0; n < 2; ++n) _Pragma("unroll") for (int k = 0; k < 2; ++k) dst[n][k] = *(const PG8_LAS bf16x8*)(lds + PG8_SB(b, h) + boff + n * 2048 + k * 1024); } while (0)
; #define PG8_MMA(ai, bj, At, Bt) do { if (GEMM_PRIO_MODE == 0) __builtin_amdgcn_s_setprio(1); PG8_MMA_LOOPS \
;         acc[ai][bj][m][n] = __builtin_amdgcn_mfma_f32_16x16x32_bf16(Bt[n][k], At[m][k], acc[ai][bj][m][n], 0, 0, 0); if (GEMM_PRIO_MODE == 0) __builtin_amdgcn_s_setprio(0); } while (0)
; #define PG8_WAIT_V(n) asm volatile("s_waitcnt vmcnt(" #n ")" ::: "memory")
; #define PG8_WAIT_VR(n, nr, flag) asm volatile("s_cmp_eq_u32 %0, 0\n\ts_cbranch_scc1 .Lpg8s%=\n\ts_waitcnt vmcnt(" #nr ")\n\ts_branch .Lpg8d%=\n.Lpg8s%=:\n\ts_waitcnt vmcnt(" #n ")\n.Lpg8d%=:" :: "s"(flag) : "memory", "scc")
; #define PG8_WAIT_L(n) asm volatile("s_waitcnt lgkmcnt(" #n ")" ::: "memory")
; #define PG8_BAR __builtin_amdgcn_s_barrier()
; #define PG8_SCHED __builtin_amdgcn_sched_barrier(0)
;     ...
;             PG8_LDB(B0, 0, 0); PG8_LDB(B1, 0, 1); PG8_SCHED; PG8_LDA(At, 0, 0); PG8_STAGEA(PG8_SA(1, 1), a1 + hstepA, voffA);
;     ...
;             const int relax = __builtin_amdgcn_readfirstlane((t == 0 && ui > 0) ? 1 : 0);
;             PG8_WAIT_VR(8, 24, relax); PG8_WAIT_L(0); PG8_BAR; PG8_MMA(0, 0, At, B0); PG8_MMA(0, 1, At, B1); PG8_BAR; PG8_SCHED;
;     ...
;             PG8_WAIT_V(8); PG8_WAIT_L(0); PG8_BAR; PG8_MMA(0, 0, At, B0); PG8_MMA(0, 1, At, B1); PG8_BAR; PG8_SCHED;
;     ...
;             PG8_LDA(At, 0, 1); PG8_STAGEB(PG8_SB(0, 0), b2, voffB); PG8_STAGEB(PG8_SB(0, 1), b2 + hstepB, voffB); PG8_STAGEA(PG8_SA(0, 0), a2, voffA);
;     ...
;             PG8_WAIT_VR(8, 24, relax); PG8_WAIT_L(0); PG8_BAR; PG8_MMA(1, 0, At, B0); PG8_MMA(1, 1, At, B1); PG8_BAR; PG8_SCHED;
;     ...
;             PG8_WAIT_V(8); PG8_WAIT_L(0); PG8_BAR; PG8_MMA(1, 0, At, B0); PG8_MMA(1, 1, At, B1); PG8_BAR; PG8_SCHED;
	v_mfma_f32_16x16x32_bf16 v[126:129], v[130:133], v[178:181], v[126:129]
	v_mfma_f32_16x16x32_bf16 v[122:125], v[148:151], v[178:181], v[122:125]
	v_mfma_f32_16x16x32_bf16 v[110:113], v[130:133], v[186:189], v[110:113]
	v_mfma_f32_16x16x32_bf16 v[106:109], v[148:151], v[186:189], v[106:109]
	v_mfma_f32_16x16x32_bf16 v[94:97], v[130:133], v[194:197], v[94:97]
	v_mfma_f32_16x16x32_bf16 v[90:93], v[148:151], v[194:197], v[90:93]
	v_mfma_f32_16x16x32_bf16 v[78:81], v[130:133], v[202:205], v[78:81]
	v_mfma_f32_16x16x32_bf16 v[74:77], v[148:151], v[202:205], v[74:77]
	v_mfma_f32_16x16x32_bf16 v[126:129], v[134:137], v[182:185], v[126:129]
	v_mfma_f32_16x16x32_bf16 v[122:125], v[152:155], v[182:185], v[122:125]
	v_mfma_f32_16x16x32_bf16 v[110:113], v[134:137], v[190:193], v[110:113]
	v_mfma_f32_16x16x32_bf16 v[106:109], v[152:155], v[190:193], v[106:109]
	v_mfma_f32_16x16x32_bf16 v[94:97], v[134:137], v[198:201], v[94:97]
	v_mfma_f32_16x16x32_bf16 v[90:93], v[152:155], v[198:201], v[90:93]
	v_mfma_f32_16x16x32_bf16 v[78:81], v[134:137], v[206:209], v[78:81]
	v_mfma_f32_16x16x32_bf16 v[74:77], v[152:155], v[206:209], v[74:77]
	v_mfma_f32_16x16x32_bf16 v[118:121], v[162:165], v[178:181], v[118:121]
	v_mfma_f32_16x16x32_bf16 v[114:117], v[170:173], v[178:181], v[114:117]
	v_mfma_f32_16x16x32_bf16 v[102:105], v[162:165], v[186:189], v[102:105]
	v_mfma_f32_16x16x32_bf16 v[98:101], v[170:173], v[186:189], v[98:101]
	v_mfma_f32_16x16x32_bf16 v[86:89], v[162:165], v[194:197], v[86:89]
	v_mfma_f32_16x16x32_bf16 v[82:85], v[170:173], v[194:197], v[82:85]
	v_mfma_f32_16x16x32_bf16 v[70:73], v[162:165], v[202:205], v[70:73]
	v_mfma_f32_16x16x32_bf16 v[66:69], v[170:173], v[202:205], v[66:69]
	v_mfma_f32_16x16x32_bf16 v[118:121], v[166:169], v[182:185], v[118:121]
	v_mfma_f32_16x16x32_bf16 v[114:117], v[174:177], v[182:185], v[114:117]
	v_mfma_f32_16x16x32_bf16 v[102:105], v[166:169], v[190:193], v[102:105]
	v_mfma_f32_16x16x32_bf16 v[98:101], v[174:177], v[190:193], v[98:101]
	v_mfma_f32_16x16x32_bf16 v[86:89], v[166:169], v[198:201], v[86:89]
	v_mfma_f32_16x16x32_bf16 v[82:85], v[174:177], v[198:201], v[82:85]
	v_mfma_f32_16x16x32_bf16 v[70:73], v[166:169], v[206:209], v[70:73]
	v_mfma_f32_16x16x32_bf16 v[66:69], v[174:177], v[206:209], v[66:69]
	s_barrier
	s_setprio 0
	s_add_i32 s6, s91, s12
	v_lshl_add_u64 v[210:211], s[16:17], 0, v[16:17]
	s_mov_b32 m0, s6
	ds_read_b128 v[178:181], v161 offset:16384
	ds_read_b128 v[182:185], v161 offset:17408
	ds_read_b128 v[186:189], v161 offset:18432
	ds_read_b128 v[190:193], v161 offset:19456
	ds_read_b128 v[194:197], v161 offset:20480
	ds_read_b128 v[198:201], v161 offset:21504
	ds_read_b128 v[202:205], v161 offset:22528
	ds_read_b128 v[206:209], v161 offset:23552
	global_load_lds_dwordx4 v[210:211], off
	s_add_i32 m0, s6, 0x2000
	s_add_u32 s6, s16, 0x100000
	v_lshl_add_u64 v[212:213], s[16:17], 0, v[138:139]
	s_addc_u32 s7, s17, 0
	s_add_i32 s91, s94, s12
	global_load_lds_dwordx4 v[212:213], off
	v_lshl_add_u64 v[214:215], s[6:7], 0, v[16:17]
	s_mov_b32 m0, s91
	v_lshl_add_u64 v[216:217], s[40:41], 0, v[140:141]
	global_load_lds_dwordx4 v[214:215], off
	v_lshl_add_u64 v[214:215], s[6:7], 0, v[138:139]
	s_add_i32 m0, s91, 0x2000
	s_nop 0
	global_load_lds_dwordx4 v[214:215], off
	v_lshl_add_u64 v[214:215], s[40:41], 0, v[142:143]
	s_mov_b32 m0, s13
	s_nop 0
	global_load_lds_dwordx4 v[214:215], off
	s_mov_b32 m0, s42
	s_nop 0
	global_load_lds_dwordx4 v[216:217], off
	s_waitcnt vmcnt(8)
	s_waitcnt lgkmcnt(0)
	s_nop 0
	s_nop 0
	s_setprio 1
	s_barrier
	v_mfma_f32_16x16x32_bf16 v[62:65], v[130:133], v[178:181], v[62:65]
	v_mfma_f32_16x16x32_bf16 v[58:61], v[148:151], v[178:181], v[58:61]
	v_mfma_f32_16x16x32_bf16 v[46:49], v[130:133], v[186:189], v[46:49]
	v_mfma_f32_16x16x32_bf16 v[42:45], v[148:151], v[186:189], v[42:45]
	v_mfma_f32_16x16x32_bf16 v[30:33], v[130:133], v[194:197], v[30:33]
	v_mfma_f32_16x16x32_bf16 v[26:29], v[148:151], v[194:197], v[26:29]
	v_mfma_f32_16x16x32_bf16 v[12:15], v[130:133], v[202:205], v[12:15]
	v_mfma_f32_16x16x32_bf16 v[8:11], v[148:151], v[202:205], v[8:11]
	v_mfma_f32_16x16x32_bf16 v[62:65], v[134:137], v[182:185], v[62:65]
	v_mfma_f32_16x16x32_bf16 v[58:61], v[152:155], v[182:185], v[58:61]
	v_mfma_f32_16x16x32_bf16 v[46:49], v[134:137], v[190:193], v[46:49]
	v_mfma_f32_16x16x32_bf16 v[42:45], v[152:155], v[190:193], v[42:45]
	v_mfma_f32_16x16x32_bf16 v[30:33], v[134:137], v[198:201], v[30:33]
	v_mfma_f32_16x16x32_bf16 v[26:29], v[152:155], v[198:201], v[26:29]
	v_mfma_f32_16x16x32_bf16 v[12:15], v[134:137], v[206:209], v[12:15]
	v_mfma_f32_16x16x32_bf16 v[8:11], v[152:155], v[206:209], v[8:11]
	v_mfma_f32_16x16x32_bf16 v[54:57], v[162:165], v[178:181], v[54:57]
	v_mfma_f32_16x16x32_bf16 v[50:53], v[170:173], v[178:181], v[50:53]
	v_mfma_f32_16x16x32_bf16 v[38:41], v[162:165], v[186:189], v[38:41]
	v_mfma_f32_16x16x32_bf16 v[34:37], v[170:173], v[186:189], v[34:37]
	v_mfma_f32_16x16x32_bf16 v[22:25], v[162:165], v[194:197], v[22:25]
	v_mfma_f32_16x16x32_bf16 v[18:21], v[170:173], v[194:197], v[18:21]
	v_mfma_f32_16x16x32_bf16 v[4:7], v[162:165], v[202:205], v[4:7]
	v_mfma_f32_16x16x32_bf16 v[0:3], v[170:173], v[202:205], v[0:3]
	v_mfma_f32_16x16x32_bf16 v[54:57], v[166:169], v[182:185], v[54:57]
	v_mfma_f32_16x16x32_bf16 v[50:53], v[174:177], v[182:185], v[50:53]
	v_mfma_f32_16x16x32_bf16 v[38:41], v[166:169], v[190:193], v[38:41]
	v_mfma_f32_16x16x32_bf16 v[34:37], v[174:177], v[190:193], v[34:37]
	v_mfma_f32_16x16x32_bf16 v[22:25], v[166:169], v[198:201], v[22:25]
	v_mfma_f32_16x16x32_bf16 v[18:21], v[174:177], v[198:201], v[18:21]
	v_mfma_f32_16x16x32_bf16 v[4:7], v[166:169], v[206:209], v[4:7]
	v_mfma_f32_16x16x32_bf16 v[0:3], v[174:177], v[206:209], v[0:3]
	s_barrier
; #define PG8_STAGEA(bufoff, gbase, voff) PG8_STAGE_X(bufoff, gbase, voff, AUXA)
; #define PG8_LDA(dst, b, h) do { _Pragma("unroll") for (int m = 0; m < 4; ++m) _Pragma("unroll") for (int k = 0; k < 2; ++k) dst[m][k] = *(const PG8_LAS bf16x8*)(lds + PG8_SA(b, h) + aoff + m * 2048 + k * 1024); } while (0)
; #define PG8_LDB(dst, b, h) do { _Pragma("unroll") for (int n = 0; n < 2; ++n) _Pragma("unroll") for (int k = 0; k < 2; ++k) dst[n][k] = *(const PG8_LAS bf16x8*)(lds + PG8_SB(b, h) + boff + n * 2048 + k * 1024); } while (0)
; #define PG8_MMA(ai, bj, At, Bt) do { if (GEMM_PRIO_MODE == 0) __builtin_amdgcn_s_setprio(1); PG8_MMA_LOOPS \
;         acc[ai][bj][m][n] = __builtin_amdgcn_mfma_f32_16x16x32_bf16(Bt[n][k], At[m][k], acc[ai][bj][m][n], 0, 0, 0); if (GEMM_PRIO_MODE == 0) __builtin_amdgcn_s_setprio(0); } while (0)
; #define PG8_WAIT_V(n) asm volatile("s_waitcnt vmcnt(" #n ")" ::: "memory")
; #define PG8_WAIT_L(n) asm volatile("s_waitcnt lgkmcnt(" #n ")" ::: "memory")
; #define PG8_BAR __builtin_amdgcn_s_barrier()
; #define PG8_SCHED __builtin_amdgcn_sched_barrier(0)
;     ...
;             PG8_LDB(B0, 1, 0); PG8_LDB(B1, 1, 1); PG8_SCHED; PG8_LDA(At, 1, 0); PG8_STAGEA(PG8_SA(0, 1), a2 + hstepA, voffA);
;             PG8_WAIT_V(8); PG8_WAIT_L(0); PG8_BAR; PG8_MMA(0, 0, At, B0); PG8_MMA(0, 1, At, B1); PG8_BAR; PG8_SCHED;
	s_setprio 0
	s_add_i32 s91, 0, 0x18000
	s_add_i32 s94, 0, 0x1c000
	v_add_u32_e32 v152, s91, v157
	v_add_u32_e32 v174, s94, v157
	ds_read_b128 v[130:133], v152
	ds_read_b128 v[134:137], v152 offset:1024
	ds_read_b128 v[148:151], v152 offset:2048
	ds_read_b128 v[152:155], v152 offset:3072
	ds_read_b128 v[162:165], v174
	ds_read_b128 v[166:169], v174 offset:1024
	ds_read_b128 v[170:173], v174 offset:2048
	ds_read_b128 v[174:177], v174 offset:3072
	s_add_u32 s6, s40, 0x100000
	s_addc_u32 s7, s41, 0
	s_mov_b32 m0, s43
	v_lshl_add_u64 v[218:219], s[6:7], 0, v[142:143]
	ds_read_b128 v[178:181], v161 offset:32768
	ds_read_b128 v[182:185], v161 offset:33792
	ds_read_b128 v[186:189], v161 offset:34816
	ds_read_b128 v[190:193], v161 offset:35840
	ds_read_b128 v[194:197], v161 offset:36864
	ds_read_b128 v[198:201], v161 offset:37888
	ds_read_b128 v[202:205], v161 offset:38912
	ds_read_b128 v[206:209], v161 offset:39936
	global_load_lds_dwordx4 v[218:219], off
	v_lshl_add_u64 v[218:219], s[6:7], 0, v[140:141]
	s_mov_b32 m0, s50
	s_nop 0
	global_load_lds_dwordx4 v[218:219], off
	s_waitcnt vmcnt(8)
	s_waitcnt lgkmcnt(0)
	s_nop 0
	s_nop 0
	s_nop 0
	s_nop 0
	s_nop 0
	s_nop 0
	s_setprio 1
	s_barrier
	v_mfma_f32_16x16x32_bf16 v[126:129], v[130:133], v[178:181], v[126:129]
	v_mfma_f32_16x16x32_bf16 v[122:125], v[148:151], v[178:181], v[122:125]
	v_mfma_f32_16x16x32_bf16 v[110:113], v[130:133], v[186:189], v[110:113]
	v_mfma_f32_16x16x32_bf16 v[106:109], v[148:151], v[186:189], v[106:109]
	v_mfma_f32_16x16x32_bf16 v[94:97], v[130:133], v[194:197], v[94:97]
	v_mfma_f32_16x16x32_bf16 v[90:93], v[148:151], v[194:197], v[90:93]
	v_mfma_f32_16x16x32_bf16 v[78:81], v[130:133], v[202:205], v[78:81]
	v_mfma_f32_16x16x32_bf16 v[74:77], v[148:151], v[202:205], v[74:77]
	v_mfma_f32_16x16x32_bf16 v[126:129], v[134:137], v[182:185], v[126:129]
	v_mfma_f32_16x16x32_bf16 v[122:125], v[152:155], v[182:185], v[122:125]
	v_mfma_f32_16x16x32_bf16 v[110:113], v[134:137], v[190:193], v[110:113]
	v_mfma_f32_16x16x32_bf16 v[106:109], v[152:155], v[190:193], v[106:109]
	v_mfma_f32_16x16x32_bf16 v[94:97], v[134:137], v[198:201], v[94:97]
	v_mfma_f32_16x16x32_bf16 v[90:93], v[152:155], v[198:201], v[90:93]
	v_mfma_f32_16x16x32_bf16 v[78:81], v[134:137], v[206:209], v[78:81]
	v_mfma_f32_16x16x32_bf16 v[74:77], v[152:155], v[206:209], v[74:77]
	v_mfma_f32_16x16x32_bf16 v[118:121], v[162:165], v[178:181], v[118:121]
	v_mfma_f32_16x16x32_bf16 v[114:117], v[170:173], v[178:181], v[114:117]
	v_mfma_f32_16x16x32_bf16 v[102:105], v[162:165], v[186:189], v[102:105]
	v_mfma_f32_16x16x32_bf16 v[98:101], v[170:173], v[186:189], v[98:101]
	v_mfma_f32_16x16x32_bf16 v[86:89], v[162:165], v[194:197], v[86:89]
	v_mfma_f32_16x16x32_bf16 v[82:85], v[170:173], v[194:197], v[82:85]
	v_mfma_f32_16x16x32_bf16 v[70:73], v[162:165], v[202:205], v[70:73]
	v_mfma_f32_16x16x32_bf16 v[66:69], v[170:173], v[202:205], v[66:69]
	v_mfma_f32_16x16x32_bf16 v[118:121], v[166:169], v[182:185], v[118:121]
	v_mfma_f32_16x16x32_bf16 v[114:117], v[174:177], v[182:185], v[114:117]
	v_mfma_f32_16x16x32_bf16 v[102:105], v[166:169], v[190:193], v[102:105]
	v_mfma_f32_16x16x32_bf16 v[98:101], v[174:177], v[190:193], v[98:101]
	v_mfma_f32_16x16x32_bf16 v[86:89], v[166:169], v[198:201], v[86:89]
	v_mfma_f32_16x16x32_bf16 v[82:85], v[174:177], v[198:201], v[82:85]
	v_mfma_f32_16x16x32_bf16 v[70:73], v[166:169], v[206:209], v[70:73]
	v_mfma_f32_16x16x32_bf16 v[66:69], v[174:177], v[206:209], v[66:69]
	s_barrier
; #define PG8_STAGEA(bufoff, gbase, voff) PG8_STAGE_X(bufoff, gbase, voff, AUXA)
; #define PG8_STAGEB(bufoff, gbase, voff) PG8_STAGE_X(bufoff, gbase, voff, AUXB)
; #define PG8_LDA(dst, b, h) do { _Pragma("unroll") for (int m = 0; m < 4; ++m) _Pragma("unroll") for (int k = 0; k < 2; ++k) dst[m][k] = *(const PG8_LAS bf16x8*)(lds + PG8_SA(b, h) + aoff + m * 2048 + k * 1024); } while (0)
; #define PG8_MMA(ai, bj, At, Bt) do { if (GEMM_PRIO_MODE == 0) __builtin_amdgcn_s_setprio(1); PG8_MMA_LOOPS \
;         acc[ai][bj][m][n] = __builtin_amdgcn_mfma_f32_16x16x32_bf16(Bt[n][k], At[m][k], acc[ai][bj][m][n], 0, 0, 0); if (GEMM_PRIO_MODE == 0) __builtin_amdgcn_s_setprio(0); } while (0)
; #define PG8_WAIT_V(n) asm volatile("s_waitcnt vmcnt(" #n ")" ::: "memory")
; #define PG8_WAIT_L(n) asm volatile("s_waitcnt lgkmcnt(" #n ")" ::: "memory")
; #define PG8_BAR __builtin_amdgcn_s_barrier()
; #define PG8_SCHED __builtin_amdgcn_sched_barrier(0)
;     ...
;             PG8_LDA(At, 1, 1); PG8_STAGEB(PG8_SB(1, 0), b3, voffB); PG8_STAGEB(PG8_SB(1, 1), b3 + hstepB, voffB); PG8_STAGEA(PG8_SA(1, 0), a3, voffA);
;             PG8_WAIT_V(8); PG8_WAIT_L(0); PG8_BAR; PG8_MMA(1, 0, At, B0); PG8_MMA(1, 1, At, B1); PG8_BAR; PG8_SCHED;
;     ...
;         if constexpr (ALIGN_EPI) { if (wr == 0) PG8_BAR; }
	s_setprio 0
	s_add_i32 s6, s91, s12
	v_lshl_add_u64 v[210:211], v[210:211], 0, s[86:87]
	s_mov_b32 m0, s6
	ds_read_b128 v[178:181], v161 offset:49152
	ds_read_b128 v[182:185], v161 offset:50176
	ds_read_b128 v[186:189], v161 offset:51200
	ds_read_b128 v[190:193], v161 offset:52224
	ds_read_b128 v[194:197], v161 offset:53248
	ds_read_b128 v[198:201], v161 offset:54272
	ds_read_b128 v[202:205], v161 offset:55296
	ds_read_b128 v[206:209], v161 offset:56320
	global_load_lds_dwordx4 v[210:211], off
	s_add_i32 m0, s6, 0x2000
	s_add_u32 s6, s16, 0x100080
	v_lshl_add_u64 v[210:211], v[212:213], 0, s[86:87]
	s_addc_u32 s7, s17, 0
	s_add_i32 s16, s94, s12
	global_load_lds_dwordx4 v[210:211], off
	v_lshl_add_u64 v[210:211], s[6:7], 0, v[16:17]
	s_mov_b32 m0, s16
	s_nop 0
	global_load_lds_dwordx4 v[210:211], off
	v_lshl_add_u64 v[210:211], s[6:7], 0, v[138:139]
	s_add_i32 m0, s16, 0x2000
	s_nop 0
	global_load_lds_dwordx4 v[210:211], off
	v_lshl_add_u64 v[210:211], v[214:215], 0, s[86:87]
	s_mov_b32 m0, s68
	s_nop 0
	global_load_lds_dwordx4 v[210:211], off
	v_lshl_add_u64 v[210:211], v[216:217], 0, s[86:87]
	s_mov_b32 m0, s69
	s_nop 0
	global_load_lds_dwordx4 v[210:211], off
	s_waitcnt vmcnt(8)
	s_waitcnt lgkmcnt(0)
	s_nop 0
	s_setprio 1
	s_barrier
	v_mfma_f32_16x16x32_bf16 v[62:65], v[130:133], v[178:181], v[62:65]
	v_mfma_f32_16x16x32_bf16 v[58:61], v[148:151], v[178:181], v[58:61]
	v_mfma_f32_16x16x32_bf16 v[46:49], v[130:133], v[186:189], v[46:49]
	v_mfma_f32_16x16x32_bf16 v[42:45], v[148:151], v[186:189], v[42:45]
	v_mfma_f32_16x16x32_bf16 v[30:33], v[130:133], v[194:197], v[30:33]
	v_mfma_f32_16x16x32_bf16 v[26:29], v[148:151], v[194:197], v[26:29]
	v_mfma_f32_16x16x32_bf16 v[12:15], v[130:133], v[202:205], v[12:15]
	v_mfma_f32_16x16x32_bf16 v[8:11], v[148:151], v[202:205], v[8:11]
	v_mfma_f32_16x16x32_bf16 v[62:65], v[134:137], v[182:185], v[62:65]
	v_mfma_f32_16x16x32_bf16 v[58:61], v[152:155], v[182:185], v[58:61]
	v_mfma_f32_16x16x32_bf16 v[46:49], v[134:137], v[190:193], v[46:49]
	v_mfma_f32_16x16x32_bf16 v[42:45], v[152:155], v[190:193], v[42:45]
	v_mfma_f32_16x16x32_bf16 v[30:33], v[134:137], v[198:201], v[30:33]
	v_mfma_f32_16x16x32_bf16 v[26:29], v[152:155], v[198:201], v[26:29]
	v_mfma_f32_16x16x32_bf16 v[12:15], v[134:137], v[206:209], v[12:15]
	v_mfma_f32_16x16x32_bf16 v[8:11], v[152:155], v[206:209], v[8:11]
	v_mfma_f32_16x16x32_bf16 v[54:57], v[162:165], v[178:181], v[54:57]
	v_mfma_f32_16x16x32_bf16 v[50:53], v[170:173], v[178:181], v[50:53]
	v_mfma_f32_16x16x32_bf16 v[38:41], v[162:165], v[186:189], v[38:41]
	v_mfma_f32_16x16x32_bf16 v[34:37], v[170:173], v[186:189], v[34:37]
	v_mfma_f32_16x16x32_bf16 v[22:25], v[162:165], v[194:197], v[22:25]
	v_mfma_f32_16x16x32_bf16 v[18:21], v[170:173], v[194:197], v[18:21]
	v_mfma_f32_16x16x32_bf16 v[4:7], v[162:165], v[202:205], v[4:7]
	v_mfma_f32_16x16x32_bf16 v[0:3], v[170:173], v[202:205], v[0:3]
	v_mfma_f32_16x16x32_bf16 v[54:57], v[166:169], v[182:185], v[54:57]
	v_mfma_f32_16x16x32_bf16 v[50:53], v[174:177], v[182:185], v[50:53]
	v_mfma_f32_16x16x32_bf16 v[38:41], v[166:169], v[190:193], v[38:41]
	v_mfma_f32_16x16x32_bf16 v[34:37], v[174:177], v[190:193], v[34:37]
	v_mfma_f32_16x16x32_bf16 v[22:25], v[166:169], v[198:201], v[22:25]
	v_mfma_f32_16x16x32_bf16 v[18:21], v[174:177], v[198:201], v[18:21]
	v_mfma_f32_16x16x32_bf16 v[4:7], v[166:169], v[206:209], v[4:7]
	v_mfma_f32_16x16x32_bf16 v[0:3], v[174:177], v[206:209], v[0:3]
	s_barrier
	s_setprio 0
	s_add_i32 s90, s90, 2
	s_add_u32 s38, s38, 0x100
	s_addc_u32 s39, s39, 0
	s_add_u32 s0, s0, 0x100
	s_addc_u32 s1, s1, 0
	s_cmp_gt_u32 s90, 61
	s_cbranch_scc0 .LBB0_558
	s_and_b64 vcc, exec, s[18:19]
	s_cbranch_vccz .LBB0_561
	s_barrier

; #define PG8_STAGEA(bufoff, gbase, voff) PG8_STAGE_X(bufoff, gbase, voff, AUXA)
; #define PG8_STR(x) PG8_STR2(x)
;     ...
;         const bool has_next = S.next(ui + 1, nxt);
;         const char* nA = has_next ? (const char*)g.A + (size_t)nxt.pm * tstepA : cA; const char* nB = has_next ? (const char*)g.Bt + (size_t)nxt.pn * tstepB : cB;
;         int t0 = 0;
;         if constexpr (SP2 && GEMM_RELAX == 1) { if (ui > 0) {
;             const char* a1 = cA + kstepA; const char* a2 = cA + 2 * kstepA; const char* b2 = cB + 2 * kstepB; const char* a3 = a2 + kstepA; const char* b3 = b2 + kstepB;
;             PG8_LDB(B0, 0, 0); PG8_LDB(B1, 0, 1); PG8_SCHED; PG8_LDA(At, 0, 0); PG8_STAGEA(PG8_SA(1, 1), a1 + hstepA, voffA);
;             PG8_WAIT_V(24); PG8_WAIT_L(0); PG8_BAR; PG8_MMA(0, 0, At, B0); PG8_MMA(0, 1, At, B1); PG8_BAR; PG8_SCHED;
;             PG8_LDA(At, 0, 1); PG8_STAGEB(PG8_SB(0, 0), b2, voffB); PG8_STAGEB(PG8_SB(0, 1), b2 + hstepB, voffB); PG8_STAGEA(PG8_SA(0, 0), a2, voffA);
;             PG8_WAIT_V(24); PG8_WAIT_L(0); PG8_BAR; PG8_MMA(1, 0, At, B0); PG8_MMA(1, 1, At, B1); PG8_BAR; PG8_SCHED;
;             PG8_LDB(B0, 1, 0); PG8_LDB(B1, 1, 1); PG8_SCHED; PG8_LDA(At, 1, 0); PG8_STAGEA(PG8_SA(0, 1), a2 + hstepA, voffA);
;             PG8_WAIT_V(8); PG8_WAIT_L(0); PG8_BAR; PG8_MMA(0, 0, At, B0); PG8_MMA(0, 1, At, B1); PG8_BAR; PG8_SCHED;
;             PG8_LDA(At, 1, 1); PG8_STAGEB(PG8_SB(1, 0), b3, voffB); PG8_STAGEB(PG8_SB(1, 1), b3 + hstepB, voffB); PG8_STAGEA(PG8_SA(1, 0), a3, voffA);
;             PG8_WAIT_V(8); PG8_WAIT_L(0); PG8_BAR; PG8_MMA(1, 0, At, B0); PG8_MMA(1, 1, At, B1); PG8_BAR; PG8_SCHED;
;             t0 = 2; } }
;     ...
;         asm volatile(".p2align " PG8_STR(GEMM_LOOP_ALIGN) ::: "memory");
;     ...
;         for (int t = t0; t < nt; t += 2) {
;             const bool last = (t == nt - 2);
;             const char* a1 = cA + (size_t)(t + 1) * kstepA;
;             const char* a2 = last ? nA : cA + (size_t)(t + 2) * kstepA; const char* b2 = last ? nB : cB + (size_t)(t + 2) * kstepB;
;             const char* a3 = a2 + kstepA; const char* b3 = b2 + kstepB;
;             if (last && has_next) S.a_ready(nxt);
;             if constexpr (SP2) {
;             PG8_LDB(B0, 0, 0); PG8_LDB(B1, 0, 1); PG8_SCHED; PG8_LDA(At, 0, 0); PG8_STAGEA(PG8_SA(1, 1), a1 + hstepA, voffA);
;     ...
;             const int relax = __builtin_amdgcn_readfirstlane((t == 0 && ui > 0) ? 1 : 0);
.LBB0_711:
	s_ashr_i32 s25, s24, 31
	s_lshl_b64 s[0:1], s[24:25], 21
	s_add_u32 s26, s56, s0
	s_addc_u32 s27, s57, s1
	s_and_b64 s[0:1], s[10:11], exec
	s_cselect_b32 s0, s27, s13
	s_cselect_b32 s1, s26, s12
	s_ashr_i32 s23, s22, 31
	s_lshl_b64 s[6:7], s[22:23], 21
	s_add_u32 s36, s51, s6
	s_addc_u32 s37, s68, s7
	s_and_b64 s[6:7], s[10:11], exec
	s_cselect_b32 s23, s37, s43
	s_cselect_b32 s25, s36, s42
	s_add_u32 s40, s12, 0x100080
	s_addc_u32 s41, s13, 0
	s_add_u32 s12, s42, 0x100
	s_addc_u32 s13, s43, 0
	s_mov_b32 s39, -2
	s_add_u32 s6, s40, 0xfff00080
	s_addc_u32 s7, s41, -1
	s_add_i32 s95, 0, 0x10000
	s_cmp_eq_u32 s39, 60
	s_cselect_b32 s43, s0, s7
	s_cselect_b32 s42, s1, s6
	v_add_u32_e32 v144, s95, v146
	s_cselect_b32 s17, s23, s13
	s_cselect_b32 s16, s25, s12
	s_add_i32 vcc_lo, 0, 0x14000
	ds_read_b128 v[150:153], v144
	ds_read_b128 v[154:157], v144 offset:1024
	ds_read_b128 v[158:161], v144 offset:2048
	ds_read_b128 v[162:165], v144 offset:3072
	v_add_u32_e32 v144, vcc_lo, v146
	ds_read_b128 v[166:169], v144
	ds_read_b128 v[170:173], v144 offset:1024
	ds_read_b128 v[174:177], v144 offset:2048
	ds_read_b128 v[178:181], v144 offset:3072
	v_lshl_add_u64 v[144:145], s[40:41], 0, v[140:141]
	s_add_i32 m0, s69, 0xc000
	ds_read_b128 v[182:185], v148
	ds_read_b128 v[186:189], v148 offset:1024
	ds_read_b128 v[190:193], v148 offset:2048
	ds_read_b128 v[194:197], v148 offset:3072
	ds_read_b128 v[198:201], v148 offset:4096
	ds_read_b128 v[202:205], v148 offset:5120
	ds_read_b128 v[206:209], v148 offset:6144
	ds_read_b128 v[210:213], v148 offset:7168
	global_load_lds_dwordx4 v[144:145], off
	v_lshl_add_u64 v[144:145], s[40:41], 0, v[142:143]
	s_add_i32 m0, s69, 0xe000
	s_nop 0
	global_load_lds_dwordx4 v[144:145], off
	s_waitcnt vmcnt(8)
	s_waitcnt lgkmcnt(0)
	s_nop 0
	s_nop 0
	s_nop 0
	s_nop 0
	s_nop 0
	s_setprio 1
	s_barrier
	v_mfma_f32_16x16x32_bf16 v[126:129], v[150:153], v[182:185], 0
	v_mfma_f32_16x16x32_bf16 v[122:125], v[158:161], v[182:185], 0
	v_mfma_f32_16x16x32_bf16 v[110:113], v[150:153], v[190:193], 0
	v_mfma_f32_16x16x32_bf16 v[106:109], v[158:161], v[190:193], 0
	v_mfma_f32_16x16x32_bf16 v[94:97], v[150:153], v[198:201], 0
	v_mfma_f32_16x16x32_bf16 v[90:93], v[158:161], v[198:201], 0
	v_mfma_f32_16x16x32_bf16 v[78:81], v[150:153], v[206:209], 0
	v_mfma_f32_16x16x32_bf16 v[74:77], v[158:161], v[206:209], 0
	v_mfma_f32_16x16x32_bf16 v[126:129], v[154:157], v[186:189], v[126:129]
	v_mfma_f32_16x16x32_bf16 v[122:125], v[162:165], v[186:189], v[122:125]
	v_mfma_f32_16x16x32_bf16 v[110:113], v[154:157], v[194:197], v[110:113]
	v_mfma_f32_16x16x32_bf16 v[106:109], v[162:165], v[194:197], v[106:109]
	v_mfma_f32_16x16x32_bf16 v[94:97], v[154:157], v[202:205], v[94:97]
	v_mfma_f32_16x16x32_bf16 v[90:93], v[162:165], v[202:205], v[90:93]
	v_mfma_f32_16x16x32_bf16 v[78:81], v[154:157], v[210:213], v[78:81]
	v_mfma_f32_16x16x32_bf16 v[74:77], v[162:165], v[210:213], v[74:77]
	v_mfma_f32_16x16x32_bf16 v[118:121], v[166:169], v[182:185], 0
	v_mfma_f32_16x16x32_bf16 v[114:117], v[174:177], v[182:185], 0
	v_mfma_f32_16x16x32_bf16 v[102:105], v[166:169], v[190:193], 0
	v_mfma_f32_16x16x32_bf16 v[98:101], v[174:177], v[190:193], 0
	v_mfma_f32_16x16x32_bf16 v[86:89], v[166:169], v[198:201], 0
	v_mfma_f32_16x16x32_bf16 v[82:85], v[174:177], v[198:201], 0
	v_mfma_f32_16x16x32_bf16 v[70:73], v[166:169], v[206:209], 0
	v_mfma_f32_16x16x32_bf16 v[66:69], v[174:177], v[206:209], 0
	v_mfma_f32_16x16x32_bf16 v[118:121], v[170:173], v[186:189], v[118:121]
	v_mfma_f32_16x16x32_bf16 v[114:117], v[178:181], v[186:189], v[114:117]
	v_mfma_f32_16x16x32_bf16 v[102:105], v[170:173], v[194:197], v[102:105]
	v_mfma_f32_16x16x32_bf16 v[98:101], v[178:181], v[194:197], v[98:101]
	v_mfma_f32_16x16x32_bf16 v[86:89], v[170:173], v[202:205], v[86:89]
	v_mfma_f32_16x16x32_bf16 v[82:85], v[178:181], v[202:205], v[82:85]
	v_mfma_f32_16x16x32_bf16 v[70:73], v[170:173], v[210:213], v[70:73]
	v_mfma_f32_16x16x32_bf16 v[66:69], v[178:181], v[210:213], v[66:69]
	s_barrier
	s_setprio 0
	s_add_i32 s6, s95, s50
	v_lshl_add_u64 v[144:145], s[16:17], 0, v[134:135]
	s_mov_b32 m0, s6
	ds_read_b128 v[182:185], v148 offset:16384
	ds_read_b128 v[186:189], v148 offset:17408
	ds_read_b128 v[190:193], v148 offset:18432
	ds_read_b128 v[194:197], v148 offset:19456
	ds_read_b128 v[198:201], v148 offset:20480
	ds_read_b128 v[202:205], v148 offset:21504
	ds_read_b128 v[206:209], v148 offset:22528
	ds_read_b128 v[210:213], v148 offset:23552
	global_load_lds_dwordx4 v[144:145], off
	s_add_i32 m0, s6, 0x2000
	s_add_u32 s6, s16, 0x100000
	v_lshl_add_u64 v[214:215], s[16:17], 0, v[130:131]
	s_addc_u32 s7, s17, 0
	s_add_i32 s95, vcc_lo, s50
	global_load_lds_dwordx4 v[214:215], off
	v_lshl_add_u64 v[216:217], s[6:7], 0, v[134:135]
	s_mov_b32 m0, s95
	v_lshl_add_u64 v[218:219], s[42:43], 0, v[132:133]
	global_load_lds_dwordx4 v[216:217], off
	v_lshl_add_u64 v[216:217], s[6:7], 0, v[130:131]
	s_add_i32 m0, s95, 0x2000
	s_nop 0
	global_load_lds_dwordx4 v[216:217], off
	v_lshl_add_u64 v[216:217], s[42:43], 0, v[136:137]
	s_mov_b32 m0, s69
	s_nop 0
	global_load_lds_dwordx4 v[216:217], off
	s_mov_b32 m0, s72
	s_nop 0
	global_load_lds_dwordx4 v[218:219], off
	s_waitcnt vmcnt(8)
	s_waitcnt lgkmcnt(0)
	s_nop 0
	s_nop 0
	s_setprio 1
	s_barrier
; #define PG8_STAGEA(bufoff, gbase, voff) PG8_STAGE_X(bufoff, gbase, voff, AUXA)
; #define PG8_LDA(dst, b, h) do { _Pragma("unroll") for (int m = 0; m < 4; ++m) _Pragma("unroll") for (int k = 0; k < 2; ++k) dst[m][k] = *(const PG8_LAS bf16x8*)(lds + PG8_SA(b, h) + aoff + m * 2048 + k * 1024); } while (0)
; #define PG8_LDB(dst, b, h) do { _Pragma("unroll") for (int n = 0; n < 2; ++n) _Pragma("unroll") for (int k = 0; k < 2; ++k) dst[n][k] = *(const PG8_LAS bf16x8*)(lds + PG8_SB(b, h) + boff + n * 2048 + k * 1024); } while (0)
; #define PG8_MMA(ai, bj, At, Bt) do { if (GEMM_PRIO_MODE == 0) __builtin_amdgcn_s_setprio(1); PG8_MMA_LOOPS \
;         acc[ai][bj][m][n] = __builtin_amdgcn_mfma_f32_16x16x32_bf16(Bt[n][k], At[m][k], acc[ai][bj][m][n], 0, 0, 0); if (GEMM_PRIO_MODE == 0) __builtin_amdgcn_s_setprio(0); } while (0)
; #define PG8_WAIT_V(n) asm volatile("s_waitcnt vmcnt(" #n ")" ::: "memory")
; #define PG8_WAIT_L(n) asm volatile("s_waitcnt lgkmcnt(" #n ")" ::: "memory")
; #define PG8_BAR __builtin_amdgcn_s_barrier()
; #define PG8_SCHED __builtin_amdgcn_sched_barrier(0)
;     ...
;             PG8_WAIT_V(8); PG8_WAIT_L(0); PG8_BAR; PG8_MMA(1, 0, At, B0); PG8_MMA(1, 1, At, B1); PG8_BAR; PG8_SCHED;
;     ...
;             PG8_LDB(B0, 1, 0); PG8_LDB(B1, 1, 1); PG8_SCHED; PG8_LDA(At, 1, 0); PG8_STAGEA(PG8_SA(0, 1), a2 + hstepA, voffA);
;             PG8_WAIT_V(8); PG8_WAIT_L(0); PG8_BAR; PG8_MMA(0, 0, At, B0); PG8_MMA(0, 1, At, B1); PG8_BAR; PG8_SCHED;
	v_mfma_f32_16x16x32_bf16 v[62:65], v[150:153], v[182:185], 0
	v_mfma_f32_16x16x32_bf16 v[58:61], v[158:161], v[182:185], 0
	v_mfma_f32_16x16x32_bf16 v[46:49], v[150:153], v[190:193], 0
	v_mfma_f32_16x16x32_bf16 v[42:45], v[158:161], v[190:193], 0
	v_mfma_f32_16x16x32_bf16 v[30:33], v[150:153], v[198:201], 0
	v_mfma_f32_16x16x32_bf16 v[26:29], v[158:161], v[198:201], 0
	v_mfma_f32_16x16x32_bf16 v[12:15], v[150:153], v[206:209], 0
	v_mfma_f32_16x16x32_bf16 v[8:11], v[158:161], v[206:209], 0
	v_mfma_f32_16x16x32_bf16 v[62:65], v[154:157], v[186:189], v[62:65]
	v_mfma_f32_16x16x32_bf16 v[58:61], v[162:165], v[186:189], v[58:61]
	v_mfma_f32_16x16x32_bf16 v[46:49], v[154:157], v[194:197], v[46:49]
	v_mfma_f32_16x16x32_bf16 v[42:45], v[162:165], v[194:197], v[42:45]
	v_mfma_f32_16x16x32_bf16 v[30:33], v[154:157], v[202:205], v[30:33]
	v_mfma_f32_16x16x32_bf16 v[26:29], v[162:165], v[202:205], v[26:29]
	v_mfma_f32_16x16x32_bf16 v[12:15], v[154:157], v[210:213], v[12:15]
	v_mfma_f32_16x16x32_bf16 v[8:11], v[162:165], v[210:213], v[8:11]
	v_mfma_f32_16x16x32_bf16 v[54:57], v[166:169], v[182:185], 0
	v_mfma_f32_16x16x32_bf16 v[50:53], v[174:177], v[182:185], 0
	v_mfma_f32_16x16x32_bf16 v[38:41], v[166:169], v[190:193], 0
	v_mfma_f32_16x16x32_bf16 v[34:37], v[174:177], v[190:193], 0
	v_mfma_f32_16x16x32_bf16 v[22:25], v[166:169], v[198:201], 0
	v_mfma_f32_16x16x32_bf16 v[18:21], v[174:177], v[198:201], 0
	v_mfma_f32_16x16x32_bf16 v[4:7], v[166:169], v[206:209], 0
	v_mfma_f32_16x16x32_bf16 v[0:3], v[174:177], v[206:209], 0
	v_mfma_f32_16x16x32_bf16 v[54:57], v[170:173], v[186:189], v[54:57]
	v_mfma_f32_16x16x32_bf16 v[50:53], v[178:181], v[186:189], v[50:53]
	v_mfma_f32_16x16x32_bf16 v[38:41], v[170:173], v[194:197], v[38:41]
	v_mfma_f32_16x16x32_bf16 v[34:37], v[178:181], v[194:197], v[34:37]
	v_mfma_f32_16x16x32_bf16 v[22:25], v[170:173], v[202:205], v[22:25]
	v_mfma_f32_16x16x32_bf16 v[18:21], v[178:181], v[202:205], v[18:21]
	v_mfma_f32_16x16x32_bf16 v[4:7], v[170:173], v[210:213], v[4:7]
	v_mfma_f32_16x16x32_bf16 v[0:3], v[178:181], v[210:213], v[0:3]
	s_barrier
	s_setprio 0
	s_add_i32 s95, 0, 0x18000
	v_add_u32_e32 v149, s95, v146
	s_add_i32 vcc_lo, 0, 0x1c000
	ds_read_b128 v[150:153], v149
	ds_read_b128 v[154:157], v149 offset:1024
	ds_read_b128 v[158:161], v149 offset:2048
	ds_read_b128 v[162:165], v149 offset:3072
	v_add_u32_e32 v149, vcc_lo, v146
	ds_read_b128 v[166:169], v149
	ds_read_b128 v[170:173], v149 offset:1024
	ds_read_b128 v[174:177], v149 offset:2048
	ds_read_b128 v[178:181], v149 offset:3072
	s_add_u32 s6, s42, 0x100000
	s_addc_u32 s7, s43, 0
	s_mov_b32 m0, s73
	v_lshl_add_u64 v[220:221], s[6:7], 0, v[136:137]
	ds_read_b128 v[182:185], v148 offset:32768
	ds_read_b128 v[186:189], v148 offset:33792
	ds_read_b128 v[190:193], v148 offset:34816
	ds_read_b128 v[194:197], v148 offset:35840
	ds_read_b128 v[198:201], v148 offset:36864
	ds_read_b128 v[202:205], v148 offset:37888
	ds_read_b128 v[206:209], v148 offset:38912
	ds_read_b128 v[210:213], v148 offset:39936
	global_load_lds_dwordx4 v[220:221], off
	v_lshl_add_u64 v[220:221], s[6:7], 0, v[132:133]
	s_mov_b32 m0, s82
	s_nop 0
	global_load_lds_dwordx4 v[220:221], off
	s_waitcnt vmcnt(8)
	s_waitcnt lgkmcnt(0)
	s_nop 0
	s_nop 0
	s_nop 0
	s_nop 0
	s_nop 0
	s_nop 0
	s_setprio 1
	s_barrier
	v_mfma_f32_16x16x32_bf16 v[126:129], v[150:153], v[182:185], v[126:129]
	v_mfma_f32_16x16x32_bf16 v[122:125], v[158:161], v[182:185], v[122:125]
	v_mfma_f32_16x16x32_bf16 v[110:113], v[150:153], v[190:193], v[110:113]
	v_mfma_f32_16x16x32_bf16 v[106:109], v[158:161], v[190:193], v[106:109]
	v_mfma_f32_16x16x32_bf16 v[94:97], v[150:153], v[198:201], v[94:97]
	v_mfma_f32_16x16x32_bf16 v[90:93], v[158:161], v[198:201], v[90:93]
	v_mfma_f32_16x16x32_bf16 v[78:81], v[150:153], v[206:209], v[78:81]
	v_mfma_f32_16x16x32_bf16 v[74:77], v[158:161], v[206:209], v[74:77]
	v_mfma_f32_16x16x32_bf16 v[126:129], v[154:157], v[186:189], v[126:129]
	v_mfma_f32_16x16x32_bf16 v[122:125], v[162:165], v[186:189], v[122:125]
	v_mfma_f32_16x16x32_bf16 v[110:113], v[154:157], v[194:197], v[110:113]
	v_mfma_f32_16x16x32_bf16 v[106:109], v[162:165], v[194:197], v[106:109]
	v_mfma_f32_16x16x32_bf16 v[94:97], v[154:157], v[202:205], v[94:97]
	v_mfma_f32_16x16x32_bf16 v[90:93], v[162:165], v[202:205], v[90:93]
	v_mfma_f32_16x16x32_bf16 v[78:81], v[154:157], v[210:213], v[78:81]
	v_mfma_f32_16x16x32_bf16 v[74:77], v[162:165], v[210:213], v[74:77]
	v_mfma_f32_16x16x32_bf16 v[118:121], v[166:169], v[182:185], v[118:121]
	v_mfma_f32_16x16x32_bf16 v[114:117], v[174:177], v[182:185], v[114:117]
	v_mfma_f32_16x16x32_bf16 v[102:105], v[166:169], v[190:193], v[102:105]
	v_mfma_f32_16x16x32_bf16 v[98:101], v[174:177], v[190:193], v[98:101]
	v_mfma_f32_16x16x32_bf16 v[86:89], v[166:169], v[198:201], v[86:89]
	v_mfma_f32_16x16x32_bf16 v[82:85], v[174:177], v[198:201], v[82:85]
	v_mfma_f32_16x16x32_bf16 v[70:73], v[166:169], v[206:209], v[70:73]
	v_mfma_f32_16x16x32_bf16 v[66:69], v[174:177], v[206:209], v[66:69]
	v_mfma_f32_16x16x32_bf16 v[118:121], v[170:173], v[186:189], v[118:121]
	v_mfma_f32_16x16x32_bf16 v[114:117], v[178:181], v[186:189], v[114:117]
	v_mfma_f32_16x16x32_bf16 v[102:105], v[170:173], v[194:197], v[102:105]
	v_mfma_f32_16x16x32_bf16 v[98:101], v[178:181], v[194:197], v[98:101]
	v_mfma_f32_16x16x32_bf16 v[86:89], v[170:173], v[202:205], v[86:89]
	v_mfma_f32_16x16x32_bf16 v[82:85], v[178:181], v[202:205], v[82:85]
	v_mfma_f32_16x16x32_bf16 v[70:73], v[170:173], v[210:213], v[70:73]
	v_mfma_f32_16x16x32_bf16 v[66:69], v[178:181], v[210:213], v[66:69]
	s_barrier
; #define PG8_STAGEA(bufoff, gbase, voff) PG8_STAGE_X(bufoff, gbase, voff, AUXA)
; #define PG8_STAGEB(bufoff, gbase, voff) PG8_STAGE_X(bufoff, gbase, voff, AUXB)
; #define PG8_LDA(dst, b, h) do { _Pragma("unroll") for (int m = 0; m < 4; ++m) _Pragma("unroll") for (int k = 0; k < 2; ++k) dst[m][k] = *(const PG8_LAS bf16x8*)(lds + PG8_SA(b, h) + aoff + m * 2048 + k * 1024); } while (0)
; #define PG8_LDB(dst, b, h) do { _Pragma("unroll") for (int n = 0; n < 2; ++n) _Pragma("unroll") for (int k = 0; k < 2; ++k) dst[n][k] = *(const PG8_LAS bf16x8*)(lds + PG8_SB(b, h) + boff + n * 2048 + k * 1024); } while (0)
; #define PG8_MMA(ai, bj, At, Bt) do { if (GEMM_PRIO_MODE == 0) __builtin_amdgcn_s_setprio(1); PG8_MMA_LOOPS \
;         acc[ai][bj][m][n] = __builtin_amdgcn_mfma_f32_16x16x32_bf16(Bt[n][k], At[m][k], acc[ai][bj][m][n], 0, 0, 0); if (GEMM_PRIO_MODE == 0) __builtin_amdgcn_s_setprio(0); } while (0)
; #define PG8_WAIT_V(n) asm volatile("s_waitcnt vmcnt(" #n ")" ::: "memory")
; #define PG8_WAIT_VR(n, nr, flag) asm volatile("s_cmp_eq_u32 %0, 0\n\ts_cbranch_scc1 .Lpg8s%=\n\ts_waitcnt vmcnt(" #nr ")\n\ts_branch .Lpg8d%=\n.Lpg8s%=:\n\ts_waitcnt vmcnt(" #n ")\n.Lpg8d%=:" :: "s"(flag) : "memory", "scc")
;     ...
;             const bool last = (t == nt - 2);
;             const char* a1 = cA + (size_t)(t + 1) * kstepA;
;             const char* a2 = last ? nA : cA + (size_t)(t + 2) * kstepA; const char* b2 = last ? nB : cB + (size_t)(t + 2) * kstepB;
;             const char* a3 = a2 + kstepA; const char* b3 = b2 + kstepB;
;             if (last && has_next) S.a_ready(nxt);
;             if constexpr (SP2) {
;             PG8_LDB(B0, 0, 0); PG8_LDB(B1, 0, 1); PG8_SCHED; PG8_LDA(At, 0, 0); PG8_STAGEA(PG8_SA(1, 1), a1 + hstepA, voffA);
;     ...
;             const int relax = __builtin_amdgcn_readfirstlane((t == 0 && ui > 0) ? 1 : 0);
;             PG8_WAIT_VR(8, 24, relax); PG8_WAIT_L(0); PG8_BAR; PG8_MMA(0, 0, At, B0); PG8_MMA(0, 1, At, B1); PG8_BAR; PG8_SCHED;
;     ...
;             PG8_WAIT_V(8); PG8_WAIT_L(0); PG8_BAR; PG8_MMA(0, 0, At, B0); PG8_MMA(0, 1, At, B1); PG8_BAR; PG8_SCHED;
;     ...
;             PG8_LDA(At, 1, 1); PG8_STAGEB(PG8_SB(1, 0), b3, voffB); PG8_STAGEB(PG8_SB(1, 1), b3 + hstepB, voffB); PG8_STAGEA(PG8_SA(1, 0), a3, voffA);
;             PG8_WAIT_V(8); PG8_WAIT_L(0); PG8_BAR; PG8_MMA(1, 0, At, B0); PG8_MMA(1, 1, At, B1); PG8_BAR; PG8_SCHED;
	s_setprio 0
	s_add_i32 s6, s95, s50
	v_lshl_add_u64 v[144:145], v[144:145], 0, s[86:87]
	s_mov_b32 m0, s6
	ds_read_b128 v[182:185], v148 offset:49152
	ds_read_b128 v[186:189], v148 offset:50176
	ds_read_b128 v[190:193], v148 offset:51200
	ds_read_b128 v[194:197], v148 offset:52224
	ds_read_b128 v[198:201], v148 offset:53248
	ds_read_b128 v[202:205], v148 offset:54272
	ds_read_b128 v[206:209], v148 offset:55296
	ds_read_b128 v[210:213], v148 offset:56320
	global_load_lds_dwordx4 v[144:145], off
	s_add_i32 m0, s6, 0x2000
	s_add_u32 s6, s16, 0x100080
	v_lshl_add_u64 v[144:145], v[214:215], 0, s[86:87]
	s_addc_u32 s7, s17, 0
	s_add_i32 s16, vcc_lo, s50
	global_load_lds_dwordx4 v[144:145], off
	v_lshl_add_u64 v[144:145], s[6:7], 0, v[134:135]
	s_mov_b32 m0, s16
	s_nop 0
	global_load_lds_dwordx4 v[144:145], off
	v_lshl_add_u64 v[144:145], s[6:7], 0, v[130:131]
	s_add_i32 m0, s16, 0x2000
	s_nop 0
	global_load_lds_dwordx4 v[144:145], off
	v_lshl_add_u64 v[144:145], v[216:217], 0, s[86:87]
	s_mov_b32 m0, s83
	s_nop 0
	global_load_lds_dwordx4 v[144:145], off
	v_lshl_add_u64 v[144:145], v[218:219], 0, s[86:87]
	s_mov_b32 m0, s90
	s_nop 0
	global_load_lds_dwordx4 v[144:145], off
	s_waitcnt vmcnt(8)
	s_waitcnt lgkmcnt(0)
	s_nop 0
	s_setprio 1
	s_barrier
	v_mfma_f32_16x16x32_bf16 v[62:65], v[150:153], v[182:185], v[62:65]
	v_mfma_f32_16x16x32_bf16 v[58:61], v[158:161], v[182:185], v[58:61]
	v_mfma_f32_16x16x32_bf16 v[46:49], v[150:153], v[190:193], v[46:49]
	v_mfma_f32_16x16x32_bf16 v[42:45], v[158:161], v[190:193], v[42:45]
	v_mfma_f32_16x16x32_bf16 v[30:33], v[150:153], v[198:201], v[30:33]
	v_mfma_f32_16x16x32_bf16 v[26:29], v[158:161], v[198:201], v[26:29]
	v_mfma_f32_16x16x32_bf16 v[12:15], v[150:153], v[206:209], v[12:15]
	v_mfma_f32_16x16x32_bf16 v[8:11], v[158:161], v[206:209], v[8:11]
	v_mfma_f32_16x16x32_bf16 v[62:65], v[154:157], v[186:189], v[62:65]
	v_mfma_f32_16x16x32_bf16 v[58:61], v[162:165], v[186:189], v[58:61]
	v_mfma_f32_16x16x32_bf16 v[46:49], v[154:157], v[194:197], v[46:49]
	v_mfma_f32_16x16x32_bf16 v[42:45], v[162:165], v[194:197], v[42:45]
	v_mfma_f32_16x16x32_bf16 v[30:33], v[154:157], v[202:205], v[30:33]
	v_mfma_f32_16x16x32_bf16 v[26:29], v[162:165], v[202:205], v[26:29]
	v_mfma_f32_16x16x32_bf16 v[12:15], v[154:157], v[210:213], v[12:15]
	v_mfma_f32_16x16x32_bf16 v[8:11], v[162:165], v[210:213], v[8:11]
	v_mfma_f32_16x16x32_bf16 v[54:57], v[166:169], v[182:185], v[54:57]
	v_mfma_f32_16x16x32_bf16 v[50:53], v[174:177], v[182:185], v[50:53]
	v_mfma_f32_16x16x32_bf16 v[38:41], v[166:169], v[190:193], v[38:41]
	v_mfma_f32_16x16x32_bf16 v[34:37], v[174:177], v[190:193], v[34:37]
	v_mfma_f32_16x16x32_bf16 v[22:25], v[166:169], v[198:201], v[22:25]
	v_mfma_f32_16x16x32_bf16 v[18:21], v[174:177], v[198:201], v[18:21]
	v_mfma_f32_16x16x32_bf16 v[4:7], v[166:169], v[206:209], v[4:7]
	v_mfma_f32_16x16x32_bf16 v[0:3], v[174:177], v[206:209], v[0:3]
	v_mfma_f32_16x16x32_bf16 v[54:57], v[170:173], v[186:189], v[54:57]
	v_mfma_f32_16x16x32_bf16 v[50:53], v[178:181], v[186:189], v[50:53]
	v_mfma_f32_16x16x32_bf16 v[38:41], v[170:173], v[194:197], v[38:41]
	v_mfma_f32_16x16x32_bf16 v[34:37], v[178:181], v[194:197], v[34:37]
	v_mfma_f32_16x16x32_bf16 v[22:25], v[170:173], v[202:205], v[22:25]
	v_mfma_f32_16x16x32_bf16 v[18:21], v[178:181], v[202:205], v[18:21]
	v_mfma_f32_16x16x32_bf16 v[4:7], v[170:173], v[210:213], v[4:7]
	v_mfma_f32_16x16x32_bf16 v[0:3], v[178:181], v[210:213], v[0:3]
	s_barrier
	s_setprio 0
	s_add_i32 s39, s39, 2
	s_add_u32 s40, s40, 0x100
	s_addc_u32 s41, s41, 0
	s_add_u32 s12, s12, 0x100
	s_addc_u32 s13, s13, 0
.LBB0_712:
	s_add_u32 s6, s40, 0xfff00080
	s_addc_u32 s7, s41, -1
	s_add_i32 s95, 0, 0x10000
	s_cmp_eq_u32 s39, 60
	s_cselect_b32 s43, s0, s7
	s_cselect_b32 s42, s1, s6
	v_add_u32_e32 v144, s95, v146
	s_cselect_b32 s17, s23, s13
	s_cselect_b32 s16, s25, s12
	s_add_i32 vcc_lo, 0, 0x14000
	ds_read_b128 v[150:153], v144
	ds_read_b128 v[154:157], v144 offset:1024
	ds_read_b128 v[158:161], v144 offset:2048
	ds_read_b128 v[162:165], v144 offset:3072
	v_add_u32_e32 v144, vcc_lo, v146
	ds_read_b128 v[166:169], v144
	ds_read_b128 v[170:173], v144 offset:1024
	ds_read_b128 v[174:177], v144 offset:2048
	ds_read_b128 v[178:181], v144 offset:3072
	v_lshl_add_u64 v[144:145], s[40:41], 0, v[140:141]
	s_add_i32 m0, s69, 0xc000
	ds_read_b128 v[182:185], v148
	ds_read_b128 v[186:189], v148 offset:1024
	ds_read_b128 v[190:193], v148 offset:2048
	ds_read_b128 v[194:197], v148 offset:3072
	ds_read_b128 v[198:201], v148 offset:4096
	ds_read_b128 v[202:205], v148 offset:5120
	ds_read_b128 v[206:209], v148 offset:6144
	ds_read_b128 v[210:213], v148 offset:7168
	global_load_lds_dwordx4 v[144:145], off
	v_lshl_add_u64 v[144:145], s[40:41], 0, v[142:143]
	s_add_i32 m0, s69, 0xe000
	s_nop 0
	global_load_lds_dwordx4 v[144:145], off
	s_waitcnt vmcnt(8)
	s_waitcnt lgkmcnt(0)
	s_nop 0
	s_nop 0
	s_nop 0
	s_nop 0
	s_nop 0
	s_nop 0
	s_nop 0
	s_nop 0
	s_setprio 1
	s_barrier
; #define PG8_STAGEA(bufoff, gbase, voff) PG8_STAGE_X(bufoff, gbase, voff, AUXA)
; #define PG8_STAGEB(bufoff, gbase, voff) PG8_STAGE_X(bufoff, gbase, voff, AUXB)
; #define PG8_LDA(dst, b, h) do { _Pragma("unroll") for (int m = 0; m < 4; ++m) _Pragma("unroll") for (int k = 0; k < 2; ++k) dst[m][k] = *(const PG8_LAS bf16x8*)(lds + PG8_SA(b, h) + aoff + m * 2048 + k * 1024); } while (0)
; #define PG8_MMA(ai, bj, At, Bt) do { if (GEMM_PRIO_MODE == 0) __builtin_amdgcn_s_setprio(1); PG8_MMA_LOOPS \
;         acc[ai][bj][m][n] = __builtin_amdgcn_mfma_f32_16x16x32_bf16(Bt[n][k], At[m][k], acc[ai][bj][m][n], 0, 0, 0); if (GEMM_PRIO_MODE == 0) __builtin_amdgcn_s_setprio(0); } while (0)
; #define PG8_WAIT_V(n) asm volatile("s_waitcnt vmcnt(" #n ")" ::: "memory")
; #define PG8_WAIT_VR(n, nr, flag) asm volatile("s_cmp_eq_u32 %0, 0\n\ts_cbranch_scc1 .Lpg8s%=\n\ts_waitcnt vmcnt(" #nr ")\n\ts_branch .Lpg8d%=\n.Lpg8s%=:\n\ts_waitcnt vmcnt(" #n ")\n.Lpg8d%=:" :: "s"(flag) : "memory", "scc")
; #define PG8_WAIT_L(n) asm volatile("s_waitcnt lgkmcnt(" #n ")" ::: "memory")
; #define PG8_BAR __builtin_amdgcn_s_barrier()
; #define PG8_SCHED __builtin_amdgcn_sched_barrier(0)
;     ...
;             PG8_WAIT_V(8); PG8_WAIT_L(0); PG8_BAR; PG8_MMA(0, 0, At, B0); PG8_MMA(0, 1, At, B1); PG8_BAR; PG8_SCHED;
;     ...
;             PG8_LDA(At, 0, 1); PG8_STAGEB(PG8_SB(0, 0), b2, voffB); PG8_STAGEB(PG8_SB(0, 1), b2 + hstepB, voffB); PG8_STAGEA(PG8_SA(0, 0), a2, voffA);
;     ...
;             PG8_WAIT_VR(8, 24, relax); PG8_WAIT_L(0); PG8_BAR; PG8_MMA(1, 0, At, B0); PG8_MMA(1, 1, At, B1); PG8_BAR; PG8_SCHED;
;     ...
;             PG8_WAIT_V(8); PG8_WAIT_L(0); PG8_BAR; PG8_MMA(1, 0, At, B0); PG8_MMA(1, 1, At, B1); PG8_BAR; PG8_SCHED;
	v_mfma_f32_16x16x32_bf16 v[126:129], v[150:153], v[182:185], v[126:129]
	v_mfma_f32_16x16x32_bf16 v[122:125], v[158:161], v[182:185], v[122:125]
	v_mfma_f32_16x16x32_bf16 v[110:113], v[150:153], v[190:193], v[110:113]
	v_mfma_f32_16x16x32_bf16 v[106:109], v[158:161], v[190:193], v[106:109]
	v_mfma_f32_16x16x32_bf16 v[94:97], v[150:153], v[198:201], v[94:97]
	v_mfma_f32_16x16x32_bf16 v[90:93], v[158:161], v[198:201], v[90:93]
	v_mfma_f32_16x16x32_bf16 v[78:81], v[150:153], v[206:209], v[78:81]
	v_mfma_f32_16x16x32_bf16 v[74:77], v[158:161], v[206:209], v[74:77]
	v_mfma_f32_16x16x32_bf16 v[126:129], v[154:157], v[186:189], v[126:129]
	v_mfma_f32_16x16x32_bf16 v[122:125], v[162:165], v[186:189], v[122:125]
	v_mfma_f32_16x16x32_bf16 v[110:113], v[154:157], v[194:197], v[110:113]
	v_mfma_f32_16x16x32_bf16 v[106:109], v[162:165], v[194:197], v[106:109]
	v_mfma_f32_16x16x32_bf16 v[94:97], v[154:157], v[202:205], v[94:97]
	v_mfma_f32_16x16x32_bf16 v[90:93], v[162:165], v[202:205], v[90:93]
	v_mfma_f32_16x16x32_bf16 v[78:81], v[154:157], v[210:213], v[78:81]
	v_mfma_f32_16x16x32_bf16 v[74:77], v[162:165], v[210:213], v[74:77]
	v_mfma_f32_16x16x32_bf16 v[118:121], v[166:169], v[182:185], v[118:121]
	v_mfma_f32_16x16x32_bf16 v[114:117], v[174:177], v[182:185], v[114:117]
	v_mfma_f32_16x16x32_bf16 v[102:105], v[166:169], v[190:193], v[102:105]
	v_mfma_f32_16x16x32_bf16 v[98:101], v[174:177], v[190:193], v[98:101]
	v_mfma_f32_16x16x32_bf16 v[86:89], v[166:169], v[198:201], v[86:89]
	v_mfma_f32_16x16x32_bf16 v[82:85], v[174:177], v[198:201], v[82:85]
	v_mfma_f32_16x16x32_bf16 v[70:73], v[166:169], v[206:209], v[70:73]
	v_mfma_f32_16x16x32_bf16 v[66:69], v[174:177], v[206:209], v[66:69]
	v_mfma_f32_16x16x32_bf16 v[118:121], v[170:173], v[186:189], v[118:121]
	v_mfma_f32_16x16x32_bf16 v[114:117], v[178:181], v[186:189], v[114:117]
	v_mfma_f32_16x16x32_bf16 v[102:105], v[170:173], v[194:197], v[102:105]
	v_mfma_f32_16x16x32_bf16 v[98:101], v[178:181], v[194:197], v[98:101]
	v_mfma_f32_16x16x32_bf16 v[86:89], v[170:173], v[202:205], v[86:89]
	v_mfma_f32_16x16x32_bf16 v[82:85], v[178:181], v[202:205], v[82:85]
	v_mfma_f32_16x16x32_bf16 v[70:73], v[170:173], v[210:213], v[70:73]
	v_mfma_f32_16x16x32_bf16 v[66:69], v[178:181], v[210:213], v[66:69]
	s_barrier
	s_setprio 0
	s_add_i32 s6, s95, s50
	v_lshl_add_u64 v[144:145], s[16:17], 0, v[134:135]
	s_mov_b32 m0, s6
	ds_read_b128 v[182:185], v148 offset:16384
	ds_read_b128 v[186:189], v148 offset:17408
	ds_read_b128 v[190:193], v148 offset:18432
	ds_read_b128 v[194:197], v148 offset:19456
	ds_read_b128 v[198:201], v148 offset:20480
	ds_read_b128 v[202:205], v148 offset:21504
	ds_read_b128 v[206:209], v148 offset:22528
	ds_read_b128 v[210:213], v148 offset:23552
	global_load_lds_dwordx4 v[144:145], off
	s_add_i32 m0, s6, 0x2000
	s_add_u32 s6, s16, 0x100000
	v_lshl_add_u64 v[214:215], s[16:17], 0, v[130:131]
	s_addc_u32 s7, s17, 0
	s_add_i32 s95, vcc_lo, s50
	global_load_lds_dwordx4 v[214:215], off
	v_lshl_add_u64 v[216:217], s[6:7], 0, v[134:135]
	s_mov_b32 m0, s95
	v_lshl_add_u64 v[218:219], s[42:43], 0, v[132:133]
	global_load_lds_dwordx4 v[216:217], off
	v_lshl_add_u64 v[216:217], s[6:7], 0, v[130:131]
	s_add_i32 m0, s95, 0x2000
	s_nop 0
	global_load_lds_dwordx4 v[216:217], off
	v_lshl_add_u64 v[216:217], s[42:43], 0, v[136:137]
	s_mov_b32 m0, s69
	s_nop 0
	global_load_lds_dwordx4 v[216:217], off
	s_mov_b32 m0, s72
	s_nop 0
	global_load_lds_dwordx4 v[218:219], off
	s_waitcnt vmcnt(8)
	s_waitcnt lgkmcnt(0)
	s_nop 0
	s_nop 0
	s_setprio 1
	s_barrier
	v_mfma_f32_16x16x32_bf16 v[62:65], v[150:153], v[182:185], v[62:65]
	v_mfma_f32_16x16x32_bf16 v[58:61], v[158:161], v[182:185], v[58:61]
	v_mfma_f32_16x16x32_bf16 v[46:49], v[150:153], v[190:193], v[46:49]
	v_mfma_f32_16x16x32_bf16 v[42:45], v[158:161], v[190:193], v[42:45]
	v_mfma_f32_16x16x32_bf16 v[30:33], v[150:153], v[198:201], v[30:33]
	v_mfma_f32_16x16x32_bf16 v[26:29], v[158:161], v[198:201], v[26:29]
	v_mfma_f32_16x16x32_bf16 v[12:15], v[150:153], v[206:209], v[12:15]
	v_mfma_f32_16x16x32_bf16 v[8:11], v[158:161], v[206:209], v[8:11]
	v_mfma_f32_16x16x32_bf16 v[62:65], v[154:157], v[186:189], v[62:65]
	v_mfma_f32_16x16x32_bf16 v[58:61], v[162:165], v[186:189], v[58:61]
	v_mfma_f32_16x16x32_bf16 v[46:49], v[154:157], v[194:197], v[46:49]
	v_mfma_f32_16x16x32_bf16 v[42:45], v[162:165], v[194:197], v[42:45]
	v_mfma_f32_16x16x32_bf16 v[30:33], v[154:157], v[202:205], v[30:33]
	v_mfma_f32_16x16x32_bf16 v[26:29], v[162:165], v[202:205], v[26:29]
	v_mfma_f32_16x16x32_bf16 v[12:15], v[154:157], v[210:213], v[12:15]
	v_mfma_f32_16x16x32_bf16 v[8:11], v[162:165], v[210:213], v[8:11]
	v_mfma_f32_16x16x32_bf16 v[54:57], v[166:169], v[182:185], v[54:57]
	v_mfma_f32_16x16x32_bf16 v[50:53], v[174:177], v[182:185], v[50:53]
	v_mfma_f32_16x16x32_bf16 v[38:41], v[166:169], v[190:193], v[38:41]
	v_mfma_f32_16x16x32_bf16 v[34:37], v[174:177], v[190:193], v[34:37]
	v_mfma_f32_16x16x32_bf16 v[22:25], v[166:169], v[198:201], v[22:25]
	v_mfma_f32_16x16x32_bf16 v[18:21], v[174:177], v[198:201], v[18:21]
	v_mfma_f32_16x16x32_bf16 v[4:7], v[166:169], v[206:209], v[4:7]
	v_mfma_f32_16x16x32_bf16 v[0:3], v[174:177], v[206:209], v[0:3]
	v_mfma_f32_16x16x32_bf16 v[54:57], v[170:173], v[186:189], v[54:57]
	v_mfma_f32_16x16x32_bf16 v[50:53], v[178:181], v[186:189], v[50:53]
	v_mfma_f32_16x16x32_bf16 v[38:41], v[170:173], v[194:197], v[38:41]
	v_mfma_f32_16x16x32_bf16 v[34:37], v[178:181], v[194:197], v[34:37]
	v_mfma_f32_16x16x32_bf16 v[22:25], v[170:173], v[202:205], v[22:25]
	v_mfma_f32_16x16x32_bf16 v[18:21], v[178:181], v[202:205], v[18:21]
	v_mfma_f32_16x16x32_bf16 v[4:7], v[170:173], v[210:213], v[4:7]
	v_mfma_f32_16x16x32_bf16 v[0:3], v[178:181], v[210:213], v[0:3]
	s_barrier
; #define PG8_STAGEA(bufoff, gbase, voff) PG8_STAGE_X(bufoff, gbase, voff, AUXA)
; #define PG8_LDA(dst, b, h) do { _Pragma("unroll") for (int m = 0; m < 4; ++m) _Pragma("unroll") for (int k = 0; k < 2; ++k) dst[m][k] = *(const PG8_LAS bf16x8*)(lds + PG8_SA(b, h) + aoff + m * 2048 + k * 1024); } while (0)
; #define PG8_LDB(dst, b, h) do { _Pragma("unroll") for (int n = 0; n < 2; ++n) _Pragma("unroll") for (int k = 0; k < 2; ++k) dst[n][k] = *(const PG8_LAS bf16x8*)(lds + PG8_SB(b, h) + boff + n * 2048 + k * 1024); } while (0)
; #define PG8_MMA(ai, bj, At, Bt) do { if (GEMM_PRIO_MODE == 0) __builtin_amdgcn_s_setprio(1); PG8_MMA_LOOPS \
;         acc[ai][bj][m][n] = __builtin_amdgcn_mfma_f32_16x16x32_bf16(Bt[n][k], At[m][k], acc[ai][bj][m][n], 0, 0, 0); if (GEMM_PRIO_MODE == 0) __builtin_amdgcn_s_setprio(0); } while (0)
; #define PG8_WAIT_V(n) asm volatile("s_waitcnt vmcnt(" #n ")" ::: "memory")
; #define PG8_WAIT_L(n) asm volatile("s_waitcnt lgkmcnt(" #n ")" ::: "memory")
; #define PG8_BAR __builtin_amdgcn_s_barrier()
; #define PG8_SCHED __builtin_amdgcn_sched_barrier(0)
;     ...
;             PG8_LDB(B0, 1, 0); PG8_LDB(B1, 1, 1); PG8_SCHED; PG8_LDA(At, 1, 0); PG8_STAGEA(PG8_SA(0, 1), a2 + hstepA, voffA);
;             PG8_WAIT_V(8); PG8_WAIT_L(0); PG8_BAR; PG8_MMA(0, 0, At, B0); PG8_MMA(0, 1, At, B1); PG8_BAR; PG8_SCHED;
	s_setprio 0
	s_add_i32 s95, 0, 0x18000
	v_add_u32_e32 v149, s95, v146
	s_add_i32 vcc_lo, 0, 0x1c000
	ds_read_b128 v[150:153], v149
	ds_read_b128 v[154:157], v149 offset:1024
	ds_read_b128 v[158:161], v149 offset:2048
	ds_read_b128 v[162:165], v149 offset:3072
	v_add_u32_e32 v149, vcc_lo, v146
	ds_read_b128 v[166:169], v149
	ds_read_b128 v[170:173], v149 offset:1024
	ds_read_b128 v[174:177], v149 offset:2048
	ds_read_b128 v[178:181], v149 offset:3072
	s_add_u32 s6, s42, 0x100000
	s_addc_u32 s7, s43, 0
	s_mov_b32 m0, s73
	v_lshl_add_u64 v[220:221], s[6:7], 0, v[136:137]
	ds_read_b128 v[182:185], v148 offset:32768
	ds_read_b128 v[186:189], v148 offset:33792
	ds_read_b128 v[190:193], v148 offset:34816
	ds_read_b128 v[194:197], v148 offset:35840
	ds_read_b128 v[198:201], v148 offset:36864
	ds_read_b128 v[202:205], v148 offset:37888
	ds_read_b128 v[206:209], v148 offset:38912
	ds_read_b128 v[210:213], v148 offset:39936
	global_load_lds_dwordx4 v[220:221], off
	v_lshl_add_u64 v[220:221], s[6:7], 0, v[132:133]
	s_mov_b32 m0, s82
	s_nop 0
	global_load_lds_dwordx4 v[220:221], off
	s_waitcnt vmcnt(8)
	s_waitcnt lgkmcnt(0)
	s_nop 0
	s_nop 0
	s_nop 0
	s_nop 0
	s_nop 0
	s_nop 0
	s_setprio 1
	s_barrier
	v_mfma_f32_16x16x32_bf16 v[126:129], v[150:153], v[182:185], v[126:129]
	v_mfma_f32_16x16x32_bf16 v[122:125], v[158:161], v[182:185], v[122:125]
	v_mfma_f32_16x16x32_bf16 v[110:113], v[150:153], v[190:193], v[110:113]
	v_mfma_f32_16x16x32_bf16 v[106:109], v[158:161], v[190:193], v[106:109]
	v_mfma_f32_16x16x32_bf16 v[94:97], v[150:153], v[198:201], v[94:97]
	v_mfma_f32_16x16x32_bf16 v[90:93], v[158:161], v[198:201], v[90:93]
	v_mfma_f32_16x16x32_bf16 v[78:81], v[150:153], v[206:209], v[78:81]
	v_mfma_f32_16x16x32_bf16 v[74:77], v[158:161], v[206:209], v[74:77]
	v_mfma_f32_16x16x32_bf16 v[126:129], v[154:157], v[186:189], v[126:129]
	v_mfma_f32_16x16x32_bf16 v[122:125], v[162:165], v[186:189], v[122:125]
	v_mfma_f32_16x16x32_bf16 v[110:113], v[154:157], v[194:197], v[110:113]
	v_mfma_f32_16x16x32_bf16 v[106:109], v[162:165], v[194:197], v[106:109]
	v_mfma_f32_16x16x32_bf16 v[94:97], v[154:157], v[202:205], v[94:97]
	v_mfma_f32_16x16x32_bf16 v[90:93], v[162:165], v[202:205], v[90:93]
	v_mfma_f32_16x16x32_bf16 v[78:81], v[154:157], v[210:213], v[78:81]
	v_mfma_f32_16x16x32_bf16 v[74:77], v[162:165], v[210:213], v[74:77]
	v_mfma_f32_16x16x32_bf16 v[118:121], v[166:169], v[182:185], v[118:121]
	v_mfma_f32_16x16x32_bf16 v[114:117], v[174:177], v[182:185], v[114:117]
	v_mfma_f32_16x16x32_bf16 v[102:105], v[166:169], v[190:193], v[102:105]
	v_mfma_f32_16x16x32_bf16 v[98:101], v[174:177], v[190:193], v[98:101]
	v_mfma_f32_16x16x32_bf16 v[86:89], v[166:169], v[198:201], v[86:89]
	v_mfma_f32_16x16x32_bf16 v[82:85], v[174:177], v[198:201], v[82:85]
	v_mfma_f32_16x16x32_bf16 v[70:73], v[166:169], v[206:209], v[70:73]
	v_mfma_f32_16x16x32_bf16 v[66:69], v[174:177], v[206:209], v[66:69]
	v_mfma_f32_16x16x32_bf16 v[118:121], v[170:173], v[186:189], v[118:121]
	v_mfma_f32_16x16x32_bf16 v[114:117], v[178:181], v[186:189], v[114:117]
	v_mfma_f32_16x16x32_bf16 v[102:105], v[170:173], v[194:197], v[102:105]
	v_mfma_f32_16x16x32_bf16 v[98:101], v[178:181], v[194:197], v[98:101]
	v_mfma_f32_16x16x32_bf16 v[86:89], v[170:173], v[202:205], v[86:89]
	v_mfma_f32_16x16x32_bf16 v[82:85], v[178:181], v[202:205], v[82:85]
	v_mfma_f32_16x16x32_bf16 v[70:73], v[170:173], v[210:213], v[70:73]
	v_mfma_f32_16x16x32_bf16 v[66:69], v[178:181], v[210:213], v[66:69]
	s_barrier
; #define PG8_STAGEA(bufoff, gbase, voff) PG8_STAGE_X(bufoff, gbase, voff, AUXA)
; #define PG8_STAGEB(bufoff, gbase, voff) PG8_STAGE_X(bufoff, gbase, voff, AUXB)
; #define PG8_LDA(dst, b, h) do { _Pragma("unroll") for (int m = 0; m < 4; ++m) _Pragma("unroll") for (int k = 0; k < 2; ++k) dst[m][k] = *(const PG8_LAS bf16x8*)(lds + PG8_SA(b, h) + aoff + m * 2048 + k * 1024); } while (0)
; #define PG8_MMA(ai, bj, At, Bt) do { if (GEMM_PRIO_MODE == 0) __builtin_amdgcn_s_setprio(1); PG8_MMA_LOOPS \
;         acc[ai][bj][m][n] = __builtin_amdgcn_mfma_f32_16x16x32_bf16(Bt[n][k], At[m][k], acc[ai][bj][m][n], 0, 0, 0); if (GEMM_PRIO_MODE == 0) __builtin_amdgcn_s_setprio(0); } while (0)
; #define PG8_WAIT_V(n) asm volatile("s_waitcnt vmcnt(" #n ")" ::: "memory")
; #define PG8_WAIT_L(n) asm volatile("s_waitcnt lgkmcnt(" #n ")" ::: "memory")
; #define PG8_BAR __builtin_amdgcn_s_barrier()
; #define PG8_SCHED __builtin_amdgcn_sched_barrier(0)
;     ...
;             PG8_LDA(At, 1, 1); PG8_STAGEB(PG8_SB(1, 0), b3, voffB); PG8_STAGEB(PG8_SB(1, 1), b3 + hstepB, voffB); PG8_STAGEA(PG8_SA(1, 0), a3, voffA);
;             PG8_WAIT_V(8); PG8_WAIT_L(0); PG8_BAR; PG8_MMA(1, 0, At, B0); PG8_MMA(1, 1, At, B1); PG8_BAR; PG8_SCHED;
;     ...
;         if constexpr (ALIGN_EPI) { if (wr == 0) PG8_BAR; }
	s_setprio 0
	s_add_i32 s6, s95, s50
	v_lshl_add_u64 v[144:145], v[144:145], 0, s[86:87]
	s_mov_b32 m0, s6
	ds_read_b128 v[182:185], v148 offset:49152
	ds_read_b128 v[186:189], v148 offset:50176
	ds_read_b128 v[190:193], v148 offset:51200
	ds_read_b128 v[194:197], v148 offset:52224
	ds_read_b128 v[198:201], v148 offset:53248
	ds_read_b128 v[202:205], v148 offset:54272
	ds_read_b128 v[206:209], v148 offset:55296
	ds_read_b128 v[210:213], v148 offset:56320
	global_load_lds_dwordx4 v[144:145], off
	s_add_i32 m0, s6, 0x2000
	s_add_u32 s6, s16, 0x100080
	v_lshl_add_u64 v[144:145], v[214:215], 0, s[86:87]
	s_addc_u32 s7, s17, 0
	s_add_i32 s16, vcc_lo, s50
	global_load_lds_dwordx4 v[144:145], off
	v_lshl_add_u64 v[144:145], s[6:7], 0, v[134:135]
	s_mov_b32 m0, s16
	s_nop 0
	global_load_lds_dwordx4 v[144:145], off
	v_lshl_add_u64 v[144:145], s[6:7], 0, v[130:131]
	s_add_i32 m0, s16, 0x2000
	s_nop 0
	global_load_lds_dwordx4 v[144:145], off
	v_lshl_add_u64 v[144:145], v[216:217], 0, s[86:87]
	s_mov_b32 m0, s83
	s_nop 0
	global_load_lds_dwordx4 v[144:145], off
	v_lshl_add_u64 v[144:145], v[218:219], 0, s[86:87]
	s_mov_b32 m0, s90
	s_nop 0
	global_load_lds_dwordx4 v[144:145], off
	s_waitcnt vmcnt(8)
	s_waitcnt lgkmcnt(0)
	s_nop 0
	s_setprio 1
	s_barrier
	v_mfma_f32_16x16x32_bf16 v[62:65], v[150:153], v[182:185], v[62:65]
	v_mfma_f32_16x16x32_bf16 v[58:61], v[158:161], v[182:185], v[58:61]
	v_mfma_f32_16x16x32_bf16 v[46:49], v[150:153], v[190:193], v[46:49]
	v_mfma_f32_16x16x32_bf16 v[42:45], v[158:161], v[190:193], v[42:45]
	v_mfma_f32_16x16x32_bf16 v[30:33], v[150:153], v[198:201], v[30:33]
	v_mfma_f32_16x16x32_bf16 v[26:29], v[158:161], v[198:201], v[26:29]
	v_mfma_f32_16x16x32_bf16 v[12:15], v[150:153], v[206:209], v[12:15]
	v_mfma_f32_16x16x32_bf16 v[8:11], v[158:161], v[206:209], v[8:11]
	v_mfma_f32_16x16x32_bf16 v[62:65], v[154:157], v[186:189], v[62:65]
	v_mfma_f32_16x16x32_bf16 v[58:61], v[162:165], v[186:189], v[58:61]
	v_mfma_f32_16x16x32_bf16 v[46:49], v[154:157], v[194:197], v[46:49]
	v_mfma_f32_16x16x32_bf16 v[42:45], v[162:165], v[194:197], v[42:45]
	v_mfma_f32_16x16x32_bf16 v[30:33], v[154:157], v[202:205], v[30:33]
	v_mfma_f32_16x16x32_bf16 v[26:29], v[162:165], v[202:205], v[26:29]
	v_mfma_f32_16x16x32_bf16 v[12:15], v[154:157], v[210:213], v[12:15]
	v_mfma_f32_16x16x32_bf16 v[8:11], v[162:165], v[210:213], v[8:11]
	v_mfma_f32_16x16x32_bf16 v[54:57], v[166:169], v[182:185], v[54:57]
	v_mfma_f32_16x16x32_bf16 v[50:53], v[174:177], v[182:185], v[50:53]
	v_mfma_f32_16x16x32_bf16 v[38:41], v[166:169], v[190:193], v[38:41]
	v_mfma_f32_16x16x32_bf16 v[34:37], v[174:177], v[190:193], v[34:37]
	v_mfma_f32_16x16x32_bf16 v[22:25], v[166:169], v[198:201], v[22:25]
	v_mfma_f32_16x16x32_bf16 v[18:21], v[174:177], v[198:201], v[18:21]
	v_mfma_f32_16x16x32_bf16 v[4:7], v[166:169], v[206:209], v[4:7]
	v_mfma_f32_16x16x32_bf16 v[0:3], v[174:177], v[206:209], v[0:3]
	v_mfma_f32_16x16x32_bf16 v[54:57], v[170:173], v[186:189], v[54:57]
	v_mfma_f32_16x16x32_bf16 v[50:53], v[178:181], v[186:189], v[50:53]
	v_mfma_f32_16x16x32_bf16 v[38:41], v[170:173], v[194:197], v[38:41]
	v_mfma_f32_16x16x32_bf16 v[34:37], v[178:181], v[194:197], v[34:37]
	v_mfma_f32_16x16x32_bf16 v[22:25], v[170:173], v[202:205], v[22:25]
	v_mfma_f32_16x16x32_bf16 v[18:21], v[178:181], v[202:205], v[18:21]
	v_mfma_f32_16x16x32_bf16 v[4:7], v[170:173], v[210:213], v[4:7]
	v_mfma_f32_16x16x32_bf16 v[0:3], v[178:181], v[210:213], v[0:3]
	s_barrier
	s_setprio 0
	s_add_i32 s39, s39, 2
	s_add_u32 s40, s40, 0x100
	s_addc_u32 s41, s41, 0
	s_add_u32 s12, s12, 0x100
	s_addc_u32 s13, s13, 0
	s_cmp_gt_u32 s39, 61
	s_cbranch_scc0 .LBB0_712
	s_and_b64 vcc, exec, s[18:19]
	s_cbranch_vccz .LBB0_715
	s_barrier

; #define PG8_STAGEA(bufoff, gbase, voff) PG8_STAGE_X(bufoff, gbase, voff, AUXA)
; #define PG8_STR(x) PG8_STR2(x)
;     ...
;         const bool has_next = S.next(ui + 1, nxt);
;         const char* nA = has_next ? (const char*)g.A + (size_t)nxt.pm * tstepA : cA; const char* nB = has_next ? (const char*)g.Bt + (size_t)nxt.pn * tstepB : cB;
;         int t0 = 0;
;         if constexpr (SP2 && GEMM_RELAX == 1) { if (ui > 0) {
;             const char* a1 = cA + kstepA; const char* a2 = cA + 2 * kstepA; const char* b2 = cB + 2 * kstepB; const char* a3 = a2 + kstepA; const char* b3 = b2 + kstepB;
;             PG8_LDB(B0, 0, 0); PG8_LDB(B1, 0, 1); PG8_SCHED; PG8_LDA(At, 0, 0); PG8_STAGEA(PG8_SA(1, 1), a1 + hstepA, voffA);
;             PG8_WAIT_V(24); PG8_WAIT_L(0); PG8_BAR; PG8_MMA(0, 0, At, B0); PG8_MMA(0, 1, At, B1); PG8_BAR; PG8_SCHED;
;             PG8_LDA(At, 0, 1); PG8_STAGEB(PG8_SB(0, 0), b2, voffB); PG8_STAGEB(PG8_SB(0, 1), b2 + hstepB, voffB); PG8_STAGEA(PG8_SA(0, 0), a2, voffA);
;             PG8_WAIT_V(24); PG8_WAIT_L(0); PG8_BAR; PG8_MMA(1, 0, At, B0); PG8_MMA(1, 1, At, B1); PG8_BAR; PG8_SCHED;
;             PG8_LDB(B0, 1, 0); PG8_LDB(B1, 1, 1); PG8_SCHED; PG8_LDA(At, 1, 0); PG8_STAGEA(PG8_SA(0, 1), a2 + hstepA, voffA);
;             PG8_WAIT_V(8); PG8_WAIT_L(0); PG8_BAR; PG8_MMA(0, 0, At, B0); PG8_MMA(0, 1, At, B1); PG8_BAR; PG8_SCHED;
;             PG8_LDA(At, 1, 1); PG8_STAGEB(PG8_SB(1, 0), b3, voffB); PG8_STAGEB(PG8_SB(1, 1), b3 + hstepB, voffB); PG8_STAGEA(PG8_SA(1, 0), a3, voffA);
;             PG8_WAIT_V(8); PG8_WAIT_L(0); PG8_BAR; PG8_MMA(1, 0, At, B0); PG8_MMA(1, 1, At, B1); PG8_BAR; PG8_SCHED;
;             t0 = 2; } }
;     ...
;         asm volatile(".p2align " PG8_STR(GEMM_LOOP_ALIGN) ::: "memory");
;     ...
;         for (int t = t0; t < nt; t += 2) {
;             const bool last = (t == nt - 2);
;             const char* a1 = cA + (size_t)(t + 1) * kstepA;
;             const char* a2 = last ? nA : cA + (size_t)(t + 2) * kstepA; const char* b2 = last ? nB : cB + (size_t)(t + 2) * kstepB;
;             const char* a3 = a2 + kstepA; const char* b3 = b2 + kstepB;
;             if (last && has_next) S.a_ready(nxt);
;             if constexpr (SP2) {
;             PG8_LDB(B0, 0, 0); PG8_LDB(B1, 0, 1); PG8_SCHED; PG8_LDA(At, 0, 0); PG8_STAGEA(PG8_SA(1, 1), a1 + hstepA, voffA);
;     ...
;             const int relax = __builtin_amdgcn_readfirstlane((t == 0 && ui > 0) ? 1 : 0);
.LBB0_847:
	s_ashr_i32 s11, s10, 31
	s_lshl_b64 s[18:19], s[10:11], 23
	s_add_u32 s18, s62, s18
	s_addc_u32 s19, s63, s19
	s_and_b64 s[22:23], s[20:21], exec
	s_cselect_b32 s11, s19, s1
	s_cselect_b32 s73, s18, s0
	s_ashr_i32 s15, s14, 31
	s_lshl_b64 s[22:23], s[14:15], 23
	s_add_u32 s22, s12, s22
	s_addc_u32 s23, s13, s23
	s_and_b64 s[24:25], s[20:21], exec
	s_cselect_b32 s15, s23, s17
	s_cselect_b32 s78, s22, s16
	s_add_u32 s24, s0, 0xc000
	s_addc_u32 s25, s1, 0
	s_add_u32 s0, s16, 0x10000
	s_addc_u32 s1, s17, 0
	s_mov_b32 s82, -2
	s_waitcnt lgkmcnt(0)
	s_add_u32 s16, s24, 0x4000
	s_addc_u32 s17, s25, 0
	s_cmpk_eq_i32 s82, 0xfc
	s_cselect_b32 s36, s73, s16
	s_cselect_b32 s37, s11, s17
	s_cselect_b32 s16, s78, s0
	s_cselect_b32 s17, s15, s1
	s_add_u32 s26, s36, 0x8000
	s_addc_u32 s27, s37, 0
	s_add_i32 s83, 0, 0x10000
	s_add_i32 s94, 0, 0x14000
	v_add_u32_e32 v152, s83, v157
	v_add_u32_e32 v174, s94, v157
	ds_read_b128 v[130:133], v152
	ds_read_b128 v[134:137], v152 offset:1024
	ds_read_b128 v[148:151], v152 offset:2048
	ds_read_b128 v[152:155], v152 offset:3072
	ds_read_b128 v[162:165], v174
	ds_read_b128 v[166:169], v174 offset:1024
	ds_read_b128 v[170:173], v174 offset:2048
	ds_read_b128 v[174:177], v174 offset:3072
	v_lshl_add_u64 v[210:211], s[24:25], 0, v[144:145]
	s_add_i32 m0, s39, 0xc000
	ds_read_b128 v[178:181], v161
	ds_read_b128 v[182:185], v161 offset:1024
	ds_read_b128 v[186:189], v161 offset:2048
	ds_read_b128 v[190:193], v161 offset:3072
	ds_read_b128 v[194:197], v161 offset:4096
	ds_read_b128 v[198:201], v161 offset:5120
	ds_read_b128 v[202:205], v161 offset:6144
	ds_read_b128 v[206:209], v161 offset:7168
	global_load_lds_dwordx4 v[210:211], off
	v_lshl_add_u64 v[210:211], s[24:25], 0, v[146:147]
	s_add_i32 m0, s39, 0xe000
	s_nop 0
	global_load_lds_dwordx4 v[210:211], off
	s_waitcnt vmcnt(8)
	s_waitcnt lgkmcnt(0)
	s_nop 0
	s_nop 0
	s_nop 0
	s_nop 0
	s_nop 0
	s_nop 0
	s_setprio 1
	s_barrier
	v_mfma_f32_16x16x32_bf16 v[126:129], v[130:133], v[178:181], 0
	v_mfma_f32_16x16x32_bf16 v[122:125], v[148:151], v[178:181], 0
	v_mfma_f32_16x16x32_bf16 v[110:113], v[130:133], v[186:189], 0
	v_mfma_f32_16x16x32_bf16 v[106:109], v[148:151], v[186:189], 0
	v_mfma_f32_16x16x32_bf16 v[94:97], v[130:133], v[194:197], 0
	v_mfma_f32_16x16x32_bf16 v[90:93], v[148:151], v[194:197], 0
	v_mfma_f32_16x16x32_bf16 v[78:81], v[130:133], v[202:205], 0
	v_mfma_f32_16x16x32_bf16 v[74:77], v[148:151], v[202:205], 0
	v_mfma_f32_16x16x32_bf16 v[126:129], v[134:137], v[182:185], v[126:129]
	v_mfma_f32_16x16x32_bf16 v[122:125], v[152:155], v[182:185], v[122:125]
	v_mfma_f32_16x16x32_bf16 v[110:113], v[134:137], v[190:193], v[110:113]
	v_mfma_f32_16x16x32_bf16 v[106:109], v[152:155], v[190:193], v[106:109]
	v_mfma_f32_16x16x32_bf16 v[94:97], v[134:137], v[198:201], v[94:97]
	v_mfma_f32_16x16x32_bf16 v[90:93], v[152:155], v[198:201], v[90:93]
	v_mfma_f32_16x16x32_bf16 v[78:81], v[134:137], v[206:209], v[78:81]
	v_mfma_f32_16x16x32_bf16 v[74:77], v[152:155], v[206:209], v[74:77]
	v_mfma_f32_16x16x32_bf16 v[118:121], v[162:165], v[178:181], 0
	v_mfma_f32_16x16x32_bf16 v[114:117], v[170:173], v[178:181], 0
	v_mfma_f32_16x16x32_bf16 v[102:105], v[162:165], v[186:189], 0
	v_mfma_f32_16x16x32_bf16 v[98:101], v[170:173], v[186:189], 0
	v_mfma_f32_16x16x32_bf16 v[86:89], v[162:165], v[194:197], 0
	v_mfma_f32_16x16x32_bf16 v[82:85], v[170:173], v[194:197], 0
	v_mfma_f32_16x16x32_bf16 v[70:73], v[162:165], v[202:205], 0
	v_mfma_f32_16x16x32_bf16 v[66:69], v[170:173], v[202:205], 0
	v_mfma_f32_16x16x32_bf16 v[118:121], v[166:169], v[182:185], v[118:121]
	v_mfma_f32_16x16x32_bf16 v[114:117], v[174:177], v[182:185], v[114:117]
	v_mfma_f32_16x16x32_bf16 v[102:105], v[166:169], v[190:193], v[102:105]
	v_mfma_f32_16x16x32_bf16 v[98:101], v[174:177], v[190:193], v[98:101]
	v_mfma_f32_16x16x32_bf16 v[86:89], v[166:169], v[198:201], v[86:89]
	v_mfma_f32_16x16x32_bf16 v[82:85], v[174:177], v[198:201], v[82:85]
	v_mfma_f32_16x16x32_bf16 v[70:73], v[166:169], v[206:209], v[70:73]
	v_mfma_f32_16x16x32_bf16 v[66:69], v[174:177], v[206:209], v[66:69]
	s_barrier
	s_setprio 0
	s_add_i32 s83, s83, s38
	v_lshl_add_u64 v[210:211], s[16:17], 0, v[16:17]
	s_mov_b32 m0, s83
	ds_read_b128 v[178:181], v161 offset:16384
	ds_read_b128 v[182:185], v161 offset:17408
	ds_read_b128 v[186:189], v161 offset:18432
	ds_read_b128 v[190:193], v161 offset:19456
	ds_read_b128 v[194:197], v161 offset:20480
	ds_read_b128 v[198:201], v161 offset:21504
	ds_read_b128 v[202:205], v161 offset:22528
	ds_read_b128 v[206:209], v161 offset:23552
	global_load_lds_dwordx4 v[210:211], off
	s_add_i32 m0, s83, 0x2000
	s_add_u32 s90, s16, 0x4000
	v_lshl_add_u64 v[210:211], s[16:17], 0, v[138:139]
	s_addc_u32 s91, s17, 0
	s_add_i32 s83, s94, s38
	global_load_lds_dwordx4 v[210:211], off
	v_lshl_add_u64 v[210:211], s[90:91], 0, v[16:17]
	s_mov_b32 m0, s83
	s_nop 0
	global_load_lds_dwordx4 v[210:211], off
	v_lshl_add_u64 v[210:211], s[90:91], 0, v[138:139]
	s_add_i32 m0, s83, 0x2000
	s_nop 0
	global_load_lds_dwordx4 v[210:211], off
	v_lshl_add_u64 v[210:211], s[36:37], 0, v[142:143]
	s_mov_b32 m0, s39
	s_nop 0
	global_load_lds_dwordx4 v[210:211], off
	v_lshl_add_u64 v[210:211], s[36:37], 0, v[140:141]
	s_mov_b32 m0, s40
	s_nop 0
	global_load_lds_dwordx4 v[210:211], off
	s_waitcnt vmcnt(8)
	s_waitcnt lgkmcnt(0)
	s_nop 0
	s_setprio 1
	s_barrier
; #define PG8_STAGEA(bufoff, gbase, voff) PG8_STAGE_X(bufoff, gbase, voff, AUXA)
; #define PG8_LDA(dst, b, h) do { _Pragma("unroll") for (int m = 0; m < 4; ++m) _Pragma("unroll") for (int k = 0; k < 2; ++k) dst[m][k] = *(const PG8_LAS bf16x8*)(lds + PG8_SA(b, h) + aoff + m * 2048 + k * 1024); } while (0)
; #define PG8_LDB(dst, b, h) do { _Pragma("unroll") for (int n = 0; n < 2; ++n) _Pragma("unroll") for (int k = 0; k < 2; ++k) dst[n][k] = *(const PG8_LAS bf16x8*)(lds + PG8_SB(b, h) + boff + n * 2048 + k * 1024); } while (0)
; #define PG8_MMA(ai, bj, At, Bt) do { if (GEMM_PRIO_MODE == 0) __builtin_amdgcn_s_setprio(1); PG8_MMA_LOOPS \
;         acc[ai][bj][m][n] = __builtin_amdgcn_mfma_f32_16x16x32_bf16(Bt[n][k], At[m][k], acc[ai][bj][m][n], 0, 0, 0); if (GEMM_PRIO_MODE == 0) __builtin_amdgcn_s_setprio(0); } while (0)
; #define PG8_WAIT_V(n) asm volatile("s_waitcnt vmcnt(" #n ")" ::: "memory")
; #define PG8_WAIT_L(n) asm volatile("s_waitcnt lgkmcnt(" #n ")" ::: "memory")
; #define PG8_BAR __builtin_amdgcn_s_barrier()
; #define PG8_SCHED __builtin_amdgcn_sched_barrier(0)
;     ...
;             PG8_WAIT_V(8); PG8_WAIT_L(0); PG8_BAR; PG8_MMA(1, 0, At, B0); PG8_MMA(1, 1, At, B1); PG8_BAR; PG8_SCHED;
;     ...
;             PG8_LDB(B0, 1, 0); PG8_LDB(B1, 1, 1); PG8_SCHED; PG8_LDA(At, 1, 0); PG8_STAGEA(PG8_SA(0, 1), a2 + hstepA, voffA);
;             PG8_WAIT_V(8); PG8_WAIT_L(0); PG8_BAR; PG8_MMA(0, 0, At, B0); PG8_MMA(0, 1, At, B1); PG8_BAR; PG8_SCHED;
	v_mfma_f32_16x16x32_bf16 v[62:65], v[130:133], v[178:181], 0
	v_mfma_f32_16x16x32_bf16 v[58:61], v[148:151], v[178:181], 0
	v_mfma_f32_16x16x32_bf16 v[46:49], v[130:133], v[186:189], 0
	v_mfma_f32_16x16x32_bf16 v[42:45], v[148:151], v[186:189], 0
	v_mfma_f32_16x16x32_bf16 v[30:33], v[130:133], v[194:197], 0
	v_mfma_f32_16x16x32_bf16 v[26:29], v[148:151], v[194:197], 0
	v_mfma_f32_16x16x32_bf16 v[12:15], v[130:133], v[202:205], 0
	v_mfma_f32_16x16x32_bf16 v[8:11], v[148:151], v[202:205], 0
	v_mfma_f32_16x16x32_bf16 v[62:65], v[134:137], v[182:185], v[62:65]
	v_mfma_f32_16x16x32_bf16 v[58:61], v[152:155], v[182:185], v[58:61]
	v_mfma_f32_16x16x32_bf16 v[46:49], v[134:137], v[190:193], v[46:49]
	v_mfma_f32_16x16x32_bf16 v[42:45], v[152:155], v[190:193], v[42:45]
	v_mfma_f32_16x16x32_bf16 v[30:33], v[134:137], v[198:201], v[30:33]
	v_mfma_f32_16x16x32_bf16 v[26:29], v[152:155], v[198:201], v[26:29]
	v_mfma_f32_16x16x32_bf16 v[12:15], v[134:137], v[206:209], v[12:15]
	v_mfma_f32_16x16x32_bf16 v[8:11], v[152:155], v[206:209], v[8:11]
	v_mfma_f32_16x16x32_bf16 v[54:57], v[162:165], v[178:181], 0
	v_mfma_f32_16x16x32_bf16 v[50:53], v[170:173], v[178:181], 0
	v_mfma_f32_16x16x32_bf16 v[38:41], v[162:165], v[186:189], 0
	v_mfma_f32_16x16x32_bf16 v[34:37], v[170:173], v[186:189], 0
	v_mfma_f32_16x16x32_bf16 v[22:25], v[162:165], v[194:197], 0
	v_mfma_f32_16x16x32_bf16 v[18:21], v[170:173], v[194:197], 0
	v_mfma_f32_16x16x32_bf16 v[4:7], v[162:165], v[202:205], 0
	v_mfma_f32_16x16x32_bf16 v[0:3], v[170:173], v[202:205], 0
	v_mfma_f32_16x16x32_bf16 v[54:57], v[166:169], v[182:185], v[54:57]
	v_mfma_f32_16x16x32_bf16 v[50:53], v[174:177], v[182:185], v[50:53]
	v_mfma_f32_16x16x32_bf16 v[38:41], v[166:169], v[190:193], v[38:41]
	v_mfma_f32_16x16x32_bf16 v[34:37], v[174:177], v[190:193], v[34:37]
	v_mfma_f32_16x16x32_bf16 v[22:25], v[166:169], v[198:201], v[22:25]
	v_mfma_f32_16x16x32_bf16 v[18:21], v[174:177], v[198:201], v[18:21]
	v_mfma_f32_16x16x32_bf16 v[4:7], v[166:169], v[206:209], v[4:7]
	v_mfma_f32_16x16x32_bf16 v[0:3], v[174:177], v[206:209], v[0:3]
	s_barrier
	s_setprio 0
	s_add_i32 s83, 0, 0x18000
	s_add_i32 s90, 0, 0x1c000
	v_add_u32_e32 v152, s83, v157
	v_add_u32_e32 v174, s90, v157
	ds_read_b128 v[130:133], v152
	ds_read_b128 v[134:137], v152 offset:1024
	ds_read_b128 v[148:151], v152 offset:2048
	ds_read_b128 v[152:155], v152 offset:3072
	ds_read_b128 v[162:165], v174
	ds_read_b128 v[166:169], v174 offset:1024
	ds_read_b128 v[170:173], v174 offset:2048
	ds_read_b128 v[174:177], v174 offset:3072
	s_add_u32 s36, s36, 0x4000
	s_addc_u32 s37, s37, 0
	s_mov_b32 m0, s41
	v_lshl_add_u64 v[210:211], s[36:37], 0, v[142:143]
	ds_read_b128 v[178:181], v161 offset:32768
	ds_read_b128 v[182:185], v161 offset:33792
	ds_read_b128 v[186:189], v161 offset:34816
	ds_read_b128 v[190:193], v161 offset:35840
	ds_read_b128 v[194:197], v161 offset:36864
	ds_read_b128 v[198:201], v161 offset:37888
	ds_read_b128 v[202:205], v161 offset:38912
	ds_read_b128 v[206:209], v161 offset:39936
	global_load_lds_dwordx4 v[210:211], off
	v_lshl_add_u64 v[210:211], s[36:37], 0, v[140:141]
	s_mov_b32 m0, s42
	s_nop 0
	global_load_lds_dwordx4 v[210:211], off
	s_waitcnt vmcnt(8)
	s_waitcnt lgkmcnt(0)
	s_nop 0
	s_nop 0
	s_nop 0
	s_nop 0
	s_nop 0
	s_nop 0
	s_setprio 1
	s_barrier
	v_mfma_f32_16x16x32_bf16 v[126:129], v[130:133], v[178:181], v[126:129]
	v_mfma_f32_16x16x32_bf16 v[122:125], v[148:151], v[178:181], v[122:125]
	v_mfma_f32_16x16x32_bf16 v[110:113], v[130:133], v[186:189], v[110:113]
	v_mfma_f32_16x16x32_bf16 v[106:109], v[148:151], v[186:189], v[106:109]
	v_mfma_f32_16x16x32_bf16 v[94:97], v[130:133], v[194:197], v[94:97]
	v_mfma_f32_16x16x32_bf16 v[90:93], v[148:151], v[194:197], v[90:93]
	v_mfma_f32_16x16x32_bf16 v[78:81], v[130:133], v[202:205], v[78:81]
	v_mfma_f32_16x16x32_bf16 v[74:77], v[148:151], v[202:205], v[74:77]
	v_mfma_f32_16x16x32_bf16 v[126:129], v[134:137], v[182:185], v[126:129]
	v_mfma_f32_16x16x32_bf16 v[122:125], v[152:155], v[182:185], v[122:125]
	v_mfma_f32_16x16x32_bf16 v[110:113], v[134:137], v[190:193], v[110:113]
	v_mfma_f32_16x16x32_bf16 v[106:109], v[152:155], v[190:193], v[106:109]
	v_mfma_f32_16x16x32_bf16 v[94:97], v[134:137], v[198:201], v[94:97]
	v_mfma_f32_16x16x32_bf16 v[90:93], v[152:155], v[198:201], v[90:93]
	v_mfma_f32_16x16x32_bf16 v[78:81], v[134:137], v[206:209], v[78:81]
	v_mfma_f32_16x16x32_bf16 v[74:77], v[152:155], v[206:209], v[74:77]
	v_mfma_f32_16x16x32_bf16 v[118:121], v[162:165], v[178:181], v[118:121]
	v_mfma_f32_16x16x32_bf16 v[114:117], v[170:173], v[178:181], v[114:117]
	v_mfma_f32_16x16x32_bf16 v[102:105], v[162:165], v[186:189], v[102:105]
	v_mfma_f32_16x16x32_bf16 v[98:101], v[170:173], v[186:189], v[98:101]
	v_mfma_f32_16x16x32_bf16 v[86:89], v[162:165], v[194:197], v[86:89]
	v_mfma_f32_16x16x32_bf16 v[82:85], v[170:173], v[194:197], v[82:85]
	v_mfma_f32_16x16x32_bf16 v[70:73], v[162:165], v[202:205], v[70:73]
	v_mfma_f32_16x16x32_bf16 v[66:69], v[170:173], v[202:205], v[66:69]
	v_mfma_f32_16x16x32_bf16 v[118:121], v[166:169], v[182:185], v[118:121]
	v_mfma_f32_16x16x32_bf16 v[114:117], v[174:177], v[182:185], v[114:117]
	v_mfma_f32_16x16x32_bf16 v[102:105], v[166:169], v[190:193], v[102:105]
	v_mfma_f32_16x16x32_bf16 v[98:101], v[174:177], v[190:193], v[98:101]
	v_mfma_f32_16x16x32_bf16 v[86:89], v[166:169], v[198:201], v[86:89]
	v_mfma_f32_16x16x32_bf16 v[82:85], v[174:177], v[198:201], v[82:85]
	v_mfma_f32_16x16x32_bf16 v[70:73], v[166:169], v[206:209], v[70:73]
	v_mfma_f32_16x16x32_bf16 v[66:69], v[174:177], v[206:209], v[66:69]
	s_barrier
; #define PG8_STAGEA(bufoff, gbase, voff) PG8_STAGE_X(bufoff, gbase, voff, AUXA)
; #define PG8_STAGEB(bufoff, gbase, voff) PG8_STAGE_X(bufoff, gbase, voff, AUXB)
; #define PG8_LDA(dst, b, h) do { _Pragma("unroll") for (int m = 0; m < 4; ++m) _Pragma("unroll") for (int k = 0; k < 2; ++k) dst[m][k] = *(const PG8_LAS bf16x8*)(lds + PG8_SA(b, h) + aoff + m * 2048 + k * 1024); } while (0)
; #define PG8_LDB(dst, b, h) do { _Pragma("unroll") for (int n = 0; n < 2; ++n) _Pragma("unroll") for (int k = 0; k < 2; ++k) dst[n][k] = *(const PG8_LAS bf16x8*)(lds + PG8_SB(b, h) + boff + n * 2048 + k * 1024); } while (0)
; #define PG8_MMA(ai, bj, At, Bt) do { if (GEMM_PRIO_MODE == 0) __builtin_amdgcn_s_setprio(1); PG8_MMA_LOOPS \
;         acc[ai][bj][m][n] = __builtin_amdgcn_mfma_f32_16x16x32_bf16(Bt[n][k], At[m][k], acc[ai][bj][m][n], 0, 0, 0); if (GEMM_PRIO_MODE == 0) __builtin_amdgcn_s_setprio(0); } while (0)
; #define PG8_WAIT_V(n) asm volatile("s_waitcnt vmcnt(" #n ")" ::: "memory")
; #define PG8_WAIT_VR(n, nr, flag) asm volatile("s_cmp_eq_u32 %0, 0\n\ts_cbranch_scc1 .Lpg8s%=\n\ts_waitcnt vmcnt(" #nr ")\n\ts_branch .Lpg8d%=\n.Lpg8s%=:\n\ts_waitcnt vmcnt(" #n ")\n.Lpg8d%=:" :: "s"(flag) : "memory", "scc")
;     ...
;             const bool last = (t == nt - 2);
;             const char* a1 = cA + (size_t)(t + 1) * kstepA;
;             const char* a2 = last ? nA : cA + (size_t)(t + 2) * kstepA; const char* b2 = last ? nB : cB + (size_t)(t + 2) * kstepB;
;             const char* a3 = a2 + kstepA; const char* b3 = b2 + kstepB;
;             if (last && has_next) S.a_ready(nxt);
;             if constexpr (SP2) {
;             PG8_LDB(B0, 0, 0); PG8_LDB(B1, 0, 1); PG8_SCHED; PG8_LDA(At, 0, 0); PG8_STAGEA(PG8_SA(1, 1), a1 + hstepA, voffA);
;     ...
;             const int relax = __builtin_amdgcn_readfirstlane((t == 0 && ui > 0) ? 1 : 0);
;             PG8_WAIT_VR(8, 24, relax); PG8_WAIT_L(0); PG8_BAR; PG8_MMA(0, 0, At, B0); PG8_MMA(0, 1, At, B1); PG8_BAR; PG8_SCHED;
;     ...
;             PG8_WAIT_V(8); PG8_WAIT_L(0); PG8_BAR; PG8_MMA(0, 0, At, B0); PG8_MMA(0, 1, At, B1); PG8_BAR; PG8_SCHED;
;     ...
;             PG8_LDA(At, 1, 1); PG8_STAGEB(PG8_SB(1, 0), b3, voffB); PG8_STAGEB(PG8_SB(1, 1), b3 + hstepB, voffB); PG8_STAGEA(PG8_SA(1, 0), a3, voffA);
;             PG8_WAIT_V(8); PG8_WAIT_L(0); PG8_BAR; PG8_MMA(1, 0, At, B0); PG8_MMA(1, 1, At, B1); PG8_BAR; PG8_SCHED;
	s_setprio 0
	s_add_u32 s36, s16, 0x8000
	s_addc_u32 s37, s17, 0
	s_add_i32 s83, s83, s38
	v_lshl_add_u64 v[210:211], s[36:37], 0, v[16:17]
	s_mov_b32 m0, s83
	ds_read_b128 v[178:181], v161 offset:49152
	ds_read_b128 v[182:185], v161 offset:50176
	ds_read_b128 v[186:189], v161 offset:51200
	ds_read_b128 v[190:193], v161 offset:52224
	ds_read_b128 v[194:197], v161 offset:53248
	ds_read_b128 v[198:201], v161 offset:54272
	ds_read_b128 v[202:205], v161 offset:55296
	ds_read_b128 v[206:209], v161 offset:56320
	global_load_lds_dwordx4 v[210:211], off
	s_add_i32 m0, s83, 0x2000
	s_add_u32 s16, s16, 0xc000
	v_lshl_add_u64 v[210:211], s[36:37], 0, v[138:139]
	s_addc_u32 s17, s17, 0
	s_add_i32 s36, s90, s38
	global_load_lds_dwordx4 v[210:211], off
	v_lshl_add_u64 v[210:211], s[16:17], 0, v[16:17]
	s_mov_b32 m0, s36
	s_nop 0
	global_load_lds_dwordx4 v[210:211], off
	v_lshl_add_u64 v[210:211], s[16:17], 0, v[138:139]
	s_add_i32 m0, s36, 0x2000
	s_nop 0
	global_load_lds_dwordx4 v[210:211], off
	v_lshl_add_u64 v[210:211], s[26:27], 0, v[142:143]
	s_mov_b32 m0, s50
	s_nop 0
	global_load_lds_dwordx4 v[210:211], off
	v_lshl_add_u64 v[210:211], s[26:27], 0, v[140:141]
	s_mov_b32 m0, s51
	s_nop 0
	global_load_lds_dwordx4 v[210:211], off
	s_waitcnt vmcnt(8)
	s_waitcnt lgkmcnt(0)
	s_nop 0
	s_nop 0
	s_nop 0
	s_nop 0
	s_nop 0
	s_nop 0
	s_nop 0
	s_nop 0
	s_nop 0
	s_nop 0
	s_nop 0
	s_nop 0
	s_nop 0
	s_nop 0
	s_setprio 1
	s_barrier
	v_mfma_f32_16x16x32_bf16 v[62:65], v[130:133], v[178:181], v[62:65]
	v_mfma_f32_16x16x32_bf16 v[58:61], v[148:151], v[178:181], v[58:61]
	v_mfma_f32_16x16x32_bf16 v[46:49], v[130:133], v[186:189], v[46:49]
	v_mfma_f32_16x16x32_bf16 v[42:45], v[148:151], v[186:189], v[42:45]
	v_mfma_f32_16x16x32_bf16 v[30:33], v[130:133], v[194:197], v[30:33]
	v_mfma_f32_16x16x32_bf16 v[26:29], v[148:151], v[194:197], v[26:29]
	v_mfma_f32_16x16x32_bf16 v[12:15], v[130:133], v[202:205], v[12:15]
	v_mfma_f32_16x16x32_bf16 v[8:11], v[148:151], v[202:205], v[8:11]
	v_mfma_f32_16x16x32_bf16 v[62:65], v[134:137], v[182:185], v[62:65]
	v_mfma_f32_16x16x32_bf16 v[58:61], v[152:155], v[182:185], v[58:61]
	v_mfma_f32_16x16x32_bf16 v[46:49], v[134:137], v[190:193], v[46:49]
	v_mfma_f32_16x16x32_bf16 v[42:45], v[152:155], v[190:193], v[42:45]
	v_mfma_f32_16x16x32_bf16 v[30:33], v[134:137], v[198:201], v[30:33]
	v_mfma_f32_16x16x32_bf16 v[26:29], v[152:155], v[198:201], v[26:29]
	v_mfma_f32_16x16x32_bf16 v[12:15], v[134:137], v[206:209], v[12:15]
	v_mfma_f32_16x16x32_bf16 v[8:11], v[152:155], v[206:209], v[8:11]
	v_mfma_f32_16x16x32_bf16 v[54:57], v[162:165], v[178:181], v[54:57]
	v_mfma_f32_16x16x32_bf16 v[50:53], v[170:173], v[178:181], v[50:53]
	v_mfma_f32_16x16x32_bf16 v[38:41], v[162:165], v[186:189], v[38:41]
	v_mfma_f32_16x16x32_bf16 v[34:37], v[170:173], v[186:189], v[34:37]
	v_mfma_f32_16x16x32_bf16 v[22:25], v[162:165], v[194:197], v[22:25]
	v_mfma_f32_16x16x32_bf16 v[18:21], v[170:173], v[194:197], v[18:21]
	v_mfma_f32_16x16x32_bf16 v[4:7], v[162:165], v[202:205], v[4:7]
	v_mfma_f32_16x16x32_bf16 v[0:3], v[170:173], v[202:205], v[0:3]
	v_mfma_f32_16x16x32_bf16 v[54:57], v[166:169], v[182:185], v[54:57]
	v_mfma_f32_16x16x32_bf16 v[50:53], v[174:177], v[182:185], v[50:53]
	v_mfma_f32_16x16x32_bf16 v[38:41], v[166:169], v[190:193], v[38:41]
	v_mfma_f32_16x16x32_bf16 v[34:37], v[174:177], v[190:193], v[34:37]
	v_mfma_f32_16x16x32_bf16 v[22:25], v[166:169], v[198:201], v[22:25]
	v_mfma_f32_16x16x32_bf16 v[18:21], v[174:177], v[198:201], v[18:21]
	v_mfma_f32_16x16x32_bf16 v[4:7], v[166:169], v[206:209], v[4:7]
	v_mfma_f32_16x16x32_bf16 v[0:3], v[174:177], v[206:209], v[0:3]
	s_barrier
	s_setprio 0
	s_add_i32 s82, s82, 2
	s_add_u32 s24, s24, 0x10000
	s_addc_u32 s25, s25, 0
	s_add_u32 s0, s0, 0x10000
	s_addc_u32 s1, s1, 0
.LBB0_848:
	s_add_u32 s16, s24, 0x4000
	s_addc_u32 s17, s25, 0
	s_cmpk_eq_i32 s82, 0xfc
	s_cselect_b32 s36, s73, s16
	s_cselect_b32 s37, s11, s17
	s_cselect_b32 s16, s78, s0
	s_cselect_b32 s17, s15, s1
	s_add_u32 s26, s36, 0x8000
	s_addc_u32 s27, s37, 0
	s_add_i32 s83, 0, 0x10000
	s_add_i32 s94, 0, 0x14000
	v_add_u32_e32 v152, s83, v157
	v_add_u32_e32 v174, s94, v157
	ds_read_b128 v[130:133], v152
	ds_read_b128 v[134:137], v152 offset:1024
	ds_read_b128 v[148:151], v152 offset:2048
	ds_read_b128 v[152:155], v152 offset:3072
	ds_read_b128 v[162:165], v174
	ds_read_b128 v[166:169], v174 offset:1024
	ds_read_b128 v[170:173], v174 offset:2048
	ds_read_b128 v[174:177], v174 offset:3072
	v_lshl_add_u64 v[210:211], s[24:25], 0, v[144:145]
	s_add_i32 m0, s39, 0xc000
	ds_read_b128 v[178:181], v161
	ds_read_b128 v[182:185], v161 offset:1024
	ds_read_b128 v[186:189], v161 offset:2048
	ds_read_b128 v[190:193], v161 offset:3072
	ds_read_b128 v[194:197], v161 offset:4096
	ds_read_b128 v[198:201], v161 offset:5120
	ds_read_b128 v[202:205], v161 offset:6144
	ds_read_b128 v[206:209], v161 offset:7168
	global_load_lds_dwordx4 v[210:211], off
	v_lshl_add_u64 v[210:211], s[24:25], 0, v[146:147]
	s_add_i32 m0, s39, 0xe000
	s_nop 0
	global_load_lds_dwordx4 v[210:211], off
	s_waitcnt vmcnt(8)
	s_waitcnt lgkmcnt(0)
	s_nop 0
	s_nop 0
	s_nop 0
	s_nop 0
	s_nop 0
	s_setprio 1
	s_barrier
; #define PG8_STAGEA(bufoff, gbase, voff) PG8_STAGE_X(bufoff, gbase, voff, AUXA)
; #define PG8_STAGEB(bufoff, gbase, voff) PG8_STAGE_X(bufoff, gbase, voff, AUXB)
; #define PG8_LDA(dst, b, h) do { _Pragma("unroll") for (int m = 0; m < 4; ++m) _Pragma("unroll") for (int k = 0; k < 2; ++k) dst[m][k] = *(const PG8_LAS bf16x8*)(lds + PG8_SA(b, h) + aoff + m * 2048 + k * 1024); } while (0)
; #define PG8_MMA(ai, bj, At, Bt) do { if (GEMM_PRIO_MODE == 0) __builtin_amdgcn_s_setprio(1); PG8_MMA_LOOPS \
;         acc[ai][bj][m][n] = __builtin_amdgcn_mfma_f32_16x16x32_bf16(Bt[n][k], At[m][k], acc[ai][bj][m][n], 0, 0, 0); if (GEMM_PRIO_MODE == 0) __builtin_amdgcn_s_setprio(0); } while (0)
; #define PG8_WAIT_V(n) asm volatile("s_waitcnt vmcnt(" #n ")" ::: "memory")
; #define PG8_WAIT_VR(n, nr, flag) asm volatile("s_cmp_eq_u32 %0, 0\n\ts_cbranch_scc1 .Lpg8s%=\n\ts_waitcnt vmcnt(" #nr ")\n\ts_branch .Lpg8d%=\n.Lpg8s%=:\n\ts_waitcnt vmcnt(" #n ")\n.Lpg8d%=:" :: "s"(flag) : "memory", "scc")
; #define PG8_WAIT_L(n) asm volatile("s_waitcnt lgkmcnt(" #n ")" ::: "memory")
; #define PG8_BAR __builtin_amdgcn_s_barrier()
; #define PG8_SCHED __builtin_amdgcn_sched_barrier(0)
;     ...
;             PG8_WAIT_V(8); PG8_WAIT_L(0); PG8_BAR; PG8_MMA(0, 0, At, B0); PG8_MMA(0, 1, At, B1); PG8_BAR; PG8_SCHED;
;     ...
;             PG8_LDA(At, 0, 1); PG8_STAGEB(PG8_SB(0, 0), b2, voffB); PG8_STAGEB(PG8_SB(0, 1), b2 + hstepB, voffB); PG8_STAGEA(PG8_SA(0, 0), a2, voffA);
;     ...
;             PG8_WAIT_VR(8, 24, relax); PG8_WAIT_L(0); PG8_BAR; PG8_MMA(1, 0, At, B0); PG8_MMA(1, 1, At, B1); PG8_BAR; PG8_SCHED;
;     ...
;             PG8_WAIT_V(8); PG8_WAIT_L(0); PG8_BAR; PG8_MMA(1, 0, At, B0); PG8_MMA(1, 1, At, B1); PG8_BAR; PG8_SCHED;
	v_mfma_f32_16x16x32_bf16 v[126:129], v[130:133], v[178:181], v[126:129]
	v_mfma_f32_16x16x32_bf16 v[122:125], v[148:151], v[178:181], v[122:125]
	v_mfma_f32_16x16x32_bf16 v[110:113], v[130:133], v[186:189], v[110:113]
	v_mfma_f32_16x16x32_bf16 v[106:109], v[148:151], v[186:189], v[106:109]
	v_mfma_f32_16x16x32_bf16 v[94:97], v[130:133], v[194:197], v[94:97]
	v_mfma_f32_16x16x32_bf16 v[90:93], v[148:151], v[194:197], v[90:93]
	v_mfma_f32_16x16x32_bf16 v[78:81], v[130:133], v[202:205], v[78:81]
	v_mfma_f32_16x16x32_bf16 v[74:77], v[148:151], v[202:205], v[74:77]
	v_mfma_f32_16x16x32_bf16 v[126:129], v[134:137], v[182:185], v[126:129]
	v_mfma_f32_16x16x32_bf16 v[122:125], v[152:155], v[182:185], v[122:125]
	v_mfma_f32_16x16x32_bf16 v[110:113], v[134:137], v[190:193], v[110:113]
	v_mfma_f32_16x16x32_bf16 v[106:109], v[152:155], v[190:193], v[106:109]
	v_mfma_f32_16x16x32_bf16 v[94:97], v[134:137], v[198:201], v[94:97]
	v_mfma_f32_16x16x32_bf16 v[90:93], v[152:155], v[198:201], v[90:93]
	v_mfma_f32_16x16x32_bf16 v[78:81], v[134:137], v[206:209], v[78:81]
	v_mfma_f32_16x16x32_bf16 v[74:77], v[152:155], v[206:209], v[74:77]
	v_mfma_f32_16x16x32_bf16 v[118:121], v[162:165], v[178:181], v[118:121]
	v_mfma_f32_16x16x32_bf16 v[114:117], v[170:173], v[178:181], v[114:117]
	v_mfma_f32_16x16x32_bf16 v[102:105], v[162:165], v[186:189], v[102:105]
	v_mfma_f32_16x16x32_bf16 v[98:101], v[170:173], v[186:189], v[98:101]
	v_mfma_f32_16x16x32_bf16 v[86:89], v[162:165], v[194:197], v[86:89]
	v_mfma_f32_16x16x32_bf16 v[82:85], v[170:173], v[194:197], v[82:85]
	v_mfma_f32_16x16x32_bf16 v[70:73], v[162:165], v[202:205], v[70:73]
	v_mfma_f32_16x16x32_bf16 v[66:69], v[170:173], v[202:205], v[66:69]
	v_mfma_f32_16x16x32_bf16 v[118:121], v[166:169], v[182:185], v[118:121]
	v_mfma_f32_16x16x32_bf16 v[114:117], v[174:177], v[182:185], v[114:117]
	v_mfma_f32_16x16x32_bf16 v[102:105], v[166:169], v[190:193], v[102:105]
	v_mfma_f32_16x16x32_bf16 v[98:101], v[174:177], v[190:193], v[98:101]
	v_mfma_f32_16x16x32_bf16 v[86:89], v[166:169], v[198:201], v[86:89]
	v_mfma_f32_16x16x32_bf16 v[82:85], v[174:177], v[198:201], v[82:85]
	v_mfma_f32_16x16x32_bf16 v[70:73], v[166:169], v[206:209], v[70:73]
	v_mfma_f32_16x16x32_bf16 v[66:69], v[174:177], v[206:209], v[66:69]
	s_barrier
	s_setprio 0
	s_add_i32 s83, s83, s38
	v_lshl_add_u64 v[210:211], s[16:17], 0, v[16:17]
	s_mov_b32 m0, s83
	ds_read_b128 v[178:181], v161 offset:16384
	ds_read_b128 v[182:185], v161 offset:17408
	ds_read_b128 v[186:189], v161 offset:18432
	ds_read_b128 v[190:193], v161 offset:19456
	ds_read_b128 v[194:197], v161 offset:20480
	ds_read_b128 v[198:201], v161 offset:21504
	ds_read_b128 v[202:205], v161 offset:22528
	ds_read_b128 v[206:209], v161 offset:23552
	global_load_lds_dwordx4 v[210:211], off
	s_add_i32 m0, s83, 0x2000
	s_add_u32 s90, s16, 0x4000
	v_lshl_add_u64 v[210:211], s[16:17], 0, v[138:139]
	s_addc_u32 s91, s17, 0
	s_add_i32 s83, s94, s38
	global_load_lds_dwordx4 v[210:211], off
	v_lshl_add_u64 v[210:211], s[90:91], 0, v[16:17]
	s_mov_b32 m0, s83
	s_nop 0
	global_load_lds_dwordx4 v[210:211], off
	v_lshl_add_u64 v[210:211], s[90:91], 0, v[138:139]
	s_add_i32 m0, s83, 0x2000
	s_nop 0
	global_load_lds_dwordx4 v[210:211], off
	v_lshl_add_u64 v[210:211], s[36:37], 0, v[142:143]
	s_mov_b32 m0, s39
	s_nop 0
	global_load_lds_dwordx4 v[210:211], off
	v_lshl_add_u64 v[210:211], s[36:37], 0, v[140:141]
	s_mov_b32 m0, s40
	s_nop 0
	global_load_lds_dwordx4 v[210:211], off
	s_waitcnt vmcnt(8)
	s_waitcnt lgkmcnt(0)
	s_nop 0
	s_setprio 1
	s_barrier
	v_mfma_f32_16x16x32_bf16 v[62:65], v[130:133], v[178:181], v[62:65]
	v_mfma_f32_16x16x32_bf16 v[58:61], v[148:151], v[178:181], v[58:61]
	v_mfma_f32_16x16x32_bf16 v[46:49], v[130:133], v[186:189], v[46:49]
	v_mfma_f32_16x16x32_bf16 v[42:45], v[148:151], v[186:189], v[42:45]
	v_mfma_f32_16x16x32_bf16 v[30:33], v[130:133], v[194:197], v[30:33]
	v_mfma_f32_16x16x32_bf16 v[26:29], v[148:151], v[194:197], v[26:29]
	v_mfma_f32_16x16x32_bf16 v[12:15], v[130:133], v[202:205], v[12:15]
	v_mfma_f32_16x16x32_bf16 v[8:11], v[148:151], v[202:205], v[8:11]
	v_mfma_f32_16x16x32_bf16 v[62:65], v[134:137], v[182:185], v[62:65]
	v_mfma_f32_16x16x32_bf16 v[58:61], v[152:155], v[182:185], v[58:61]
	v_mfma_f32_16x16x32_bf16 v[46:49], v[134:137], v[190:193], v[46:49]
	v_mfma_f32_16x16x32_bf16 v[42:45], v[152:155], v[190:193], v[42:45]
	v_mfma_f32_16x16x32_bf16 v[30:33], v[134:137], v[198:201], v[30:33]
	v_mfma_f32_16x16x32_bf16 v[26:29], v[152:155], v[198:201], v[26:29]
	v_mfma_f32_16x16x32_bf16 v[12:15], v[134:137], v[206:209], v[12:15]
	v_mfma_f32_16x16x32_bf16 v[8:11], v[152:155], v[206:209], v[8:11]
	v_mfma_f32_16x16x32_bf16 v[54:57], v[162:165], v[178:181], v[54:57]
	v_mfma_f32_16x16x32_bf16 v[50:53], v[170:173], v[178:181], v[50:53]
	v_mfma_f32_16x16x32_bf16 v[38:41], v[162:165], v[186:189], v[38:41]
	v_mfma_f32_16x16x32_bf16 v[34:37], v[170:173], v[186:189], v[34:37]
	v_mfma_f32_16x16x32_bf16 v[22:25], v[162:165], v[194:197], v[22:25]
	v_mfma_f32_16x16x32_bf16 v[18:21], v[170:173], v[194:197], v[18:21]
	v_mfma_f32_16x16x32_bf16 v[4:7], v[162:165], v[202:205], v[4:7]
	v_mfma_f32_16x16x32_bf16 v[0:3], v[170:173], v[202:205], v[0:3]
	v_mfma_f32_16x16x32_bf16 v[54:57], v[166:169], v[182:185], v[54:57]
	v_mfma_f32_16x16x32_bf16 v[50:53], v[174:177], v[182:185], v[50:53]
	v_mfma_f32_16x16x32_bf16 v[38:41], v[166:169], v[190:193], v[38:41]
	v_mfma_f32_16x16x32_bf16 v[34:37], v[174:177], v[190:193], v[34:37]
	v_mfma_f32_16x16x32_bf16 v[22:25], v[166:169], v[198:201], v[22:25]
	v_mfma_f32_16x16x32_bf16 v[18:21], v[174:177], v[198:201], v[18:21]
	v_mfma_f32_16x16x32_bf16 v[4:7], v[166:169], v[206:209], v[4:7]
	v_mfma_f32_16x16x32_bf16 v[0:3], v[174:177], v[206:209], v[0:3]
	s_barrier
; #define PG8_STAGEA(bufoff, gbase, voff) PG8_STAGE_X(bufoff, gbase, voff, AUXA)
; #define PG8_LDA(dst, b, h) do { _Pragma("unroll") for (int m = 0; m < 4; ++m) _Pragma("unroll") for (int k = 0; k < 2; ++k) dst[m][k] = *(const PG8_LAS bf16x8*)(lds + PG8_SA(b, h) + aoff + m * 2048 + k * 1024); } while (0)
; #define PG8_LDB(dst, b, h) do { _Pragma("unroll") for (int n = 0; n < 2; ++n) _Pragma("unroll") for (int k = 0; k < 2; ++k) dst[n][k] = *(const PG8_LAS bf16x8*)(lds + PG8_SB(b, h) + boff + n * 2048 + k * 1024); } while (0)
; #define PG8_MMA(ai, bj, At, Bt) do { if (GEMM_PRIO_MODE == 0) __builtin_amdgcn_s_setprio(1); PG8_MMA_LOOPS \
;         acc[ai][bj][m][n] = __builtin_amdgcn_mfma_f32_16x16x32_bf16(Bt[n][k], At[m][k], acc[ai][bj][m][n], 0, 0, 0); if (GEMM_PRIO_MODE == 0) __builtin_amdgcn_s_setprio(0); } while (0)
; #define PG8_WAIT_V(n) asm volatile("s_waitcnt vmcnt(" #n ")" ::: "memory")
; #define PG8_WAIT_L(n) asm volatile("s_waitcnt lgkmcnt(" #n ")" ::: "memory")
; #define PG8_BAR __builtin_amdgcn_s_barrier()
; #define PG8_SCHED __builtin_amdgcn_sched_barrier(0)
;     ...
;             PG8_LDB(B0, 1, 0); PG8_LDB(B1, 1, 1); PG8_SCHED; PG8_LDA(At, 1, 0); PG8_STAGEA(PG8_SA(0, 1), a2 + hstepA, voffA);
;             PG8_WAIT_V(8); PG8_WAIT_L(0); PG8_BAR; PG8_MMA(0, 0, At, B0); PG8_MMA(0, 1, At, B1); PG8_BAR; PG8_SCHED;
	s_setprio 0
	s_add_i32 s83, 0, 0x18000
	s_add_i32 s90, 0, 0x1c000
	v_add_u32_e32 v152, s83, v157
	v_add_u32_e32 v174, s90, v157
	ds_read_b128 v[130:133], v152
	ds_read_b128 v[134:137], v152 offset:1024
	ds_read_b128 v[148:151], v152 offset:2048
	ds_read_b128 v[152:155], v152 offset:3072
	ds_read_b128 v[162:165], v174
	ds_read_b128 v[166:169], v174 offset:1024
	ds_read_b128 v[170:173], v174 offset:2048
	ds_read_b128 v[174:177], v174 offset:3072
	s_add_u32 s36, s36, 0x4000
	s_addc_u32 s37, s37, 0
	s_mov_b32 m0, s41
	v_lshl_add_u64 v[210:211], s[36:37], 0, v[142:143]
	ds_read_b128 v[178:181], v161 offset:32768
	ds_read_b128 v[182:185], v161 offset:33792
	ds_read_b128 v[186:189], v161 offset:34816
	ds_read_b128 v[190:193], v161 offset:35840
	ds_read_b128 v[194:197], v161 offset:36864
	ds_read_b128 v[198:201], v161 offset:37888
	ds_read_b128 v[202:205], v161 offset:38912
	ds_read_b128 v[206:209], v161 offset:39936
	global_load_lds_dwordx4 v[210:211], off
	v_lshl_add_u64 v[210:211], s[36:37], 0, v[140:141]
	s_mov_b32 m0, s42
	s_nop 0
	global_load_lds_dwordx4 v[210:211], off
	s_waitcnt vmcnt(8)
	s_waitcnt lgkmcnt(0)
	s_nop 0
	s_nop 0
	s_nop 0
	s_nop 0
	s_nop 0
	s_nop 0
	s_setprio 1
	s_barrier
	v_mfma_f32_16x16x32_bf16 v[126:129], v[130:133], v[178:181], v[126:129]
	v_mfma_f32_16x16x32_bf16 v[122:125], v[148:151], v[178:181], v[122:125]
	v_mfma_f32_16x16x32_bf16 v[110:113], v[130:133], v[186:189], v[110:113]
	v_mfma_f32_16x16x32_bf16 v[106:109], v[148:151], v[186:189], v[106:109]
	v_mfma_f32_16x16x32_bf16 v[94:97], v[130:133], v[194:197], v[94:97]
	v_mfma_f32_16x16x32_bf16 v[90:93], v[148:151], v[194:197], v[90:93]
	v_mfma_f32_16x16x32_bf16 v[78:81], v[130:133], v[202:205], v[78:81]
	v_mfma_f32_16x16x32_bf16 v[74:77], v[148:151], v[202:205], v[74:77]
	v_mfma_f32_16x16x32_bf16 v[126:129], v[134:137], v[182:185], v[126:129]
	v_mfma_f32_16x16x32_bf16 v[122:125], v[152:155], v[182:185], v[122:125]
	v_mfma_f32_16x16x32_bf16 v[110:113], v[134:137], v[190:193], v[110:113]
	v_mfma_f32_16x16x32_bf16 v[106:109], v[152:155], v[190:193], v[106:109]
	v_mfma_f32_16x16x32_bf16 v[94:97], v[134:137], v[198:201], v[94:97]
	v_mfma_f32_16x16x32_bf16 v[90:93], v[152:155], v[198:201], v[90:93]
	v_mfma_f32_16x16x32_bf16 v[78:81], v[134:137], v[206:209], v[78:81]
	v_mfma_f32_16x16x32_bf16 v[74:77], v[152:155], v[206:209], v[74:77]
	v_mfma_f32_16x16x32_bf16 v[118:121], v[162:165], v[178:181], v[118:121]
	v_mfma_f32_16x16x32_bf16 v[114:117], v[170:173], v[178:181], v[114:117]
	v_mfma_f32_16x16x32_bf16 v[102:105], v[162:165], v[186:189], v[102:105]
	v_mfma_f32_16x16x32_bf16 v[98:101], v[170:173], v[186:189], v[98:101]
	v_mfma_f32_16x16x32_bf16 v[86:89], v[162:165], v[194:197], v[86:89]
	v_mfma_f32_16x16x32_bf16 v[82:85], v[170:173], v[194:197], v[82:85]
	v_mfma_f32_16x16x32_bf16 v[70:73], v[162:165], v[202:205], v[70:73]
	v_mfma_f32_16x16x32_bf16 v[66:69], v[170:173], v[202:205], v[66:69]
	v_mfma_f32_16x16x32_bf16 v[118:121], v[166:169], v[182:185], v[118:121]
	v_mfma_f32_16x16x32_bf16 v[114:117], v[174:177], v[182:185], v[114:117]
	v_mfma_f32_16x16x32_bf16 v[102:105], v[166:169], v[190:193], v[102:105]
	v_mfma_f32_16x16x32_bf16 v[98:101], v[174:177], v[190:193], v[98:101]
	v_mfma_f32_16x16x32_bf16 v[86:89], v[166:169], v[198:201], v[86:89]
	v_mfma_f32_16x16x32_bf16 v[82:85], v[174:177], v[198:201], v[82:85]
	v_mfma_f32_16x16x32_bf16 v[70:73], v[166:169], v[206:209], v[70:73]
	v_mfma_f32_16x16x32_bf16 v[66:69], v[174:177], v[206:209], v[66:69]
	s_barrier
; #define PG8_STAGEA(bufoff, gbase, voff) PG8_STAGE_X(bufoff, gbase, voff, AUXA)
; #define PG8_STAGEB(bufoff, gbase, voff) PG8_STAGE_X(bufoff, gbase, voff, AUXB)
; #define PG8_LDA(dst, b, h) do { _Pragma("unroll") for (int m = 0; m < 4; ++m) _Pragma("unroll") for (int k = 0; k < 2; ++k) dst[m][k] = *(const PG8_LAS bf16x8*)(lds + PG8_SA(b, h) + aoff + m * 2048 + k * 1024); } while (0)
; #define PG8_MMA(ai, bj, At, Bt) do { if (GEMM_PRIO_MODE == 0) __builtin_amdgcn_s_setprio(1); PG8_MMA_LOOPS \
;         acc[ai][bj][m][n] = __builtin_amdgcn_mfma_f32_16x16x32_bf16(Bt[n][k], At[m][k], acc[ai][bj][m][n], 0, 0, 0); if (GEMM_PRIO_MODE == 0) __builtin_amdgcn_s_setprio(0); } while (0)
; #define PG8_WAIT_V(n) asm volatile("s_waitcnt vmcnt(" #n ")" ::: "memory")
; #define PG8_WAIT_L(n) asm volatile("s_waitcnt lgkmcnt(" #n ")" ::: "memory")
; #define PG8_BAR __builtin_amdgcn_s_barrier()
; #define PG8_SCHED __builtin_amdgcn_sched_barrier(0)
;     ...
;             PG8_LDA(At, 1, 1); PG8_STAGEB(PG8_SB(1, 0), b3, voffB); PG8_STAGEB(PG8_SB(1, 1), b3 + hstepB, voffB); PG8_STAGEA(PG8_SA(1, 0), a3, voffA);
;             PG8_WAIT_V(8); PG8_WAIT_L(0); PG8_BAR; PG8_MMA(1, 0, At, B0); PG8_MMA(1, 1, At, B1); PG8_BAR; PG8_SCHED;
;     ...
;         if constexpr (ALIGN_EPI) { if (wr == 0) PG8_BAR; }
	s_setprio 0
	s_add_u32 s36, s16, 0x8000
	s_addc_u32 s37, s17, 0
	s_add_i32 s83, s83, s38
	v_lshl_add_u64 v[210:211], s[36:37], 0, v[16:17]
	s_mov_b32 m0, s83
	ds_read_b128 v[178:181], v161 offset:49152
	ds_read_b128 v[182:185], v161 offset:50176
	ds_read_b128 v[186:189], v161 offset:51200
	ds_read_b128 v[190:193], v161 offset:52224
	ds_read_b128 v[194:197], v161 offset:53248
	ds_read_b128 v[198:201], v161 offset:54272
	ds_read_b128 v[202:205], v161 offset:55296
	ds_read_b128 v[206:209], v161 offset:56320
	global_load_lds_dwordx4 v[210:211], off
	s_add_i32 m0, s83, 0x2000
	s_add_u32 s16, s16, 0xc000
	v_lshl_add_u64 v[210:211], s[36:37], 0, v[138:139]
	s_addc_u32 s17, s17, 0
	s_add_i32 s36, s90, s38
	global_load_lds_dwordx4 v[210:211], off
	v_lshl_add_u64 v[210:211], s[16:17], 0, v[16:17]
	s_mov_b32 m0, s36
	s_nop 0
	global_load_lds_dwordx4 v[210:211], off
	v_lshl_add_u64 v[210:211], s[16:17], 0, v[138:139]
	s_add_i32 m0, s36, 0x2000
	s_nop 0
	global_load_lds_dwordx4 v[210:211], off
	v_lshl_add_u64 v[210:211], s[26:27], 0, v[142:143]
	s_mov_b32 m0, s50
	s_nop 0
	global_load_lds_dwordx4 v[210:211], off
	v_lshl_add_u64 v[210:211], s[26:27], 0, v[140:141]
	s_mov_b32 m0, s51
	s_nop 0
	global_load_lds_dwordx4 v[210:211], off
	s_waitcnt vmcnt(8)
	s_waitcnt lgkmcnt(0)
	s_nop 0
	s_nop 0
	s_nop 0
	s_nop 0
	s_nop 0
	s_nop 0
	s_nop 0
	s_nop 0
	s_nop 0
	s_nop 0
	s_nop 0
	s_nop 0
	s_nop 0
	s_nop 0
	s_setprio 1
	s_barrier
	v_mfma_f32_16x16x32_bf16 v[62:65], v[130:133], v[178:181], v[62:65]
	v_mfma_f32_16x16x32_bf16 v[58:61], v[148:151], v[178:181], v[58:61]
	v_mfma_f32_16x16x32_bf16 v[46:49], v[130:133], v[186:189], v[46:49]
	v_mfma_f32_16x16x32_bf16 v[42:45], v[148:151], v[186:189], v[42:45]
	v_mfma_f32_16x16x32_bf16 v[30:33], v[130:133], v[194:197], v[30:33]
	v_mfma_f32_16x16x32_bf16 v[26:29], v[148:151], v[194:197], v[26:29]
	v_mfma_f32_16x16x32_bf16 v[12:15], v[130:133], v[202:205], v[12:15]
	v_mfma_f32_16x16x32_bf16 v[8:11], v[148:151], v[202:205], v[8:11]
	v_mfma_f32_16x16x32_bf16 v[62:65], v[134:137], v[182:185], v[62:65]
	v_mfma_f32_16x16x32_bf16 v[58:61], v[152:155], v[182:185], v[58:61]
	v_mfma_f32_16x16x32_bf16 v[46:49], v[134:137], v[190:193], v[46:49]
	v_mfma_f32_16x16x32_bf16 v[42:45], v[152:155], v[190:193], v[42:45]
	v_mfma_f32_16x16x32_bf16 v[30:33], v[134:137], v[198:201], v[30:33]
	v_mfma_f32_16x16x32_bf16 v[26:29], v[152:155], v[198:201], v[26:29]
	v_mfma_f32_16x16x32_bf16 v[12:15], v[134:137], v[206:209], v[12:15]
	v_mfma_f32_16x16x32_bf16 v[8:11], v[152:155], v[206:209], v[8:11]
	v_mfma_f32_16x16x32_bf16 v[54:57], v[162:165], v[178:181], v[54:57]
	v_mfma_f32_16x16x32_bf16 v[50:53], v[170:173], v[178:181], v[50:53]
	v_mfma_f32_16x16x32_bf16 v[38:41], v[162:165], v[186:189], v[38:41]
	v_mfma_f32_16x16x32_bf16 v[34:37], v[170:173], v[186:189], v[34:37]
	v_mfma_f32_16x16x32_bf16 v[22:25], v[162:165], v[194:197], v[22:25]
	v_mfma_f32_16x16x32_bf16 v[18:21], v[170:173], v[194:197], v[18:21]
	v_mfma_f32_16x16x32_bf16 v[4:7], v[162:165], v[202:205], v[4:7]
	v_mfma_f32_16x16x32_bf16 v[0:3], v[170:173], v[202:205], v[0:3]
	v_mfma_f32_16x16x32_bf16 v[54:57], v[166:169], v[182:185], v[54:57]
	v_mfma_f32_16x16x32_bf16 v[50:53], v[174:177], v[182:185], v[50:53]
	v_mfma_f32_16x16x32_bf16 v[38:41], v[166:169], v[190:193], v[38:41]
	v_mfma_f32_16x16x32_bf16 v[34:37], v[174:177], v[190:193], v[34:37]
	v_mfma_f32_16x16x32_bf16 v[22:25], v[166:169], v[198:201], v[22:25]
	v_mfma_f32_16x16x32_bf16 v[18:21], v[174:177], v[198:201], v[18:21]
	v_mfma_f32_16x16x32_bf16 v[4:7], v[166:169], v[206:209], v[4:7]
	v_mfma_f32_16x16x32_bf16 v[0:3], v[174:177], v[206:209], v[0:3]
	s_barrier
	s_setprio 0
	s_add_i32 s82, s82, 2
	s_add_u32 s24, s24, 0x10000
	s_addc_u32 s25, s25, 0
	s_add_u32 s0, s0, 0x10000
	s_addc_u32 s1, s1, 0
	s_cmpk_gt_u32 s82, 0xfd
	s_cbranch_scc0 .LBB0_848
	s_and_b64 vcc, exec, s[8:9]
	s_cbranch_vccz .LBB0_851
	s_barrier
